# permlane16/32 swaps instead of ds_bpermute round trips for the per-head sum of squares in the in-projection epilogue (lever: intra-wave movement without LDS)
# speedup vs baseline: 1.0003x; 1.0003x over previous
; __device__ __forceinline__ unsigned pk2(float lo, float hi) { return pg8::cvt_pk_bf16(lo, hi); }
; __device__ __forceinline__ float gelu_tanh(float x) {
;     const float u = 0.7978845608028654f * (x + 0.044715f * x * x * x);
;     return x / (1.f + __expf(-2.f * u));
; }
; __device__ __forceinline__ void store8(bf16_t* p, const float* v) {
;     u32x4 w; w.x = pk2(v[0], v[1]); w.y = pk2(v[2], v[3]); w.z = pk2(v[4], v[5]); w.w = pk2(v[6], v[7]);
;     *(u32x4*)p = w;
; }
; __device__ __forceinline__ void load8(const bf16_t* p, float* v) {
;     const u32x4 w = *(const u32x4*)p;
;     v[0] = __uint_as_float(w.x << 16); v[1] = __uint_as_float(w.x & 0xffff0000u);
;     v[2] = __uint_as_float(w.y << 16); v[3] = __uint_as_float(w.y & 0xffff0000u);
;     v[4] = __uint_as_float(w.z << 16); v[5] = __uint_as_float(w.z & 0xffff0000u);
;     v[6] = __uint_as_float(w.w << 16); v[7] = __uint_as_float(w.w & 0xffff0000u);
; }
; __device__ __forceinline__ float head_ssq(const float (&v)[16]) {
;     float s = 0.f;
; #pragma unroll
;     for (int i = 0; i < 16; ++i) s += v[i] * v[i];
;     s += __shfl_xor(s, 16); s += __shfl_xor(s, 32);
;     return s;
;     __device__ __forceinline__ void operator()(const f32x4 (&acc)[2][2][4][2], const pg8::Unit& u, int wr, int wc, int fr, int fq) const {
;     ...
;                 } else if (cs < 36) {
;                     const int g = cs - 28;
;                     float y[16];
; #pragma unroll
;                     for (int i = 0; i < 16; ++i) y[i] = gelu_tanh(v[i]);
;                     const float rn = rsqrtf(head_ssq(y) * (1.f / 64.f) + EPS);
.LBB0_170:
	s_mov_b64 s[6:7], -1
	s_and_b64 vcc, exec, s[72:73]
	s_cbranch_vccz .LBB0_186
	s_and_b64 vcc, exec, s[70:71]
	s_cbranch_vccz .LBB0_183
	s_and_b64 vcc, exec, s[42:43]
	s_cbranch_vccz .LBB0_180
	s_andn2_b64 vcc, exec, s[40:41]
	s_cbranch_vccnz .LBB0_175
	s_ashr_i32 s53, s52, 31
	s_lshl_b64 s[56:57], s[52:53], 21
	v_readlane_b32 s36, v254, 33
	s_mov_b64 s[58:59], s[42:43]
	v_mul_f32_e32 v112, v171, v171
	v_mul_f32_e32 v112, 0xbdd2d3e8, v112
	v_add_f32_e32 v112, 0xc0135761, v112
	v_mul_f32_e32 v112, v171, v112
	v_exp_f32_e32 v112, v112
	s_nop 0
	v_add_f32_e32 v112, 1.0, v112
	v_rcp_f32_e32 v113, v112
	s_nop 0
	v_mul_f32_e32 v112, v171, v113
	s_nop 0
	s_nop 0
	v_mul_f32_e32 v113, v173, v173
	v_mul_f32_e32 v113, 0xbdd2d3e8, v113
	v_add_f32_e32 v113, 0xc0135761, v113
	v_mul_f32_e32 v113, v173, v113
	v_exp_f32_e32 v113, v113
	s_nop 0
	v_add_f32_e32 v113, 1.0, v113
	v_rcp_f32_e32 v114, v113
	s_nop 0
	v_mul_f32_e32 v121, v173, v114
	s_nop 0
	s_nop 0
	v_mul_f32_e32 v113, v175, v175
	v_mul_f32_e32 v113, 0xbdd2d3e8, v113
	v_add_f32_e32 v113, 0xc0135761, v113
	v_mul_f32_e32 v113, v175, v113
	v_exp_f32_e32 v113, v113
	s_nop 0
	v_add_f32_e32 v113, 1.0, v113
	v_rcp_f32_e32 v114, v113
	s_nop 0
	v_mul_f32_e32 v167, v175, v114
	s_nop 0
	s_nop 0
	v_mul_f32_e32 v113, v185, v185
	v_mul_f32_e32 v113, 0xbdd2d3e8, v113
	v_add_f32_e32 v113, 0xc0135761, v113
	v_mul_f32_e32 v113, v185, v113
	v_exp_f32_e32 v113, v113
	s_nop 0
	v_add_f32_e32 v113, 1.0, v113
	v_rcp_f32_e32 v114, v113
	s_nop 0
	v_mul_f32_e32 v195, v185, v114
	s_nop 0
	s_nop 0
	v_mul_f32_e32 v113, v187, v187
	v_mul_f32_e32 v113, 0xbdd2d3e8, v113
	v_add_f32_e32 v113, 0xc0135761, v113
	v_mul_f32_e32 v113, v187, v113
	v_exp_f32_e32 v113, v113
	s_nop 0
	v_add_f32_e32 v113, 1.0, v113
	v_rcp_f32_e32 v114, v113
	s_nop 0
	v_mul_f32_e32 v197, v187, v114
	s_nop 0
	s_nop 0
	v_mul_f32_e32 v113, v189, v189
	v_mul_f32_e32 v113, 0xbdd2d3e8, v113
	v_add_f32_e32 v113, 0xc0135761, v113
	v_mul_f32_e32 v113, v189, v113
	v_exp_f32_e32 v113, v113
	s_nop 0
	v_add_f32_e32 v113, 1.0, v113
	v_rcp_f32_e32 v114, v113
	s_nop 0
	v_mul_f32_e32 v199, v189, v114
	s_nop 0
	s_nop 0
	v_mul_f32_e32 v113, v191, v191
	v_mul_f32_e32 v113, 0xbdd2d3e8, v113
	v_add_f32_e32 v113, 0xc0135761, v113
	v_mul_f32_e32 v113, v191, v113
	v_exp_f32_e32 v113, v113
	s_nop 0
	v_add_f32_e32 v113, 1.0, v113
	v_rcp_f32_e32 v114, v113
	s_nop 0
	v_mul_f32_e32 v212, v191, v114
	s_nop 0
	s_nop 0
	v_mul_f32_e32 v113, v193, v193
	v_mul_f32_e32 v113, 0xbdd2d3e8, v113
	v_add_f32_e32 v113, 0xc0135761, v113
	v_mul_f32_e32 v113, v193, v113
	v_exp_f32_e32 v113, v113
	s_nop 0
	v_add_f32_e32 v113, 1.0, v113
	v_rcp_f32_e32 v114, v113
	s_nop 0
	v_mul_f32_e32 v213, v193, v114
	v_mul_f32_e32 v115, v201, v201
	v_mul_f32_e32 v115, 0xbdd2d3e8, v115
	v_add_f32_e32 v115, 0xc0135761, v115
	v_mul_f32_e32 v115, v201, v115
	v_exp_f32_e32 v115, v115
	s_nop 0
	v_add_f32_e32 v115, 1.0, v115
	v_rcp_f32_e32 v136, v115
	s_nop 0
	v_mul_f32_e32 v203, v201, v136
	v_mul_f32_e32 v113, v121, v121
	v_fmac_f32_e32 v113, v112, v112
	v_fmac_f32_e32 v113, v167, v167
	v_fmac_f32_e32 v113, v195, v195
	v_fmac_f32_e32 v113, v197, v197
	v_fmac_f32_e32 v113, v199, v199
	v_fmac_f32_e32 v113, v212, v212
	v_mul_f32_e32 v114, v200, v200
	v_mul_f32_e32 v114, 0xbdd2d3e8, v114
	v_add_f32_e32 v114, 0xc0135761, v114
	v_mul_f32_e32 v114, v200, v114
	v_exp_f32_e32 v114, v114
	s_nop 0
	v_add_f32_e32 v114, 1.0, v114
	v_rcp_f32_e32 v115, v114
	s_nop 0
	v_mul_f32_e32 v202, v200, v115
	v_fmac_f32_e32 v113, v213, v213
	v_pk_mul_f32 v[114:115], v[202:203], v[202:203]
	s_nop 0
	v_add_f32_e32 v113, v114, v113
	v_add_f32_e32 v113, v115, v113
	s_nop 0
	s_nop 0
	v_mul_f32_e32 v115, v127, v127
	v_mul_f32_e32 v115, 0xbdd2d3e8, v115
	v_add_f32_e32 v115, 0xc0135761, v115
	v_mul_f32_e32 v115, v127, v115
	v_exp_f32_e32 v115, v115
	s_nop 0
	v_add_f32_e32 v115, 1.0, v115
	v_rcp_f32_e32 v116, v115
	s_nop 0
	v_mul_f32_e32 v205, v127, v116
	s_nop 0
	v_mul_f32_e32 v114, v126, v126
	v_mul_f32_e32 v114, 0xbdd2d3e8, v114
	v_add_f32_e32 v114, 0xc0135761, v114
	v_mul_f32_e32 v114, v126, v114
	v_exp_f32_e32 v114, v114
	s_nop 0
	v_add_f32_e32 v114, 1.0, v114
	v_rcp_f32_e32 v115, v114
	s_nop 0
	v_mul_f32_e32 v204, v126, v115
	v_pk_mul_f32 v[114:115], v[204:205], v[204:205]
	s_nop 0
	v_add_f32_e32 v113, v114, v113
	v_add_f32_e32 v113, v115, v113
	s_nop 0
	s_nop 0
	v_mul_f32_e32 v115, v125, v125
	v_mul_f32_e32 v115, 0xbdd2d3e8, v115
	v_add_f32_e32 v115, 0xc0135761, v115
	v_mul_f32_e32 v115, v125, v115
	v_exp_f32_e32 v115, v115
	s_nop 0
	v_add_f32_e32 v115, 1.0, v115
	v_rcp_f32_e32 v116, v115
	s_nop 0
	v_mul_f32_e32 v207, v125, v116
	s_nop 0
	v_mul_f32_e32 v114, v124, v124
	v_mul_f32_e32 v114, 0xbdd2d3e8, v114
	v_add_f32_e32 v114, 0xc0135761, v114
	v_mul_f32_e32 v114, v124, v114
	v_exp_f32_e32 v114, v114
	s_nop 0
	v_add_f32_e32 v114, 1.0, v114
	v_rcp_f32_e32 v115, v114
	s_nop 0
	v_mul_f32_e32 v206, v124, v115
	v_pk_mul_f32 v[114:115], v[206:207], v[206:207]
	s_nop 0
	v_add_f32_e32 v113, v114, v113
	v_add_f32_e32 v113, v115, v113
	s_nop 0
	s_nop 0
	v_mul_f32_e32 v115, v123, v123
	v_mul_f32_e32 v115, 0xbdd2d3e8, v115
	v_add_f32_e32 v115, 0xc0135761, v115
	v_mul_f32_e32 v115, v123, v115
	v_exp_f32_e32 v115, v115
	s_nop 0
	v_add_f32_e32 v115, 1.0, v115
	v_rcp_f32_e32 v116, v115
	s_nop 0
	v_mul_f32_e32 v209, v123, v116
	s_lshr_b32 s6, s89, 4
	s_and_b32 s6, s6, 0x78
	s_add_i32 s6, s6, s29
	v_mul_f32_e32 v114, v122, v122
	v_mul_f32_e32 v114, 0xbdd2d3e8, v114
	v_add_f32_e32 v114, 0xc0135761, v114
	v_mul_f32_e32 v114, v122, v114
	v_exp_f32_e32 v114, v114
	s_nop 0
	v_add_f32_e32 v114, 1.0, v114
	v_rcp_f32_e32 v115, v114
	s_nop 0
	v_mul_f32_e32 v208, v122, v115
	v_pk_mul_f32 v[114:115], v[208:209], v[208:209]
	s_mov_b32 s7, s9
	v_add_f32_e32 v113, v114, v113
	v_add_f32_e32 v113, v115, v113
	v_and_b32_e32 v115, 64, v165
	v_xor_b32_e32 v114, 16, v165
	v_add_u32_e32 v115, 64, v115
	v_cmp_lt_i32_e32 vcc, v114, v115
	s_lshl_b64 s[6:7], s[6:7], 14
	s_add_u32 s37, s36, s56
	v_cndmask_b32_e32 v114, v165, v114, vcc
	v_lshlrev_b32_e32 v114, 2, v114
	v_mov_b32_e32 v114, v113
	s_nop 1
	v_permlane16_swap_b32 v113, v114
	v_readlane_b32 s36, v254, 35
	s_addc_u32 s53, s36, s57
	s_add_u32 s6, s37, s6
	s_addc_u32 s7, s53, s7
	s_waitcnt lgkmcnt(0)
; __device__ __forceinline__ unsigned f2bf(float f) { unsigned u = __float_as_uint(f); return (u + 0x7fffu + ((u >> 16) & 1u)) >> 16; }
; __device__ __forceinline__ float head_ssq(const float (&v)[16]) {
;     float s = 0.f;
; #pragma unroll
;     for (int i = 0; i < 16; ++i) s += v[i] * v[i];
;     s += __shfl_xor(s, 16); s += __shfl_xor(s, 32);
;     return s;
;     __device__ __forceinline__ void operator()(const f32x4 (&acc)[2][2][4][2], const pg8::Unit& u, int wr, int wc, int fr, int fq) const {
;     ...
;                     const float rn = rsqrtf(head_ssq(y) * (1.f / 64.f) + EPS);
;                     bf16_t* p = zvT + (((size_t)b * 16 + (s >> 7)) * 8 + g) * 8192 + (s & 127);
; #pragma unroll
;                     for (int i = 0; i < 16; ++i) { const int d = 32 * (i >> 3) + d0 + (i & 7); p[d * 128] = (bf16_t)f2bf(y[i] * rn * g_sgu[g * 64 + d]); }
	v_add_f32_e32 v113, v113, v114
	v_xor_b32_e32 v114, 32, v165
	v_cmp_lt_i32_e32 vcc, v114, v115
	s_mov_b64 s[56:57], s[40:41]
	s_nop 0
	v_cndmask_b32_e32 v114, v165, v114, vcc
	v_lshlrev_b32_e32 v114, 2, v114
	v_mov_b32_e32 v114, v113
	s_nop 1
	v_permlane32_swap_b32 v113, v114
	s_waitcnt lgkmcnt(0)
	v_add_f32_e32 v113, v113, v114
	v_fmamk_f32 v113, v113, 0x3c800000, v161
	v_cmp_gt_f32_e32 vcc, s61, v113
	v_mul_f32_e32 v114, 0x4b800000, v113
	s_nop 0
	v_cndmask_b32_e32 v113, v113, v114, vcc
	v_rsq_f32_e32 v113, v113
	s_nop 0
	v_mul_f32_e32 v114, 0x45800000, v113
	v_cndmask_b32_e32 v214, v113, v114, vcc
	v_and_b32_e32 v113, 0x4f, v120
	v_lshlrev_b32_e32 v136, 1, v113
	v_lshl_add_u64 v[210:211], s[6:7], 0, v[136:137]
	s_mov_b64 s[6:7], s[38:39]
	v_readlane_b32 s36, v254, 8
	v_or_b32_e32 v136, s27, v140
	v_readlane_b32 s37, v254, 9
	v_mul_f32_e32 v166, v112, v214
	v_readlane_b32 s50, v254, 22
	v_lshl_add_u64 v[116:117], v[136:137], 2, s[36:37]
	global_load_dwordx4 v[112:115], v[116:117], off offset:16
	s_nop 0
	global_load_dwordx4 v[116:119], v[116:117], off
	v_readlane_b32 s51, v254, 23
	v_readlane_b32 s38, v254, 10
	v_readlane_b32 s39, v254, 11
	v_readlane_b32 s40, v254, 12
	v_readlane_b32 s41, v254, 13
	v_readlane_b32 s42, v254, 14
	v_readlane_b32 s43, v254, 15
	v_readlane_b32 s49, v254, 21
	v_readlane_b32 s50, v254, 39
	s_mov_b64 s[38:39], s[6:7]
	s_mov_b64 s[42:43], s[58:59]
	s_mov_b64 s[40:41], s[56:57]
	v_readlane_b32 s49, v254, 41
	v_readlane_b32 s51, v254, 40
	s_mov_b64 s[6:7], 0
	v_readlane_b32 s44, v254, 16
	v_readlane_b32 s45, v254, 17
	v_readlane_b32 s46, v254, 18
	v_readlane_b32 s47, v254, 19
	v_readlane_b32 s48, v254, 20
	s_waitcnt vmcnt(0)
	v_mul_f32_e32 v116, v116, v166
	v_bfe_u32 v136, v116, 16, 1
	v_add3_u32 v116, v116, v136, s20
	v_lshlrev_b32_e32 v136, 1, v142
	v_lshl_add_u64 v[216:217], v[210:211], 0, v[136:137]
	global_store_short_d16_hi v[216:217], v116, off
	v_mul_f32_e32 v116, v121, v214
	v_add_u32_e32 v136, s27, v140
	v_mul_f32_e32 v116, v117, v116
	v_lshl_add_u64 v[216:217], v[136:137], 2, s[36:37]
	v_bfe_u32 v117, v116, 16, 1
	v_lshlrev_b32_e32 v136, 1, v144
	v_add3_u32 v121, v116, v117, s20
	v_lshl_add_u64 v[116:117], v[210:211], 0, v[136:137]
	global_store_short_d16_hi v[116:117], v121, off
	v_mul_f32_e32 v116, v167, v214
	v_mul_f32_e32 v116, v118, v116
	v_bfe_u32 v117, v116, 16, 1
	v_lshlrev_b32_e32 v136, 1, v146
	v_add3_u32 v118, v116, v117, s20
	v_lshl_add_u64 v[116:117], v[210:211], 0, v[136:137]
	global_store_short_d16_hi v[116:117], v118, off
	v_mul_f32_e32 v116, v195, v214
	v_mul_f32_e32 v116, v119, v116
	v_bfe_u32 v117, v116, 16, 1
	v_lshlrev_b32_e32 v136, 1, v148
	v_add3_u32 v118, v116, v117, s20
	v_lshl_add_u64 v[116:117], v[210:211], 0, v[136:137]
	global_store_short_d16_hi v[116:117], v118, off
	v_mul_f32_e32 v116, v197, v214
	v_mul_f32_e32 v112, v112, v116
	v_bfe_u32 v116, v112, 16, 1
	v_lshlrev_b32_e32 v136, 1, v150
	v_add3_u32 v112, v112, v116, s20
	v_lshl_add_u64 v[116:117], v[210:211], 0, v[136:137]
	global_store_short_d16_hi v[116:117], v112, off
	v_mul_f32_e32 v112, v199, v214
	v_mul_f32_e32 v112, v112, v113
	v_bfe_u32 v113, v112, 16, 1
	v_lshlrev_b32_e32 v136, 1, v152
	v_add3_u32 v116, v112, v113, s20
	v_lshl_add_u64 v[112:113], v[210:211], 0, v[136:137]
	global_store_short_d16_hi v[112:113], v116, off
	v_mul_f32_e32 v112, v212, v214
	v_mul_f32_e32 v112, v112, v114
	v_bfe_u32 v113, v112, 16, 1
	v_lshlrev_b32_e32 v136, 1, v154
	v_add3_u32 v114, v112, v113, s20
	v_lshl_add_u64 v[112:113], v[210:211], 0, v[136:137]
	global_store_short_d16_hi v[112:113], v114, off
	v_mul_f32_e32 v112, v213, v214
	v_mul_f32_e32 v112, v112, v115
	v_bfe_u32 v113, v112, 16, 1
	v_lshlrev_b32_e32 v136, 1, v156
	v_add3_u32 v114, v112, v113, s20
	v_lshl_add_u64 v[112:113], v[210:211], 0, v[136:137]
	global_store_short_d16_hi v[112:113], v114, off
	global_load_dwordx4 v[112:115], v[216:217], off offset:144
	s_nop 0
	global_load_dwordx4 v[116:119], v[216:217], off offset:128
	v_mul_f32_e32 v121, v202, v214
	v_lshlrev_b32_e32 v136, 1, v158
	v_lshl_add_u64 v[166:167], v[210:211], 0, v[136:137]
	v_lshlrev_b32_e32 v136, 1, v160
	s_waitcnt vmcnt(0)
	v_mul_f32_e32 v116, v121, v116
	v_bfe_u32 v121, v116, 16, 1
	v_add3_u32 v116, v116, v121, s20
	global_store_short_d16_hi v[166:167], v116, off
	v_mul_f32_e32 v116, v203, v214
	v_mul_f32_e32 v116, v116, v117
	v_bfe_u32 v117, v116, 16, 1
	v_add3_u32 v121, v116, v117, s20
	v_lshl_add_u64 v[116:117], v[210:211], 0, v[136:137]
	global_store_short_d16_hi v[116:117], v121, off
	v_mul_f32_e32 v116, v204, v214
	v_mul_f32_e32 v116, v116, v118
	v_bfe_u32 v117, v116, 16, 1
	v_lshlrev_b32_e32 v136, 1, v162
	v_add3_u32 v118, v116, v117, s20
	v_lshl_add_u64 v[116:117], v[210:211], 0, v[136:137]
	global_store_short_d16_hi v[116:117], v118, off
	v_mul_f32_e32 v116, v205, v214
	v_mul_f32_e32 v116, v116, v119
	v_bfe_u32 v117, v116, 16, 1
	v_lshlrev_b32_e32 v136, 1, v164
	v_add3_u32 v118, v116, v117, s20
	v_lshl_add_u64 v[116:117], v[210:211], 0, v[136:137]
	global_store_short_d16_hi v[116:117], v118, off
	v_mul_f32_e32 v116, v206, v214
	v_mul_f32_e32 v112, v116, v112
	v_bfe_u32 v116, v112, 16, 1
	v_add3_u32 v112, v112, v116, s20
	v_or_b32_e32 v116, 0x1200, v142
	v_lshlrev_b32_e32 v136, 1, v116
	v_lshl_add_u64 v[116:117], v[210:211], 0, v[136:137]
	global_store_short_d16_hi v[116:117], v112, off
	v_mul_f32_e32 v112, v207, v214
	v_mul_f32_e32 v112, v112, v113
	v_bfe_u32 v113, v112, 16, 1
	v_add3_u32 v116, v112, v113, s20
	v_or_b32_e32 v112, 0x1280, v142
	v_lshlrev_b32_e32 v136, 1, v112
	v_lshl_add_u64 v[112:113], v[210:211], 0, v[136:137]
	global_store_short_d16_hi v[112:113], v116, off
	v_mul_f32_e32 v112, v208, v214
	v_mul_f32_e32 v112, v112, v114
	v_bfe_u32 v113, v112, 16, 1
	v_add3_u32 v114, v112, v113, s20
	v_or_b32_e32 v112, 0x1300, v142
	v_lshlrev_b32_e32 v136, 1, v112
	v_lshl_add_u64 v[112:113], v[210:211], 0, v[136:137]
	global_store_short_d16_hi v[112:113], v114, off
	v_mul_f32_e32 v112, v209, v214
	v_mul_f32_e32 v112, v112, v115
	v_bfe_u32 v113, v112, 16, 1
	v_lshlrev_b32_e32 v136, 1, v172
	v_add3_u32 v114, v112, v113, s20
	v_lshl_add_u64 v[112:113], v[210:211], 0, v[136:137]
	global_store_short_d16_hi v[112:113], v114, off

; __device__ __forceinline__ float head_ssq(const float (&v)[16]) {
;     float s = 0.f;
; #pragma unroll
;     for (int i = 0; i < 16; ++i) s += v[i] * v[i];
;     s += __shfl_xor(s, 16); s += __shfl_xor(s, 32);
;     return s;
;     __device__ __forceinline__ void operator()(const f32x4 (&acc)[2][2][4][2], const pg8::Unit& u, int wr, int wc, int fr, int fq) const {
;     ...
;                 if (cs < 8 || cs == 12 || cs == 13 || cs == 16 || cs == 17) {
;                     const float* gg = cs < 8 ? g_q : (cs < 14 ? g_k + 64 : g_k + 128);
;                     const float rn = rsqrtf(head_ssq(v) * (1.f / 64.f) + EPS) * (cs < 8 ? QSCALE : 1.f);
;                     float y[16];
; #pragma unroll
;                     for (int i = 0; i < 16; ++i) y[i] = v[i] * rn * gg[32 * (i >> 3) + d0 + (i & 7)];
;                     float r1[8], r2[8];
; #pragma unroll
;                     for (int i = 0; i < 8; ++i) { int di = d0 + i; asm volatile("" : "+v"(di));
;                         const float frev = __builtin_amdgcn_exp2f(-(float)di * (13.287712379549449f / 32.f)) * 0.15915494309189535f;
;                         float xr = (float)s * frev; xr -= __builtin_rintf(xr);
;                         const float c = __builtin_amdgcn_cosf(xr), sn = __builtin_amdgcn_sinf(xr); r1[i] = y[i] * c - y[8 + i] * sn; r2[i] = y[8 + i] * c + y[i] * sn; }
.LBB0_190:
	global_load_dwordx4 v[112:115], v167, s[6:7]
	global_load_dwordx4 v[116:119], v167, s[6:7] offset:16
	global_load_dwordx4 v[202:205], v167, s[6:7] offset:128
	global_load_dwordx4 v[206:209], v167, s[6:7] offset:144
	v_mul_f32_e32 v121, v173, v173
	v_fmac_f32_e32 v121, v171, v171
	v_fmac_f32_e32 v121, v175, v175
	v_fmac_f32_e32 v121, v185, v185
	v_fmac_f32_e32 v121, v187, v187
	v_fmac_f32_e32 v121, v189, v189
	v_fmac_f32_e32 v121, v191, v191
	v_pk_mul_f32 v[210:211], v[200:201], v[200:201]
	v_fmac_f32_e32 v121, v193, v193
	v_add_f32_e32 v121, v210, v121
	v_pk_mul_f32 v[212:213], v[126:127], v[126:127]
	v_add_f32_e32 v121, v211, v121
	v_add_f32_e32 v121, v212, v121
	v_pk_mul_f32 v[214:215], v[124:125], v[124:125]
	v_and_b32_e32 v166, 64, v165
	v_add_f32_e32 v121, v213, v121
	v_xor_b32_e32 v136, 16, v165
	v_add_u32_e32 v166, 64, v166
	v_add_f32_e32 v121, v214, v121
	v_pk_mul_f32 v[216:217], v[122:123], v[122:123]
	v_cmp_lt_i32_e32 vcc, v136, v166
	v_add_f32_e32 v121, v215, v121
	v_add_f32_e32 v121, v216, v121
	v_cndmask_b32_e32 v136, v165, v136, vcc
	v_lshlrev_b32_e32 v136, 2, v136
	v_add_f32_e32 v121, v217, v121
	v_mov_b32_e32 v136, v121
	s_nop 1
	v_permlane16_swap_b32 v121, v136
	v_xor_b32_e32 v168, 32, v165
	v_cmp_lt_i32_e32 vcc, v168, v166
	s_mov_b64 s[6:7], -1
	s_waitcnt lgkmcnt(0)
	v_add_f32_e32 v121, v121, v136
	v_cndmask_b32_e32 v166, v165, v168, vcc
	v_lshlrev_b32_e32 v166, 2, v166
	v_mov_b32_e32 v136, v121
	s_nop 1
	v_permlane32_swap_b32 v121, v136
	v_mov_b32_e32 v166, v140
	s_waitcnt lgkmcnt(0)
	v_add_f32_e32 v121, v121, v136
	v_fmamk_f32 v121, v121, 0x3c800000, v161
	v_mul_f32_e32 v136, 0x4b800000, v121
	v_cmp_gt_f32_e32 vcc, s61, v121
	v_cvt_f32_i32_e32 v166, v166
	v_mul_f32_e32 v166, 0xbed49a78, v166
	v_cndmask_b32_e32 v121, v121, v136, vcc
	v_rsq_f32_e32 v121, v121
	v_exp_f32_e32 v166, v166
	v_cvt_f32_u32_e32 v136, v169
	v_mul_f32_e32 v168, 0x45800000, v121
	v_cndmask_b32_e32 v121, v121, v168, vcc
	v_mul_f32_e32 v121, s53, v121
	v_mul_f32_e32 v168, v171, v121
	v_mul_f32_e32 v170, v173, v121
	v_mul_f32_e32 v173, v175, v121
	v_mul_f32_e32 v185, v185, v121
	v_mul_f32_e32 v187, v187, v121
	v_mul_f32_e32 v189, v189, v121
	v_mul_f32_e32 v191, v191, v121
	v_mul_f32_e32 v193, v193, v121
	v_mul_f32_e32 v195, v200, v121
	v_mul_f32_e32 v197, v201, v121
	v_mul_f32_e32 v199, v126, v121
	v_mul_f32_e32 v200, v127, v121
	v_mul_f32_e32 v201, v124, v121
	v_mul_f32_e32 v210, v125, v121
	v_mul_f32_e32 v211, v122, v121
	s_and_b64 vcc, exec, s[54:55]
	s_waitcnt vmcnt(3)
	v_mul_f32_e32 v171, v112, v168
	v_mul_f32_e32 v112, v123, v121
	v_mul_f32_e32 v121, 0.15915494, v166
	v_mul_f32_e32 v123, v121, v136
	v_rndne_f32_e32 v123, v123
	v_fma_f32 v121, v121, v136, -v123
	v_mov_b32_e32 v123, v141
	v_sin_f32_e32 v166, v121
	v_cvt_f32_i32_e32 v123, v123
	v_cos_f32_e32 v121, v121
	s_waitcnt vmcnt(2)
	v_mul_f32_e32 v127, v117, v189
	s_waitcnt vmcnt(1)
	v_mul_f32_e32 v117, v202, v195
	v_mul_f32_e32 v123, 0xbed49a78, v123
	v_exp_f32_e32 v168, v123
	v_mul_f32_e32 v126, v114, v173
	v_mul_f32_e32 v173, v115, v185
	s_waitcnt vmcnt(0)
	v_mul_f32_e32 v185, v112, v209
	v_mul_f32_e32 v112, v117, v166
	v_fma_f32 v123, v171, v121, -v112
	v_mul_f32_e32 v112, v171, v166
	v_fmac_f32_e32 v112, v117, v121
	v_mul_f32_e32 v121, 0.15915494, v168
	v_mov_b32_e32 v168, v143
	v_mul_f32_e32 v166, v121, v136
	v_rndne_f32_e32 v166, v166
	v_cvt_f32_i32_e32 v168, v168
	v_fma_f32 v121, v121, v136, -v166
	v_sin_f32_e32 v166, v121
	v_cos_f32_e32 v121, v121
	v_mul_f32_e32 v168, 0xbed49a78, v168
	v_mul_f32_e32 v125, v119, v193
	v_mul_f32_e32 v119, v203, v197
	v_exp_f32_e32 v168, v168
	v_mul_f32_e32 v175, v113, v170
	v_mul_f32_e32 v170, v119, v166
	v_fma_f32 v189, v175, v121, -v170
	v_mov_b32_e32 v170, v145
	v_mul_f32_e32 v124, v116, v187
	v_mul_f32_e32 v187, v175, v166
	v_mul_f32_e32 v166, 0.15915494, v168
	v_cvt_f32_i32_e32 v170, v170
	v_mul_f32_e32 v168, v166, v136
	v_rndne_f32_e32 v168, v168
	v_fma_f32 v166, v166, v136, -v168
	v_sin_f32_e32 v168, v166
	v_mul_f32_e32 v170, 0xbed49a78, v170
	v_fmac_f32_e32 v187, v119, v121
	v_cos_f32_e32 v121, v166
	v_exp_f32_e32 v170, v170
	v_mul_f32_e32 v115, v199, v204
	v_mul_f32_e32 v122, v118, v191
	v_mul_f32_e32 v166, v115, v168
	v_mul_f32_e32 v191, v126, v168
	v_fma_f32 v193, v126, v121, -v166
	v_fmac_f32_e32 v191, v115, v121
	v_mul_f32_e32 v121, 0.15915494, v170
	v_mov_b32_e32 v168, v147
	v_mul_f32_e32 v166, v121, v136
	v_rndne_f32_e32 v166, v166
	v_cvt_f32_i32_e32 v168, v168
	v_fma_f32 v121, v121, v136, -v166
	v_sin_f32_e32 v166, v121
	v_cos_f32_e32 v121, v121
	v_mul_f32_e32 v168, 0xbed49a78, v168
	v_mul_f32_e32 v118, v200, v205
	v_exp_f32_e32 v168, v168
	v_mul_f32_e32 v170, v118, v166
	v_fma_f32 v197, v173, v121, -v170
	v_mov_b32_e32 v170, v153
	v_mul_f32_e32 v195, v173, v166
	v_mul_f32_e32 v166, 0.15915494, v168
	v_cvt_f32_i32_e32 v170, v170
	v_mul_f32_e32 v168, v166, v136
	v_rndne_f32_e32 v168, v168
	v_fma_f32 v166, v166, v136, -v168
	v_sin_f32_e32 v168, v166
	v_mul_f32_e32 v170, 0xbed49a78, v170
	v_fmac_f32_e32 v195, v118, v121
	v_cos_f32_e32 v121, v166
	v_exp_f32_e32 v170, v170
	v_mul_f32_e32 v114, v201, v206
	v_mul_f32_e32 v166, v114, v168
	v_mul_f32_e32 v199, v124, v168
	v_fma_f32 v200, v124, v121, -v166
	v_fmac_f32_e32 v199, v114, v121
	v_mul_f32_e32 v121, 0.15915494, v170
	v_mov_b32_e32 v168, v155
	v_mul_f32_e32 v166, v121, v136
	v_rndne_f32_e32 v166, v166
	v_cvt_f32_i32_e32 v168, v168
	v_fma_f32 v121, v121, v136, -v166
	v_sin_f32_e32 v166, v121
	v_cos_f32_e32 v121, v121
	v_mul_f32_e32 v168, 0xbed49a78, v168
	v_mul_f32_e32 v116, v210, v207
	v_exp_f32_e32 v168, v168
	v_mul_f32_e32 v170, v116, v166
	v_fma_f32 v202, v127, v121, -v170
	v_mov_b32_e32 v170, v157
	v_mul_f32_e32 v201, v127, v166
	v_mul_f32_e32 v166, 0.15915494, v168
	v_cvt_f32_i32_e32 v170, v170
	v_mul_f32_e32 v168, v166, v136
	v_rndne_f32_e32 v168, v168
	v_fma_f32 v166, v166, v136, -v168
	v_cos_f32_e32 v168, v166
	v_sin_f32_e32 v166, v166
	v_mul_f32_e32 v170, 0xbed49a78, v170
	v_exp_f32_e32 v170, v170
	v_mul_f32_e32 v113, v211, v208
	v_fmac_f32_e32 v201, v116, v121
	v_mul_f32_e32 v121, v113, v166
	v_fma_f32 v205, v122, v168, -v121
	v_mul_f32_e32 v121, 0.15915494, v170
	v_mul_f32_e32 v170, v121, v136
	v_rndne_f32_e32 v170, v170
	v_fma_f32 v121, v121, v136, -v170
	v_sin_f32_e32 v136, v121
	v_cos_f32_e32 v121, v121
	v_mul_f32_e32 v203, v122, v166
	v_fmac_f32_e32 v203, v113, v168
	v_mul_f32_e32 v166, v185, v136
	v_mul_f32_e32 v204, v125, v136
	v_fma_f32 v206, v125, v121, -v166
	v_fmac_f32_e32 v204, v185, v121
	s_cbranch_vccz .LBB0_192
;     __device__ __forceinline__ void operator()(const f32x4 (&acc)[2][2][4][2], const pg8::Unit& u, int wr, int wc, int fr, int fq) const {
;     ...
;                         bf16_t* p = (cs < 14 ? ksl : kwn) + ((size_t)(b * 2 + (cs & 1)) * 2048 + s) * 64 + d0; store8(p, r1); store8(p + 32, r2);
	s_and_b64 s[6:7], s[10:11], exec
	s_cselect_b32 s53, s77, s76
	s_cselect_b32 s56, s74, s75
	s_lshl_b32 s6, s52, 1
	s_or_b32 s6, s6, s97
	s_ashr_i32 s7, s6, 31
	s_lshl_b64 s[6:7], s[6:7], 18
	s_add_u32 s6, s56, s6
	s_addc_u32 s7, s53, s7
	v_lshlrev_b32_e32 v136, 7, v169
	v_lshl_add_u64 v[168:169], s[6:7], 0, v[136:137]
	v_lshlrev_b32_e32 v136, 1, v140
	v_lshl_add_u64 v[168:169], v[168:169], 0, v[136:137]
	v_cvt_pk_bf16_f32 v208, v123, v189
	v_cvt_pk_bf16_f32 v209, v193, v197
	v_cvt_pk_bf16_f32 v210, v200, v202
	v_cvt_pk_bf16_f32 v211, v205, v206
	global_store_dwordx4 v[168:169], v[208:211], off
	s_mov_b64 s[6:7], 0
	s_nop 0
	v_cvt_pk_bf16_f32 v208, v112, v187
	v_cvt_pk_bf16_f32 v209, v191, v195
	v_cvt_pk_bf16_f32 v210, v199, v201
	v_cvt_pk_bf16_f32 v211, v203, v204
	global_store_dwordx4 v[168:169], v[208:211], off offset:64

; __device__ __forceinline__ unsigned pk2(float lo, float hi) { return pg8::cvt_pk_bf16(lo, hi); }
; __device__ __forceinline__ float gelu_tanh(float x) {
;     const float u = 0.7978845608028654f * (x + 0.044715f * x * x * x);
;     return x / (1.f + __expf(-2.f * u));
; }
; __device__ __forceinline__ void store8(bf16_t* p, const float* v) {
;     u32x4 w; w.x = pk2(v[0], v[1]); w.y = pk2(v[2], v[3]); w.z = pk2(v[4], v[5]); w.w = pk2(v[6], v[7]);
;     *(u32x4*)p = w;
; }
; __device__ __forceinline__ void load8(const bf16_t* p, float* v) {
;     const u32x4 w = *(const u32x4*)p;
;     v[0] = __uint_as_float(w.x << 16); v[1] = __uint_as_float(w.x & 0xffff0000u);
;     v[2] = __uint_as_float(w.y << 16); v[3] = __uint_as_float(w.y & 0xffff0000u);
;     v[4] = __uint_as_float(w.z << 16); v[5] = __uint_as_float(w.z & 0xffff0000u);
;     v[6] = __uint_as_float(w.w << 16); v[7] = __uint_as_float(w.w & 0xffff0000u);
; }
; __device__ __forceinline__ float head_ssq(const float (&v)[16]) {
;     float s = 0.f;
; #pragma unroll
;     for (int i = 0; i < 16; ++i) s += v[i] * v[i];
;     s += __shfl_xor(s, 16); s += __shfl_xor(s, 32);
;     return s;
;     __device__ __forceinline__ void operator()(const f32x4 (&acc)[2][2][4][2], const pg8::Unit& u, int wr, int wc, int fr, int fq) const {
;     ...
;                 } else if (cs < 36) {
;                     const int g = cs - 28;
;                     float y[16];
; #pragma unroll
;                     for (int i = 0; i < 16; ++i) y[i] = gelu_tanh(v[i]);
;                     const float rn = rsqrtf(head_ssq(y) * (1.f / 64.f) + EPS);
.LBB0_203:
	s_andn2_b64 vcc, exec, s[72:73]
	s_mov_b64 s[54:55], -1
	s_cbranch_vccnz .LBB0_219
	s_andn2_b64 vcc, exec, s[70:71]
	s_cbranch_vccnz .LBB0_216
	s_andn2_b64 vcc, exec, s[42:43]
	s_cbranch_vccnz .LBB0_213
	s_andn2_b64 vcc, exec, s[40:41]
	s_cbranch_vccnz .LBB0_208
	s_ashr_i32 s53, s52, 31
	s_lshl_b64 s[56:57], s[52:53], 21
	v_readlane_b32 s36, v254, 33
	s_mov_b64 s[58:59], s[42:43]
	v_mul_f32_e32 v96, v126, v126
	v_mul_f32_e32 v96, 0xbdd2d3e8, v96
	v_add_f32_e32 v96, 0xc0135761, v96
	v_mul_f32_e32 v96, v126, v96
	v_exp_f32_e32 v96, v96
	s_nop 0
	v_add_f32_e32 v96, 1.0, v96
	v_rcp_f32_e32 v97, v96
	s_nop 0
	v_mul_f32_e32 v96, v126, v97
	s_nop 0
	s_nop 0
	v_mul_f32_e32 v97, v127, v127
	v_mul_f32_e32 v97, 0xbdd2d3e8, v97
	v_add_f32_e32 v97, 0xc0135761, v97
	v_mul_f32_e32 v97, v127, v97
	v_exp_f32_e32 v97, v97
	s_nop 0
	v_add_f32_e32 v97, 1.0, v97
	v_rcp_f32_e32 v98, v97
	s_nop 0
	v_mul_f32_e32 v105, v127, v98
	s_nop 0
	s_nop 0
	v_mul_f32_e32 v97, v169, v169
	v_mul_f32_e32 v97, 0xbdd2d3e8, v97
	v_add_f32_e32 v97, 0xc0135761, v97
	v_mul_f32_e32 v97, v169, v97
	v_exp_f32_e32 v97, v97
	s_nop 0
	v_add_f32_e32 v97, 1.0, v97
	v_rcp_f32_e32 v98, v97
	s_nop 0
	v_mul_f32_e32 v189, v169, v98
	s_nop 0
	s_nop 0
	v_mul_f32_e32 v97, v171, v171
	v_mul_f32_e32 v97, 0xbdd2d3e8, v97
	v_add_f32_e32 v97, 0xc0135761, v97
	v_mul_f32_e32 v97, v171, v97
	v_exp_f32_e32 v97, v97
	s_nop 0
	v_add_f32_e32 v97, 1.0, v97
	v_rcp_f32_e32 v98, v97
	s_nop 0
	v_mul_f32_e32 v191, v171, v98
	s_nop 0
	s_nop 0
	v_mul_f32_e32 v97, v173, v173
	v_mul_f32_e32 v97, 0xbdd2d3e8, v97
	v_add_f32_e32 v97, 0xc0135761, v97
	v_mul_f32_e32 v97, v173, v97
	v_exp_f32_e32 v97, v97
	s_nop 0
	v_add_f32_e32 v97, 1.0, v97
	v_rcp_f32_e32 v98, v97
	s_nop 0
	v_mul_f32_e32 v193, v173, v98
	s_nop 0
	s_nop 0
	v_mul_f32_e32 v97, v175, v175
	v_mul_f32_e32 v97, 0xbdd2d3e8, v97
	v_add_f32_e32 v97, 0xc0135761, v97
	v_mul_f32_e32 v97, v175, v97
	v_exp_f32_e32 v97, v97
	s_nop 0
	v_add_f32_e32 v97, 1.0, v97
	v_rcp_f32_e32 v98, v97
	s_nop 0
	v_mul_f32_e32 v195, v175, v98
	s_nop 0
	s_nop 0
	v_mul_f32_e32 v97, v185, v185
	v_mul_f32_e32 v97, 0xbdd2d3e8, v97
	v_add_f32_e32 v97, 0xc0135761, v97
	v_mul_f32_e32 v97, v185, v97
	v_exp_f32_e32 v97, v97
	s_nop 0
	v_add_f32_e32 v97, 1.0, v97
	v_rcp_f32_e32 v98, v97
	s_nop 0
	v_mul_f32_e32 v197, v185, v98
	s_nop 0
	s_nop 0
	v_mul_f32_e32 v97, v187, v187
	v_mul_f32_e32 v97, 0xbdd2d3e8, v97
	v_add_f32_e32 v97, 0xc0135761, v97
	v_mul_f32_e32 v97, v187, v97
	v_exp_f32_e32 v97, v97
	s_nop 0
	v_add_f32_e32 v97, 1.0, v97
	v_rcp_f32_e32 v98, v97
	s_nop 0
	v_mul_f32_e32 v198, v187, v98
	v_mul_f32_e32 v99, v109, v109
	v_mul_f32_e32 v99, 0xbdd2d3e8, v99
	v_add_f32_e32 v99, 0xc0135761, v99
	v_mul_f32_e32 v99, v109, v99
	v_exp_f32_e32 v99, v99
	s_nop 0
	v_add_f32_e32 v99, 1.0, v99
	v_rcp_f32_e32 v114, v99
	s_nop 0
	v_mul_f32_e32 v115, v109, v114
	v_mul_f32_e32 v97, v105, v105
	v_fmac_f32_e32 v97, v96, v96
	v_fmac_f32_e32 v97, v189, v189
	v_fmac_f32_e32 v97, v191, v191
	v_fmac_f32_e32 v97, v193, v193
	v_fmac_f32_e32 v97, v195, v195
	v_fmac_f32_e32 v97, v197, v197
	v_mul_f32_e32 v98, v108, v108
	v_mul_f32_e32 v98, 0xbdd2d3e8, v98
	v_add_f32_e32 v98, 0xc0135761, v98
	v_mul_f32_e32 v98, v108, v98
	v_exp_f32_e32 v98, v98
	s_nop 0
	v_add_f32_e32 v98, 1.0, v98
	v_rcp_f32_e32 v99, v98
	s_nop 0
	v_mul_f32_e32 v114, v108, v99
	v_fmac_f32_e32 v97, v198, v198
	v_pk_mul_f32 v[98:99], v[114:115], v[114:115]
	s_nop 0
	v_add_f32_e32 v97, v98, v97
	v_add_f32_e32 v97, v99, v97
	s_nop 0
	s_nop 0
	v_mul_f32_e32 v99, v113, v113
	v_mul_f32_e32 v99, 0xbdd2d3e8, v99
	v_add_f32_e32 v99, 0xc0135761, v99
	v_mul_f32_e32 v99, v113, v99
	v_exp_f32_e32 v99, v99
	s_nop 0
	v_add_f32_e32 v99, 1.0, v99
	v_rcp_f32_e32 v100, v99
	s_nop 0
	v_mul_f32_e32 v117, v113, v100
	s_nop 0
	v_mul_f32_e32 v98, v112, v112
	v_mul_f32_e32 v98, 0xbdd2d3e8, v98
	v_add_f32_e32 v98, 0xc0135761, v98
	v_mul_f32_e32 v98, v112, v98
	v_exp_f32_e32 v98, v98
	s_nop 0
	v_add_f32_e32 v98, 1.0, v98
	v_rcp_f32_e32 v99, v98
	s_nop 0
	v_mul_f32_e32 v116, v112, v99
	v_pk_mul_f32 v[98:99], v[116:117], v[116:117]
	s_nop 0
	v_add_f32_e32 v97, v98, v97
	v_add_f32_e32 v97, v99, v97
	s_nop 0
	s_nop 0
	v_mul_f32_e32 v99, v111, v111
	v_mul_f32_e32 v99, 0xbdd2d3e8, v99
	v_add_f32_e32 v99, 0xc0135761, v99
	v_mul_f32_e32 v99, v111, v99
	v_exp_f32_e32 v99, v99
	s_nop 0
	v_add_f32_e32 v99, 1.0, v99
	v_rcp_f32_e32 v100, v99
	s_nop 0
	v_mul_f32_e32 v119, v111, v100
	s_nop 0
	v_mul_f32_e32 v98, v110, v110
	v_mul_f32_e32 v98, 0xbdd2d3e8, v98
	v_add_f32_e32 v98, 0xc0135761, v98
	v_mul_f32_e32 v98, v110, v98
	v_exp_f32_e32 v98, v98
	s_nop 0
	v_add_f32_e32 v98, 1.0, v98
	v_rcp_f32_e32 v99, v98
	s_nop 0
	v_mul_f32_e32 v118, v110, v99
	v_pk_mul_f32 v[98:99], v[118:119], v[118:119]
	s_nop 0
	v_add_f32_e32 v97, v98, v97
	v_add_f32_e32 v97, v99, v97
	s_nop 0
	s_nop 0
	v_mul_f32_e32 v99, v107, v107
	v_mul_f32_e32 v99, 0xbdd2d3e8, v99
	v_add_f32_e32 v99, 0xc0135761, v99
	v_mul_f32_e32 v99, v107, v99
	v_exp_f32_e32 v99, v99
	s_nop 0
	v_add_f32_e32 v99, 1.0, v99
	v_rcp_f32_e32 v100, v99
	s_nop 0
	v_mul_f32_e32 v123, v107, v100
	s_lshr_b32 s54, s89, 4
	s_and_b32 s54, s54, 0x78
	s_add_i32 s54, s54, s29
	v_mul_f32_e32 v98, v106, v106
	v_mul_f32_e32 v98, 0xbdd2d3e8, v98
	v_add_f32_e32 v98, 0xc0135761, v98
	v_mul_f32_e32 v98, v106, v98
	v_exp_f32_e32 v98, v98
	s_nop 0
	v_add_f32_e32 v98, 1.0, v98
	v_rcp_f32_e32 v99, v98
	s_nop 0
	v_mul_f32_e32 v122, v106, v99
	v_pk_mul_f32 v[98:99], v[122:123], v[122:123]
	s_mov_b32 s55, s9
	v_add_f32_e32 v97, v98, v97
	v_add_f32_e32 v97, v99, v97
	v_and_b32_e32 v99, 64, v165
	v_xor_b32_e32 v98, 16, v165
	v_add_u32_e32 v99, 64, v99
	v_cmp_lt_i32_e32 vcc, v98, v99
	s_lshl_b64 s[54:55], s[54:55], 14
	s_add_u32 s53, s36, s56
	v_cndmask_b32_e32 v98, v165, v98, vcc
	v_lshlrev_b32_e32 v98, 2, v98
	v_mov_b32_e32 v98, v97
	s_nop 1
	v_permlane16_swap_b32 v97, v98
	v_readlane_b32 s36, v254, 35
	s_addc_u32 s56, s36, s57
	s_add_u32 s54, s53, s54
	s_addc_u32 s55, s56, s55
	s_waitcnt lgkmcnt(0)
; __device__ __forceinline__ unsigned f2bf(float f) { unsigned u = __float_as_uint(f); return (u + 0x7fffu + ((u >> 16) & 1u)) >> 16; }
; __device__ __forceinline__ float head_ssq(const float (&v)[16]) {
;     float s = 0.f;
; #pragma unroll
;     for (int i = 0; i < 16; ++i) s += v[i] * v[i];
;     s += __shfl_xor(s, 16); s += __shfl_xor(s, 32);
;     return s;
;     __device__ __forceinline__ void operator()(const f32x4 (&acc)[2][2][4][2], const pg8::Unit& u, int wr, int wc, int fr, int fq) const {
;     ...
;                     const float rn = rsqrtf(head_ssq(y) * (1.f / 64.f) + EPS);
;                     bf16_t* p = zvT + (((size_t)b * 16 + (s >> 7)) * 8 + g) * 8192 + (s & 127);
; #pragma unroll
;                     for (int i = 0; i < 16; ++i) { const int d = 32 * (i >> 3) + d0 + (i & 7); p[d * 128] = (bf16_t)f2bf(y[i] * rn * g_sgu[g * 64 + d]); }
	v_add_f32_e32 v97, v97, v98
	v_xor_b32_e32 v98, 32, v165
	v_cmp_lt_i32_e32 vcc, v98, v99
	s_mov_b64 s[56:57], s[40:41]
	s_nop 0
	v_cndmask_b32_e32 v98, v165, v98, vcc
	v_lshlrev_b32_e32 v98, 2, v98
	v_mov_b32_e32 v98, v97
	s_nop 1
	v_permlane32_swap_b32 v97, v98
	s_waitcnt lgkmcnt(0)
	v_add_f32_e32 v97, v97, v98
	v_fmamk_f32 v97, v97, 0x3c800000, v161
	v_cmp_gt_f32_e32 vcc, s61, v97
	v_mul_f32_e32 v98, 0x4b800000, v97
	s_nop 0
	v_cndmask_b32_e32 v97, v97, v98, vcc
	v_rsq_f32_e32 v97, v97
	s_nop 0
	v_mul_f32_e32 v98, 0x45800000, v97
	v_cndmask_b32_e32 v199, v97, v98, vcc
	v_and_b32_e32 v97, 0x5f, v104
	v_lshlrev_b32_e32 v136, 1, v97
	v_lshl_add_u64 v[124:125], s[54:55], 0, v[136:137]
	s_mov_b64 s[54:55], s[38:39]
	v_readlane_b32 s36, v254, 8
	v_or_b32_e32 v136, s27, v140
	v_readlane_b32 s37, v254, 9
	v_mul_f32_e32 v166, v96, v199
	v_readlane_b32 s50, v254, 22
	v_lshl_add_u64 v[100:101], v[136:137], 2, s[36:37]
	global_load_dwordx4 v[96:99], v[100:101], off offset:16
	s_nop 0
	global_load_dwordx4 v[100:103], v[100:101], off
	v_readlane_b32 s51, v254, 23
	v_readlane_b32 s38, v254, 10
	v_readlane_b32 s39, v254, 11
	v_readlane_b32 s40, v254, 12
	v_readlane_b32 s41, v254, 13
	v_readlane_b32 s42, v254, 14
	v_readlane_b32 s43, v254, 15
	v_readlane_b32 s49, v254, 21
	v_readlane_b32 s50, v254, 39
	s_mov_b64 s[38:39], s[54:55]
	s_mov_b64 s[42:43], s[58:59]
	s_mov_b64 s[40:41], s[56:57]
	v_readlane_b32 s49, v254, 41
	v_readlane_b32 s51, v254, 40
	s_mov_b64 s[54:55], 0
	v_readlane_b32 s44, v254, 16
	v_readlane_b32 s45, v254, 17
	v_readlane_b32 s46, v254, 18
	v_readlane_b32 s47, v254, 19
	v_readlane_b32 s48, v254, 20
	s_waitcnt vmcnt(0)
	v_mul_f32_e32 v100, v100, v166
	v_bfe_u32 v136, v100, 16, 1
	v_add3_u32 v100, v100, v136, s20
	v_lshlrev_b32_e32 v136, 1, v142
	v_lshl_add_u64 v[200:201], v[124:125], 0, v[136:137]
	global_store_short_d16_hi v[200:201], v100, off
	v_mul_f32_e32 v100, v105, v199
	v_add_u32_e32 v136, s27, v140
	v_mul_f32_e32 v100, v101, v100
	v_lshl_add_u64 v[200:201], v[136:137], 2, s[36:37]
	v_bfe_u32 v101, v100, 16, 1
	v_lshlrev_b32_e32 v136, 1, v144
	v_add3_u32 v105, v100, v101, s20
	v_lshl_add_u64 v[100:101], v[124:125], 0, v[136:137]
	global_store_short_d16_hi v[100:101], v105, off
	v_mul_f32_e32 v100, v189, v199
	v_mul_f32_e32 v100, v102, v100
	v_bfe_u32 v101, v100, 16, 1
	v_lshlrev_b32_e32 v136, 1, v146
	v_add3_u32 v102, v100, v101, s20
	v_lshl_add_u64 v[100:101], v[124:125], 0, v[136:137]
	global_store_short_d16_hi v[100:101], v102, off
	v_mul_f32_e32 v100, v191, v199
	v_mul_f32_e32 v100, v103, v100
	v_bfe_u32 v101, v100, 16, 1
	v_lshlrev_b32_e32 v136, 1, v148
	v_add3_u32 v102, v100, v101, s20
	v_lshl_add_u64 v[100:101], v[124:125], 0, v[136:137]
	global_store_short_d16_hi v[100:101], v102, off
	v_mul_f32_e32 v100, v193, v199
	v_mul_f32_e32 v96, v96, v100
	v_bfe_u32 v100, v96, 16, 1
	v_lshlrev_b32_e32 v136, 1, v150
	v_add3_u32 v96, v96, v100, s20
	v_lshl_add_u64 v[100:101], v[124:125], 0, v[136:137]
	global_store_short_d16_hi v[100:101], v96, off
	v_mul_f32_e32 v96, v195, v199
	v_mul_f32_e32 v96, v96, v97
	v_bfe_u32 v97, v96, 16, 1
	v_lshlrev_b32_e32 v136, 1, v152
	v_add3_u32 v100, v96, v97, s20
	v_lshl_add_u64 v[96:97], v[124:125], 0, v[136:137]
	global_store_short_d16_hi v[96:97], v100, off
	v_mul_f32_e32 v96, v197, v199
	v_mul_f32_e32 v96, v96, v98
	v_bfe_u32 v97, v96, 16, 1
	v_lshlrev_b32_e32 v136, 1, v154
	v_add3_u32 v98, v96, v97, s20
	v_lshl_add_u64 v[96:97], v[124:125], 0, v[136:137]
	global_store_short_d16_hi v[96:97], v98, off
	v_mul_f32_e32 v96, v198, v199
	v_mul_f32_e32 v96, v96, v99
	v_bfe_u32 v97, v96, 16, 1
	v_lshlrev_b32_e32 v136, 1, v156
	v_add3_u32 v98, v96, v97, s20
	v_lshl_add_u64 v[96:97], v[124:125], 0, v[136:137]
	global_store_short_d16_hi v[96:97], v98, off
	global_load_dwordx4 v[96:99], v[200:201], off offset:144
	s_nop 0
	global_load_dwordx4 v[100:103], v[200:201], off offset:128
	v_mul_f32_e32 v105, v114, v199
	v_lshlrev_b32_e32 v136, 1, v158
	v_lshl_add_u64 v[200:201], v[124:125], 0, v[136:137]
	v_lshlrev_b32_e32 v136, 1, v160
	s_waitcnt vmcnt(0)
	v_mul_f32_e32 v100, v105, v100
	v_bfe_u32 v105, v100, 16, 1
	v_add3_u32 v100, v100, v105, s20
	global_store_short_d16_hi v[200:201], v100, off
	v_mul_f32_e32 v100, v115, v199
	v_mul_f32_e32 v100, v100, v101
	v_bfe_u32 v101, v100, 16, 1
	v_add3_u32 v105, v100, v101, s20
	v_lshl_add_u64 v[100:101], v[124:125], 0, v[136:137]
	global_store_short_d16_hi v[100:101], v105, off
	v_mul_f32_e32 v100, v116, v199
	v_mul_f32_e32 v100, v100, v102
	v_bfe_u32 v101, v100, 16, 1
	v_lshlrev_b32_e32 v136, 1, v162
	v_add3_u32 v102, v100, v101, s20
	v_lshl_add_u64 v[100:101], v[124:125], 0, v[136:137]
	global_store_short_d16_hi v[100:101], v102, off
	v_mul_f32_e32 v100, v117, v199
	v_mul_f32_e32 v100, v100, v103
	v_bfe_u32 v101, v100, 16, 1
	v_lshlrev_b32_e32 v136, 1, v164
	v_add3_u32 v102, v100, v101, s20
	v_lshl_add_u64 v[100:101], v[124:125], 0, v[136:137]
	global_store_short_d16_hi v[100:101], v102, off
	v_mul_f32_e32 v100, v118, v199
	v_mul_f32_e32 v96, v100, v96
	v_bfe_u32 v100, v96, 16, 1
	v_add3_u32 v96, v96, v100, s20
	v_or_b32_e32 v100, 0x1200, v142
	v_lshlrev_b32_e32 v136, 1, v100
	v_lshl_add_u64 v[100:101], v[124:125], 0, v[136:137]
	global_store_short_d16_hi v[100:101], v96, off
	v_mul_f32_e32 v96, v119, v199
	v_mul_f32_e32 v96, v96, v97
	v_bfe_u32 v97, v96, 16, 1
	v_add3_u32 v100, v96, v97, s20
	v_or_b32_e32 v96, 0x1280, v142
	v_lshlrev_b32_e32 v136, 1, v96
	v_lshl_add_u64 v[96:97], v[124:125], 0, v[136:137]
	global_store_short_d16_hi v[96:97], v100, off
	v_mul_f32_e32 v96, v122, v199
	v_mul_f32_e32 v96, v96, v98
	v_bfe_u32 v97, v96, 16, 1
	v_add3_u32 v98, v96, v97, s20
	v_or_b32_e32 v96, 0x1300, v142
	v_lshlrev_b32_e32 v136, 1, v96
	v_lshl_add_u64 v[96:97], v[124:125], 0, v[136:137]
	global_store_short_d16_hi v[96:97], v98, off
	v_mul_f32_e32 v96, v123, v199
	v_mul_f32_e32 v96, v96, v99
	v_bfe_u32 v97, v96, 16, 1
	v_lshlrev_b32_e32 v136, 1, v172
	v_add3_u32 v98, v96, v97, s20
	v_lshl_add_u64 v[96:97], v[124:125], 0, v[136:137]
	global_store_short_d16_hi v[96:97], v98, off

; __device__ __forceinline__ float head_ssq(const float (&v)[16]) {
;     float s = 0.f;
; #pragma unroll
;     for (int i = 0; i < 16; ++i) s += v[i] * v[i];
;     s += __shfl_xor(s, 16); s += __shfl_xor(s, 32);
;     return s;
;     __device__ __forceinline__ void operator()(const f32x4 (&acc)[2][2][4][2], const pg8::Unit& u, int wr, int wc, int fr, int fq) const {
;     ...
;                 if (cs < 8 || cs == 12 || cs == 13 || cs == 16 || cs == 17) {
;                     const float* gg = cs < 8 ? g_q : (cs < 14 ? g_k + 64 : g_k + 128);
;                     const float rn = rsqrtf(head_ssq(v) * (1.f / 64.f) + EPS) * (cs < 8 ? QSCALE : 1.f);
;                     float y[16];
; #pragma unroll
;                     for (int i = 0; i < 16; ++i) y[i] = v[i] * rn * gg[32 * (i >> 3) + d0 + (i & 7)];
;                     float r1[8], r2[8];
; #pragma unroll
;                     for (int i = 0; i < 8; ++i) { int di = d0 + i; asm volatile("" : "+v"(di));
;                         const float frev = __builtin_amdgcn_exp2f(-(float)di * (13.287712379549449f / 32.f)) * 0.15915494309189535f;
;                         float xr = (float)s * frev; xr -= __builtin_rintf(xr);
;                         const float c = __builtin_amdgcn_cosf(xr), sn = __builtin_amdgcn_sinf(xr); r1[i] = y[i] * c - y[8 + i] * sn; r2[i] = y[8 + i] * c + y[i] * sn; }
.LBB0_223:
	global_load_dwordx4 v[96:99], v167, s[54:55]
	global_load_dwordx4 v[100:103], v167, s[54:55] offset:16
	global_load_dwordx4 v[116:119], v167, s[54:55] offset:128
	global_load_dwordx4 v[122:125], v167, s[54:55] offset:144
	v_mul_f32_e32 v105, v127, v127
	v_fmac_f32_e32 v105, v126, v126
	v_fmac_f32_e32 v105, v169, v169
	v_fmac_f32_e32 v105, v171, v171
	v_fmac_f32_e32 v105, v173, v173
	v_fmac_f32_e32 v105, v175, v175
	v_fmac_f32_e32 v105, v185, v185
	v_pk_mul_f32 v[114:115], v[108:109], v[108:109]
	v_fmac_f32_e32 v105, v187, v187
	v_add_f32_e32 v105, v114, v105
	v_pk_mul_f32 v[198:199], v[112:113], v[112:113]
	v_add_f32_e32 v105, v115, v105
	v_add_f32_e32 v105, v198, v105
	v_pk_mul_f32 v[200:201], v[110:111], v[110:111]
	v_and_b32_e32 v166, 64, v165
	v_add_f32_e32 v105, v199, v105
	v_xor_b32_e32 v136, 16, v165
	v_add_u32_e32 v166, 64, v166
	v_add_f32_e32 v105, v200, v105
	v_pk_mul_f32 v[202:203], v[106:107], v[106:107]
	v_cmp_lt_i32_e32 vcc, v136, v166
	v_add_f32_e32 v105, v201, v105
	v_add_f32_e32 v105, v202, v105
	v_cndmask_b32_e32 v136, v165, v136, vcc
	v_lshlrev_b32_e32 v136, 2, v136
	v_add_f32_e32 v105, v203, v105
	v_mov_b32_e32 v114, v105
	s_nop 1
	v_permlane16_swap_b32 v105, v114
	v_xor_b32_e32 v115, 32, v165
	v_cmp_lt_i32_e32 vcc, v115, v166
	v_cvt_f32_u32_e32 v136, v121
	s_mov_b64 s[54:55], -1
	v_cndmask_b32_e32 v115, v165, v115, vcc
	v_lshlrev_b32_e32 v115, 2, v115
	s_waitcnt lgkmcnt(0)
	v_add_f32_e32 v105, v105, v114
	v_mov_b32_e32 v114, v105
	s_nop 1
	v_permlane32_swap_b32 v105, v114
	v_mov_b32_e32 v115, v140
	s_waitcnt lgkmcnt(0)
	v_add_f32_e32 v105, v105, v114
	v_fmamk_f32 v105, v105, 0x3c800000, v161
	v_mul_f32_e32 v114, 0x4b800000, v105
	v_cmp_gt_f32_e32 vcc, s61, v105
	v_cvt_f32_i32_e32 v115, v115
	s_nop 0
	v_cndmask_b32_e32 v105, v105, v114, vcc
	v_rsq_f32_e32 v105, v105
	v_mul_f32_e32 v114, 0xbed49a78, v115
	v_exp_f32_e32 v115, v114
	v_mul_f32_e32 v114, 0x45800000, v105
	v_cndmask_b32_e32 v105, v105, v114, vcc
	v_mul_f32_e32 v105, s53, v105
	v_mul_f32_e32 v114, v126, v105
	v_mul_f32_e32 v126, v127, v105
	v_mul_f32_e32 v127, v169, v105
	v_mul_f32_e32 v166, v171, v105
	v_mul_f32_e32 v168, v173, v105
	v_mul_f32_e32 v169, v175, v105
	v_mul_f32_e32 v170, v185, v105
	v_mul_f32_e32 v171, v187, v105
	v_mul_f32_e32 v173, v108, v105
	v_mul_f32_e32 v175, v109, v105
	v_mul_f32_e32 v185, v112, v105
	v_mul_f32_e32 v187, v113, v105
	v_mul_f32_e32 v189, v110, v105
	v_mul_f32_e32 v191, v111, v105
	v_mul_f32_e32 v193, v106, v105
	s_and_b64 vcc, exec, s[6:7]
	s_waitcnt vmcnt(3)
	v_mul_f32_e32 v112, v96, v114
	v_mul_f32_e32 v96, v107, v105
	v_mul_f32_e32 v105, 0.15915494, v115
	v_mul_f32_e32 v107, v105, v136
	v_rndne_f32_e32 v107, v107
	v_fma_f32 v105, v105, v136, -v107
	v_mov_b32_e32 v107, v141
	s_waitcnt vmcnt(2)
	v_mul_f32_e32 v111, v101, v169
	v_cvt_f32_i32_e32 v107, v107
	s_waitcnt vmcnt(1)
	v_mul_f32_e32 v101, v116, v173
	v_sin_f32_e32 v116, v105
	v_cos_f32_e32 v105, v105
	v_mul_f32_e32 v107, 0xbed49a78, v107
	v_mul_f32_e32 v109, v103, v171
	v_mul_f32_e32 v103, v117, v175
	v_exp_f32_e32 v117, v107
	s_waitcnt vmcnt(0)
	v_mul_f32_e32 v115, v96, v125
	v_mul_f32_e32 v96, v101, v116
	v_fma_f32 v107, v112, v105, -v96
	v_mul_f32_e32 v96, v112, v116
	v_fmac_f32_e32 v96, v101, v105
	v_mul_f32_e32 v105, 0.15915494, v117
	v_mov_b32_e32 v117, v143
	v_mul_f32_e32 v113, v99, v166
	v_cvt_f32_i32_e32 v117, v117
	v_mul_f32_e32 v99, v185, v118
	v_mul_f32_e32 v106, v102, v170
	v_mul_f32_e32 v102, v187, v119
	v_mul_f32_e32 v117, 0xbed49a78, v117
	v_exp_f32_e32 v118, v117
	v_mul_f32_e32 v116, v105, v136
	v_rndne_f32_e32 v116, v116
	v_fma_f32 v105, v105, v136, -v116
	v_mul_f32_e32 v118, 0.15915494, v118
	v_mul_f32_e32 v119, v118, v136
	v_rndne_f32_e32 v119, v119
	v_fma_f32 v118, v118, v136, -v119
	v_mov_b32_e32 v119, v145
	v_sin_f32_e32 v116, v105
	v_cos_f32_e32 v105, v105
	v_cvt_f32_i32_e32 v119, v119
	v_mul_f32_e32 v114, v97, v126
	v_mul_f32_e32 v110, v98, v127
	v_mul_f32_e32 v98, v189, v122
	v_mul_f32_e32 v117, v103, v116
	v_mul_f32_e32 v116, v114, v116
	v_sin_f32_e32 v122, v118
	v_fma_f32 v117, v114, v105, -v117
	v_fmac_f32_e32 v116, v103, v105
	v_cos_f32_e32 v105, v118
	v_mul_f32_e32 v119, 0xbed49a78, v119
	v_mul_f32_e32 v108, v100, v168
	v_mul_f32_e32 v100, v191, v123
	v_exp_f32_e32 v123, v119
	v_mul_f32_e32 v118, v99, v122
	v_fma_f32 v119, v110, v105, -v118
	v_mul_f32_e32 v118, v110, v122
	v_fmac_f32_e32 v118, v99, v105
	v_mul_f32_e32 v105, 0.15915494, v123
	v_mov_b32_e32 v123, v147
	v_mul_f32_e32 v97, v193, v124
	v_cvt_f32_i32_e32 v123, v123
	v_mul_f32_e32 v122, v105, v136
	v_rndne_f32_e32 v122, v122
	v_fma_f32 v105, v105, v136, -v122
	v_mul_f32_e32 v123, 0xbed49a78, v123
	v_exp_f32_e32 v124, v123
	v_sin_f32_e32 v122, v105
	v_cos_f32_e32 v105, v105
	v_mov_b32_e32 v169, v157
	v_mul_f32_e32 v124, 0.15915494, v124
	v_mul_f32_e32 v125, v124, v136
	v_rndne_f32_e32 v125, v125
	v_fma_f32 v124, v124, v136, -v125
	v_mov_b32_e32 v125, v153
	v_mul_f32_e32 v123, v102, v122
	v_cvt_f32_i32_e32 v125, v125
	v_mul_f32_e32 v122, v113, v122
	v_sin_f32_e32 v126, v124
	v_fma_f32 v123, v113, v105, -v123
	v_fmac_f32_e32 v122, v102, v105
	v_cos_f32_e32 v105, v124
	v_mul_f32_e32 v125, 0xbed49a78, v125
	v_exp_f32_e32 v127, v125
	v_mul_f32_e32 v124, v98, v126
	v_fma_f32 v125, v108, v105, -v124
	v_mul_f32_e32 v124, v108, v126
	v_fmac_f32_e32 v124, v98, v105
	v_mul_f32_e32 v105, 0.15915494, v127
	v_mov_b32_e32 v127, v155
	v_mul_f32_e32 v126, v105, v136
	v_cvt_f32_i32_e32 v127, v127
	v_cvt_f32_i32_e32 v169, v169
	v_rndne_f32_e32 v126, v126
	v_fma_f32 v105, v105, v136, -v126
	v_mul_f32_e32 v127, 0xbed49a78, v127
	v_exp_f32_e32 v166, v127
	v_sin_f32_e32 v126, v105
	v_cos_f32_e32 v105, v105
	v_mul_f32_e32 v169, 0xbed49a78, v169
	v_mul_f32_e32 v166, 0.15915494, v166
	v_mul_f32_e32 v168, v166, v136
	v_rndne_f32_e32 v168, v168
	v_fma_f32 v166, v166, v136, -v168
	v_cos_f32_e32 v168, v166
	v_sin_f32_e32 v166, v166
	v_exp_f32_e32 v169, v169
	v_mul_f32_e32 v127, v100, v126
	v_mul_f32_e32 v126, v111, v126
	v_fma_f32 v127, v111, v105, -v127
	v_fmac_f32_e32 v126, v100, v105
	v_mul_f32_e32 v105, v97, v166
	v_fma_f32 v173, v106, v168, -v105
	v_mul_f32_e32 v105, 0.15915494, v169
	v_mul_f32_e32 v169, v105, v136
	v_rndne_f32_e32 v169, v169
	v_fma_f32 v105, v105, v136, -v169
	v_sin_f32_e32 v136, v105
	v_cos_f32_e32 v105, v105
	v_mul_f32_e32 v169, v106, v166
	v_fmac_f32_e32 v169, v97, v168
	v_mul_f32_e32 v166, v115, v136
	v_mul_f32_e32 v171, v109, v136
	v_fma_f32 v175, v109, v105, -v166
	v_fmac_f32_e32 v171, v115, v105
	s_cbranch_vccnz .LBB0_225
;     __device__ __forceinline__ void operator()(const f32x4 (&acc)[2][2][4][2], const pg8::Unit& u, int wr, int wc, int fr, int fq) const {
;     ...
;                         bf16_t* p = (cs < 14 ? ksl : kwn) + ((size_t)(b * 2 + (cs & 1)) * 2048 + s) * 64 + d0; store8(p, r1); store8(p + 32, r2);
	s_and_b64 s[54:55], s[10:11], exec
	s_cselect_b32 s53, s77, s76
	s_cselect_b32 s56, s74, s75
	s_lshl_b32 s54, s52, 1
	s_or_b32 s54, s54, s97
	s_ashr_i32 s55, s54, 31
	s_lshl_b64 s[54:55], s[54:55], 18
	s_add_u32 s54, s56, s54
	s_addc_u32 s55, s53, s55
	v_lshlrev_b32_e32 v136, 7, v121
	v_lshl_add_u64 v[198:199], s[54:55], 0, v[136:137]
	v_lshlrev_b32_e32 v136, 1, v140
	v_lshl_add_u64 v[202:203], v[198:199], 0, v[136:137]
	v_cvt_pk_bf16_f32 v198, v107, v117
	v_cvt_pk_bf16_f32 v199, v119, v123
	v_cvt_pk_bf16_f32 v200, v125, v127
	v_cvt_pk_bf16_f32 v201, v173, v175
	s_mov_b64 s[54:55], 0
	global_store_dwordx4 v[202:203], v[198:201], off
	s_nop 1
	v_cvt_pk_bf16_f32 v198, v96, v116
	v_cvt_pk_bf16_f32 v199, v118, v122
	v_cvt_pk_bf16_f32 v200, v124, v126
	v_cvt_pk_bf16_f32 v201, v169, v171
	global_store_dwordx4 v[202:203], v[198:201], off offset:64

; __device__ __forceinline__ float gelu_tanh(float x) {
;     const float u = 0.7978845608028654f * (x + 0.044715f * x * x * x);
;     return x / (1.f + __expf(-2.f * u));
; }
; __device__ __forceinline__ float head_ssq(const float (&v)[16]) {
;     float s = 0.f;
; #pragma unroll
;     for (int i = 0; i < 16; ++i) s += v[i] * v[i];
;     s += __shfl_xor(s, 16); s += __shfl_xor(s, 32);
;     return s;
.LBB0_236:
	s_andn2_b64 vcc, exec, s[72:73]
	s_mov_b64 s[54:55], -1
	s_cbranch_vccnz .LBB0_252
	s_andn2_b64 vcc, exec, s[70:71]
	s_cbranch_vccnz .LBB0_249
	s_andn2_b64 vcc, exec, s[42:43]
	s_cbranch_vccnz .LBB0_246
	s_andn2_b64 vcc, exec, s[40:41]
	s_cbranch_vccnz .LBB0_241
	s_ashr_i32 s53, s52, 31
	s_lshl_b64 s[56:57], s[52:53], 21
	v_readlane_b32 s36, v254, 33
	s_mov_b64 s[58:59], s[42:43]
	v_mul_f32_e32 v80, v109, v109
	v_mul_f32_e32 v80, 0xbdd2d3e8, v80
	v_add_f32_e32 v80, 0xc0135761, v80
	v_mul_f32_e32 v80, v109, v80
	v_exp_f32_e32 v80, v80
	s_nop 0
	v_add_f32_e32 v80, 1.0, v80
	v_rcp_f32_e32 v81, v80
	s_nop 0
	v_mul_f32_e32 v80, v109, v81
	s_nop 0
	s_nop 0
	v_mul_f32_e32 v81, v110, v110
	v_mul_f32_e32 v81, 0xbdd2d3e8, v81
	v_add_f32_e32 v81, 0xc0135761, v81
	v_mul_f32_e32 v81, v110, v81
	v_exp_f32_e32 v81, v81
	s_nop 0
	v_add_f32_e32 v81, 1.0, v81
	v_rcp_f32_e32 v82, v81
	s_nop 0
	v_mul_f32_e32 v89, v110, v82
	s_nop 0
	s_nop 0
	v_mul_f32_e32 v81, v111, v111
	v_mul_f32_e32 v81, 0xbdd2d3e8, v81
	v_add_f32_e32 v81, 0xc0135761, v81
	v_mul_f32_e32 v81, v111, v81
	v_exp_f32_e32 v81, v81
	s_nop 0
	v_add_f32_e32 v81, 1.0, v81
	v_rcp_f32_e32 v82, v81
	s_nop 0
	v_mul_f32_e32 v117, v111, v82
	s_nop 0
	s_nop 0
	v_mul_f32_e32 v81, v112, v112
	v_mul_f32_e32 v81, 0xbdd2d3e8, v81
	v_add_f32_e32 v81, 0xc0135761, v81
	v_mul_f32_e32 v81, v112, v81
	v_exp_f32_e32 v81, v81
	s_nop 0
	v_add_f32_e32 v81, 1.0, v81
	v_rcp_f32_e32 v82, v81
	s_nop 0
	v_mul_f32_e32 v118, v112, v82
	s_nop 0
	s_nop 0
	v_mul_f32_e32 v81, v113, v113
	v_mul_f32_e32 v81, 0xbdd2d3e8, v81
	v_add_f32_e32 v81, 0xc0135761, v81
	v_mul_f32_e32 v81, v113, v81
	v_exp_f32_e32 v81, v81
	s_nop 0
	v_add_f32_e32 v81, 1.0, v81
	v_rcp_f32_e32 v82, v81
	s_nop 0
	v_mul_f32_e32 v119, v113, v82
	s_nop 0
	s_nop 0
	v_mul_f32_e32 v81, v114, v114
	v_mul_f32_e32 v81, 0xbdd2d3e8, v81
	v_add_f32_e32 v81, 0xc0135761, v81
	v_mul_f32_e32 v81, v114, v81
	v_exp_f32_e32 v81, v81
	s_nop 0
	v_add_f32_e32 v81, 1.0, v81
	v_rcp_f32_e32 v82, v81
	s_nop 0
	v_mul_f32_e32 v121, v114, v82
	s_nop 0
	s_nop 0
	v_mul_f32_e32 v81, v115, v115
	v_mul_f32_e32 v81, 0xbdd2d3e8, v81
	v_add_f32_e32 v81, 0xc0135761, v81
	v_mul_f32_e32 v81, v115, v81
	v_exp_f32_e32 v81, v81
	s_nop 0
	v_add_f32_e32 v81, 1.0, v81
	v_rcp_f32_e32 v82, v81
	s_nop 0
	v_mul_f32_e32 v122, v115, v82
	s_nop 0
	s_nop 0
	v_mul_f32_e32 v81, v116, v116
	v_mul_f32_e32 v81, 0xbdd2d3e8, v81
	v_add_f32_e32 v81, 0xc0135761, v81
	v_mul_f32_e32 v81, v116, v81
	v_exp_f32_e32 v81, v81
	s_nop 0
	v_add_f32_e32 v81, 1.0, v81
	v_rcp_f32_e32 v82, v81
	s_nop 0
	v_mul_f32_e32 v123, v116, v82
	v_mul_f32_e32 v83, v93, v93
	v_mul_f32_e32 v83, 0xbdd2d3e8, v83
	v_add_f32_e32 v83, 0xc0135761, v83
	v_mul_f32_e32 v83, v93, v83
	v_exp_f32_e32 v83, v83
	s_nop 0
	v_add_f32_e32 v83, 1.0, v83
	v_rcp_f32_e32 v98, v83
	s_nop 0
	v_mul_f32_e32 v99, v93, v98
	v_mul_f32_e32 v81, v89, v89
	v_fmac_f32_e32 v81, v80, v80
	v_fmac_f32_e32 v81, v117, v117
	v_fmac_f32_e32 v81, v118, v118
	v_fmac_f32_e32 v81, v119, v119
	v_fmac_f32_e32 v81, v121, v121
	v_fmac_f32_e32 v81, v122, v122
	v_mul_f32_e32 v82, v92, v92
	v_mul_f32_e32 v82, 0xbdd2d3e8, v82
	v_add_f32_e32 v82, 0xc0135761, v82
	v_mul_f32_e32 v82, v92, v82
	v_exp_f32_e32 v82, v82
	s_nop 0
	v_add_f32_e32 v82, 1.0, v82
	v_rcp_f32_e32 v83, v82
	s_nop 0
	v_mul_f32_e32 v98, v92, v83
	v_fmac_f32_e32 v81, v123, v123
	v_pk_mul_f32 v[82:83], v[98:99], v[98:99]
	s_nop 0
	v_add_f32_e32 v81, v82, v81
	v_add_f32_e32 v81, v83, v81
	s_nop 0
	s_nop 0
	v_mul_f32_e32 v83, v97, v97
	v_mul_f32_e32 v83, 0xbdd2d3e8, v83
	v_add_f32_e32 v83, 0xc0135761, v83
	v_mul_f32_e32 v83, v97, v83
	v_exp_f32_e32 v83, v83
	s_nop 0
	v_add_f32_e32 v83, 1.0, v83
	v_rcp_f32_e32 v84, v83
	s_nop 0
	v_mul_f32_e32 v101, v97, v84
	s_nop 0
	v_mul_f32_e32 v82, v96, v96
	v_mul_f32_e32 v82, 0xbdd2d3e8, v82
	v_add_f32_e32 v82, 0xc0135761, v82
	v_mul_f32_e32 v82, v96, v82
	v_exp_f32_e32 v82, v82
	s_nop 0
	v_add_f32_e32 v82, 1.0, v82
	v_rcp_f32_e32 v83, v82
	s_nop 0
	v_mul_f32_e32 v100, v96, v83
	v_pk_mul_f32 v[82:83], v[100:101], v[100:101]
	s_nop 0
	v_add_f32_e32 v81, v82, v81
	v_add_f32_e32 v81, v83, v81
	s_nop 0
	s_nop 0
	v_mul_f32_e32 v83, v95, v95
	v_mul_f32_e32 v83, 0xbdd2d3e8, v83
	v_add_f32_e32 v83, 0xc0135761, v83
	v_mul_f32_e32 v83, v95, v83
	v_exp_f32_e32 v83, v83
	s_nop 0
	v_add_f32_e32 v83, 1.0, v83
	v_rcp_f32_e32 v84, v83
	s_nop 0
	v_mul_f32_e32 v103, v95, v84
	s_nop 0
	v_mul_f32_e32 v82, v94, v94
	v_mul_f32_e32 v82, 0xbdd2d3e8, v82
	v_add_f32_e32 v82, 0xc0135761, v82
	v_mul_f32_e32 v82, v94, v82
	v_exp_f32_e32 v82, v82
	s_nop 0
	v_add_f32_e32 v82, 1.0, v82
	v_rcp_f32_e32 v83, v82
	s_nop 0
	v_mul_f32_e32 v102, v94, v83
	v_pk_mul_f32 v[82:83], v[102:103], v[102:103]
	s_nop 0
	v_add_f32_e32 v81, v82, v81
	v_add_f32_e32 v81, v83, v81
	s_nop 0
	s_nop 0
	v_mul_f32_e32 v83, v91, v91
	v_mul_f32_e32 v83, 0xbdd2d3e8, v83
	v_add_f32_e32 v83, 0xc0135761, v83
	v_mul_f32_e32 v83, v91, v83
	v_exp_f32_e32 v83, v83
	s_nop 0
	v_add_f32_e32 v83, 1.0, v83
	v_rcp_f32_e32 v84, v83
	s_nop 0
	v_mul_f32_e32 v105, v91, v84
	s_lshr_b32 s54, s89, 4
	s_and_b32 s54, s54, 0x78
	s_add_i32 s54, s54, s29
	v_mul_f32_e32 v82, v90, v90
	v_mul_f32_e32 v82, 0xbdd2d3e8, v82
	v_add_f32_e32 v82, 0xc0135761, v82
	v_mul_f32_e32 v82, v90, v82
	v_exp_f32_e32 v82, v82
	s_nop 0
	v_add_f32_e32 v82, 1.0, v82
	v_rcp_f32_e32 v83, v82
	s_nop 0
	v_mul_f32_e32 v104, v90, v83
	v_pk_mul_f32 v[82:83], v[104:105], v[104:105]
	s_mov_b32 s55, s9
	v_add_f32_e32 v81, v82, v81
	v_add_f32_e32 v81, v83, v81
	v_and_b32_e32 v83, 64, v165
	v_xor_b32_e32 v82, 16, v165
	v_add_u32_e32 v83, 64, v83
	v_cmp_lt_i32_e32 vcc, v82, v83
	s_lshl_b64 s[54:55], s[54:55], 14
	s_add_u32 s53, s36, s56
	v_cndmask_b32_e32 v82, v165, v82, vcc
	v_lshlrev_b32_e32 v82, 2, v82
	v_mov_b32_e32 v82, v81
	s_nop 1
	v_permlane16_swap_b32 v81, v82
	v_readlane_b32 s36, v254, 35
	s_addc_u32 s56, s36, s57
	s_add_u32 s54, s53, s54
	s_addc_u32 s55, s56, s55
	s_waitcnt lgkmcnt(0)
; __device__ __forceinline__ unsigned f2bf(float f) { unsigned u = __float_as_uint(f); return (u + 0x7fffu + ((u >> 16) & 1u)) >> 16; }
;     __device__ __forceinline__ void operator()(const f32x4 (&acc)[2][2][4][2], const pg8::Unit& u, int wr, int wc, int fr, int fq) const {
;     ...
;                     const float rn = rsqrtf(head_ssq(y) * (1.f / 64.f) + EPS);
;                     bf16_t* p = zvT + (((size_t)b * 16 + (s >> 7)) * 8 + g) * 8192 + (s & 127);
; #pragma unroll
;                     for (int i = 0; i < 16; ++i) { const int d = 32 * (i >> 3) + d0 + (i & 7); p[d * 128] = (bf16_t)f2bf(y[i] * rn * g_sgu[g * 64 + d]); }
	v_add_f32_e32 v81, v81, v82
	v_xor_b32_e32 v82, 32, v165
	v_cmp_lt_i32_e32 vcc, v82, v83
	s_mov_b64 s[56:57], s[40:41]
	s_nop 0
	v_cndmask_b32_e32 v82, v165, v82, vcc
	v_lshlrev_b32_e32 v82, 2, v82
	v_mov_b32_e32 v82, v81
	s_nop 1
	v_permlane32_swap_b32 v81, v82
	s_waitcnt lgkmcnt(0)
	v_add_f32_e32 v81, v81, v82
	v_fmamk_f32 v81, v81, 0x3c800000, v161
	v_cmp_gt_f32_e32 vcc, s61, v81
	v_mul_f32_e32 v82, 0x4b800000, v81
	s_nop 0
	v_cndmask_b32_e32 v81, v81, v82, vcc
	v_rsq_f32_e32 v81, v81
	s_nop 0
	v_mul_f32_e32 v82, 0x45800000, v81
	v_cndmask_b32_e32 v124, v81, v82, vcc
	v_and_b32_e32 v81, 0x6f, v88
	v_lshlrev_b32_e32 v136, 1, v81
	v_lshl_add_u64 v[106:107], s[54:55], 0, v[136:137]
	s_mov_b64 s[54:55], s[38:39]
	v_readlane_b32 s36, v254, 8
	v_or_b32_e32 v136, s27, v140
	v_readlane_b32 s37, v254, 9
	v_mul_f32_e32 v125, v80, v124
	v_readlane_b32 s50, v254, 22
	v_lshl_add_u64 v[84:85], v[136:137], 2, s[36:37]
	global_load_dwordx4 v[80:83], v[84:85], off offset:16
	s_nop 0
	global_load_dwordx4 v[84:87], v[84:85], off
	v_lshlrev_b32_e32 v136, 1, v142
	v_lshl_add_u64 v[126:127], v[106:107], 0, v[136:137]
	v_add_u32_e32 v136, s27, v140
	v_readlane_b32 s51, v254, 23
	v_readlane_b32 s38, v254, 10
	v_readlane_b32 s39, v254, 11
	v_readlane_b32 s40, v254, 12
	v_readlane_b32 s41, v254, 13
	v_readlane_b32 s42, v254, 14
	v_readlane_b32 s43, v254, 15
	v_readlane_b32 s49, v254, 21
	v_readlane_b32 s50, v254, 39
	s_mov_b64 s[38:39], s[54:55]
	s_mov_b64 s[42:43], s[58:59]
	s_mov_b64 s[40:41], s[56:57]
	v_readlane_b32 s49, v254, 41
	v_readlane_b32 s51, v254, 40
	s_mov_b64 s[54:55], 0
	v_readlane_b32 s44, v254, 16
	v_readlane_b32 s45, v254, 17
	v_readlane_b32 s46, v254, 18
	v_readlane_b32 s47, v254, 19
	v_readlane_b32 s48, v254, 20
	s_waitcnt vmcnt(0)
	v_mul_f32_e32 v84, v84, v125
	v_bfe_u32 v125, v84, 16, 1
	v_add3_u32 v84, v84, v125, s20
	global_store_short_d16_hi v[126:127], v84, off
	v_mul_f32_e32 v84, v89, v124
	v_mul_f32_e32 v84, v85, v84
	v_lshl_add_u64 v[126:127], v[136:137], 2, s[36:37]
	v_bfe_u32 v85, v84, 16, 1
	v_lshlrev_b32_e32 v136, 1, v144
	v_add3_u32 v89, v84, v85, s20
	v_lshl_add_u64 v[84:85], v[106:107], 0, v[136:137]
	global_store_short_d16_hi v[84:85], v89, off
	v_mul_f32_e32 v84, v117, v124
	v_mul_f32_e32 v84, v86, v84
	v_bfe_u32 v85, v84, 16, 1
	v_lshlrev_b32_e32 v136, 1, v146
	v_add3_u32 v86, v84, v85, s20
	v_lshl_add_u64 v[84:85], v[106:107], 0, v[136:137]
	global_store_short_d16_hi v[84:85], v86, off
	v_mul_f32_e32 v84, v118, v124
	v_mul_f32_e32 v84, v87, v84
	v_bfe_u32 v85, v84, 16, 1
	v_lshlrev_b32_e32 v136, 1, v148
	v_add3_u32 v86, v84, v85, s20
	v_lshl_add_u64 v[84:85], v[106:107], 0, v[136:137]
	global_store_short_d16_hi v[84:85], v86, off
	v_mul_f32_e32 v84, v119, v124
	v_mul_f32_e32 v80, v80, v84
	v_bfe_u32 v84, v80, 16, 1
	v_lshlrev_b32_e32 v136, 1, v150
	v_add3_u32 v80, v80, v84, s20
	v_lshl_add_u64 v[84:85], v[106:107], 0, v[136:137]
	global_store_short_d16_hi v[84:85], v80, off
	v_mul_f32_e32 v80, v121, v124
	v_mul_f32_e32 v80, v80, v81
	v_bfe_u32 v81, v80, 16, 1
	v_lshlrev_b32_e32 v136, 1, v152
	v_add3_u32 v84, v80, v81, s20
	v_lshl_add_u64 v[80:81], v[106:107], 0, v[136:137]
	global_store_short_d16_hi v[80:81], v84, off
	v_mul_f32_e32 v80, v122, v124
	v_mul_f32_e32 v80, v80, v82
	v_bfe_u32 v81, v80, 16, 1
	v_lshlrev_b32_e32 v136, 1, v154
	v_add3_u32 v82, v80, v81, s20
	v_lshl_add_u64 v[80:81], v[106:107], 0, v[136:137]
	global_store_short_d16_hi v[80:81], v82, off
	v_mul_f32_e32 v80, v123, v124
	v_mul_f32_e32 v80, v80, v83
	v_bfe_u32 v81, v80, 16, 1
	v_lshlrev_b32_e32 v136, 1, v156
	v_add3_u32 v82, v80, v81, s20
	v_lshl_add_u64 v[80:81], v[106:107], 0, v[136:137]
	global_store_short_d16_hi v[80:81], v82, off
	global_load_dwordx4 v[80:83], v[126:127], off offset:144
	s_nop 0
	global_load_dwordx4 v[84:87], v[126:127], off offset:128
	v_mul_f32_e32 v89, v98, v124
	v_lshlrev_b32_e32 v136, 1, v158
	v_lshl_add_u64 v[118:119], v[106:107], 0, v[136:137]
	v_lshlrev_b32_e32 v136, 1, v160
	s_waitcnt vmcnt(0)
	v_mul_f32_e32 v84, v89, v84
	v_bfe_u32 v89, v84, 16, 1
	v_add3_u32 v84, v84, v89, s20
	global_store_short_d16_hi v[118:119], v84, off
	v_mul_f32_e32 v84, v99, v124
	v_mul_f32_e32 v84, v84, v85
	v_bfe_u32 v85, v84, 16, 1
	v_add3_u32 v89, v84, v85, s20
	v_lshl_add_u64 v[84:85], v[106:107], 0, v[136:137]
	global_store_short_d16_hi v[84:85], v89, off
	v_mul_f32_e32 v84, v100, v124
	v_mul_f32_e32 v84, v84, v86
	v_bfe_u32 v85, v84, 16, 1
	v_lshlrev_b32_e32 v136, 1, v162
	v_add3_u32 v86, v84, v85, s20
	v_lshl_add_u64 v[84:85], v[106:107], 0, v[136:137]
	global_store_short_d16_hi v[84:85], v86, off
	v_mul_f32_e32 v84, v101, v124
	v_mul_f32_e32 v84, v84, v87
	v_bfe_u32 v85, v84, 16, 1
	v_lshlrev_b32_e32 v136, 1, v164
	v_add3_u32 v86, v84, v85, s20
	v_lshl_add_u64 v[84:85], v[106:107], 0, v[136:137]
	global_store_short_d16_hi v[84:85], v86, off
	v_mul_f32_e32 v84, v102, v124
	v_mul_f32_e32 v80, v84, v80
	v_bfe_u32 v84, v80, 16, 1
	v_add3_u32 v80, v80, v84, s20
	v_or_b32_e32 v84, 0x1200, v142
	v_lshlrev_b32_e32 v136, 1, v84
	v_lshl_add_u64 v[84:85], v[106:107], 0, v[136:137]
	global_store_short_d16_hi v[84:85], v80, off
	v_mul_f32_e32 v80, v103, v124
	v_mul_f32_e32 v80, v80, v81
	v_bfe_u32 v81, v80, 16, 1
	v_add3_u32 v84, v80, v81, s20
	v_or_b32_e32 v80, 0x1280, v142
	v_lshlrev_b32_e32 v136, 1, v80
	v_lshl_add_u64 v[80:81], v[106:107], 0, v[136:137]
	global_store_short_d16_hi v[80:81], v84, off
	v_mul_f32_e32 v80, v104, v124
	v_mul_f32_e32 v80, v80, v82
	v_bfe_u32 v81, v80, 16, 1
	v_add3_u32 v82, v80, v81, s20
	v_or_b32_e32 v80, 0x1300, v142
	v_lshlrev_b32_e32 v136, 1, v80
	v_lshl_add_u64 v[80:81], v[106:107], 0, v[136:137]
	global_store_short_d16_hi v[80:81], v82, off
	v_mul_f32_e32 v80, v105, v124
	v_mul_f32_e32 v80, v80, v83
	v_bfe_u32 v81, v80, 16, 1
	v_lshlrev_b32_e32 v136, 1, v172
	v_add3_u32 v82, v80, v81, s20
	v_lshl_add_u64 v[80:81], v[106:107], 0, v[136:137]
	global_store_short_d16_hi v[80:81], v82, off

;     __device__ __forceinline__ void operator()(const f32x4 (&acc)[2][2][4][2], const pg8::Unit& u, int wr, int wc, int fr, int fq) const {
;     ...
;                 if (cs < 8 || cs == 12 || cs == 13 || cs == 16 || cs == 17) {
;                     const float* gg = cs < 8 ? g_q : (cs < 14 ? g_k + 64 : g_k + 128);
;                     const float rn = rsqrtf(head_ssq(v) * (1.f / 64.f) + EPS) * (cs < 8 ? QSCALE : 1.f);
;                     float y[16];
; #pragma unroll
;                     for (int i = 0; i < 16; ++i) y[i] = v[i] * rn * gg[32 * (i >> 3) + d0 + (i & 7)];
;                     float r1[8], r2[8];
; #pragma unroll
;                     for (int i = 0; i < 8; ++i) { int di = d0 + i; asm volatile("" : "+v"(di));
;                         const float frev = __builtin_amdgcn_exp2f(-(float)di * (13.287712379549449f / 32.f)) * 0.15915494309189535f;
;                         float xr = (float)s * frev; xr -= __builtin_rintf(xr);
;                         const float c = __builtin_amdgcn_cosf(xr), sn = __builtin_amdgcn_sinf(xr); r1[i] = y[i] * c - y[8 + i] * sn; r2[i] = y[8 + i] * c + y[i] * sn; }
.LBB0_256:
	global_load_dwordx4 v[80:83], v167, s[54:55]
	global_load_dwordx4 v[84:87], v167, s[54:55] offset:16
	global_load_dwordx4 v[100:103], v167, s[54:55] offset:128
	global_load_dwordx4 v[104:107], v167, s[54:55] offset:144
	v_mul_f32_e32 v89, v110, v110
	v_fmac_f32_e32 v89, v109, v109
	v_fmac_f32_e32 v89, v111, v111
	v_fmac_f32_e32 v89, v112, v112
	v_fmac_f32_e32 v89, v113, v113
	v_fmac_f32_e32 v89, v114, v114
	v_fmac_f32_e32 v89, v115, v115
	v_pk_mul_f32 v[98:99], v[92:93], v[92:93]
	v_fmac_f32_e32 v89, v116, v116
	v_add_f32_e32 v89, v98, v89
	v_pk_mul_f32 v[118:119], v[96:97], v[96:97]
	v_add_f32_e32 v89, v99, v89
	v_add_f32_e32 v89, v118, v89
	v_pk_mul_f32 v[122:123], v[94:95], v[94:95]
	v_and_b32_e32 v121, 64, v165
	v_add_f32_e32 v89, v119, v89
	v_xor_b32_e32 v117, 16, v165
	v_add_u32_e32 v121, 64, v121
	v_add_f32_e32 v89, v122, v89
	v_pk_mul_f32 v[124:125], v[90:91], v[90:91]
	v_cmp_lt_i32_e32 vcc, v117, v121
	v_add_f32_e32 v89, v123, v89
	v_add_f32_e32 v89, v124, v89
	v_cndmask_b32_e32 v117, v165, v117, vcc
	v_lshlrev_b32_e32 v117, 2, v117
	v_add_f32_e32 v89, v125, v89
	v_mov_b32_e32 v98, v89
	s_nop 1
	v_permlane16_swap_b32 v89, v98
	v_xor_b32_e32 v99, 32, v165
	v_cmp_lt_i32_e32 vcc, v99, v121
	v_cvt_f32_u32_e32 v117, v108
	s_mov_b64 s[54:55], -1
	v_cndmask_b32_e32 v99, v165, v99, vcc
	v_lshlrev_b32_e32 v99, 2, v99
	s_waitcnt lgkmcnt(0)
	v_add_f32_e32 v89, v89, v98
	v_mov_b32_e32 v98, v89
	s_nop 1
	v_permlane32_swap_b32 v89, v98
	v_mov_b32_e32 v99, v140
	s_waitcnt lgkmcnt(0)
	v_add_f32_e32 v89, v89, v98
	v_fmamk_f32 v89, v89, 0x3c800000, v161
	v_mul_f32_e32 v98, 0x4b800000, v89
	v_cmp_gt_f32_e32 vcc, s61, v89
	v_cvt_f32_i32_e32 v99, v99
	s_nop 0
	v_cndmask_b32_e32 v89, v89, v98, vcc
	v_rsq_f32_e32 v89, v89
	v_mul_f32_e32 v98, 0xbed49a78, v99
	v_exp_f32_e32 v99, v98
	v_mul_f32_e32 v98, 0x45800000, v89
	v_cndmask_b32_e32 v89, v89, v98, vcc
	v_mul_f32_e32 v89, s53, v89
	v_mul_f32_e32 v98, v109, v89
	v_mul_f32_e32 v109, v110, v89
	v_mul_f32_e32 v110, v111, v89
	v_mul_f32_e32 v111, v112, v89
	v_mul_f32_e32 v112, v113, v89
	v_mul_f32_e32 v113, v114, v89
	v_mul_f32_e32 v114, v115, v89
	v_mul_f32_e32 v115, v116, v89
	v_mul_f32_e32 v116, v92, v89
	v_mul_f32_e32 v118, v93, v89
	v_mul_f32_e32 v119, v96, v89
	v_mul_f32_e32 v121, v97, v89
	v_mul_f32_e32 v122, v94, v89
	v_mul_f32_e32 v123, v95, v89
	v_mul_f32_e32 v124, v90, v89
	s_and_b64 vcc, exec, s[6:7]
	s_waitcnt vmcnt(3)
	v_mul_f32_e32 v96, v80, v98
	v_mul_f32_e32 v80, v91, v89
	v_mul_f32_e32 v89, 0.15915494, v99
	v_mul_f32_e32 v91, v89, v117
	v_rndne_f32_e32 v91, v91
	v_fma_f32 v89, v89, v117, -v91
	v_mov_b32_e32 v91, v141
	s_waitcnt vmcnt(2)
	v_mul_f32_e32 v95, v85, v113
	v_cvt_f32_i32_e32 v91, v91
	s_waitcnt vmcnt(1)
	v_mul_f32_e32 v85, v100, v116
	v_sin_f32_e32 v100, v89
	v_cos_f32_e32 v89, v89
	v_mul_f32_e32 v91, 0xbed49a78, v91
	v_mul_f32_e32 v93, v87, v115
	v_mul_f32_e32 v87, v101, v118
	v_exp_f32_e32 v101, v91
	s_waitcnt vmcnt(0)
	v_mul_f32_e32 v99, v80, v107
	v_mul_f32_e32 v80, v85, v100
	v_fma_f32 v91, v96, v89, -v80
	v_mul_f32_e32 v80, v96, v100
	v_fmac_f32_e32 v80, v85, v89
	v_mul_f32_e32 v89, 0.15915494, v101
	v_mov_b32_e32 v101, v143
	v_mul_f32_e32 v97, v83, v111
	v_cvt_f32_i32_e32 v101, v101
	v_mul_f32_e32 v83, v119, v102
	v_mul_f32_e32 v90, v86, v114
	v_mul_f32_e32 v86, v121, v103
	v_mul_f32_e32 v101, 0xbed49a78, v101
	v_exp_f32_e32 v102, v101
	v_mul_f32_e32 v100, v89, v117
	v_rndne_f32_e32 v100, v100
	v_fma_f32 v89, v89, v117, -v100
	v_mul_f32_e32 v102, 0.15915494, v102
	v_mul_f32_e32 v103, v102, v117
	v_rndne_f32_e32 v103, v103
	v_fma_f32 v102, v102, v117, -v103
	v_mov_b32_e32 v103, v145
	v_sin_f32_e32 v100, v89
	v_cos_f32_e32 v89, v89
	v_cvt_f32_i32_e32 v103, v103
	v_mul_f32_e32 v98, v81, v109
	v_mul_f32_e32 v94, v82, v110
	v_mul_f32_e32 v82, v122, v104
	v_mul_f32_e32 v101, v87, v100
	v_mul_f32_e32 v100, v98, v100
	v_sin_f32_e32 v104, v102
	v_fma_f32 v101, v98, v89, -v101
	v_fmac_f32_e32 v100, v87, v89
	v_cos_f32_e32 v89, v102
	v_mul_f32_e32 v103, 0xbed49a78, v103
	v_mul_f32_e32 v92, v84, v112
	v_mul_f32_e32 v84, v123, v105
	v_exp_f32_e32 v105, v103
	v_mul_f32_e32 v102, v83, v104
	v_fma_f32 v103, v94, v89, -v102
	v_mul_f32_e32 v102, v94, v104
	v_fmac_f32_e32 v102, v83, v89
	v_mul_f32_e32 v89, 0.15915494, v105
	v_mov_b32_e32 v105, v147
	v_mul_f32_e32 v81, v124, v106
	v_cvt_f32_i32_e32 v105, v105
	v_mul_f32_e32 v104, v89, v117
	v_rndne_f32_e32 v104, v104
	v_fma_f32 v89, v89, v117, -v104
	v_mul_f32_e32 v105, 0xbed49a78, v105
	v_exp_f32_e32 v106, v105
	v_sin_f32_e32 v104, v89
	v_cos_f32_e32 v89, v89
	v_mov_b32_e32 v113, v157
	v_mul_f32_e32 v106, 0.15915494, v106
	v_mul_f32_e32 v107, v106, v117
	v_rndne_f32_e32 v107, v107
	v_fma_f32 v106, v106, v117, -v107
	v_mov_b32_e32 v107, v153
	v_mul_f32_e32 v105, v86, v104
	v_cvt_f32_i32_e32 v107, v107
	v_mul_f32_e32 v104, v97, v104
	v_sin_f32_e32 v109, v106
	v_fma_f32 v105, v97, v89, -v105
	v_fmac_f32_e32 v104, v86, v89
	v_cos_f32_e32 v89, v106
	v_mul_f32_e32 v107, 0xbed49a78, v107
	v_exp_f32_e32 v110, v107
	v_mul_f32_e32 v106, v82, v109
	v_fma_f32 v107, v92, v89, -v106
	v_mul_f32_e32 v106, v92, v109
	v_fmac_f32_e32 v106, v82, v89
	v_mul_f32_e32 v89, 0.15915494, v110
	v_mov_b32_e32 v110, v155
	v_mul_f32_e32 v109, v89, v117
	v_cvt_f32_i32_e32 v110, v110
	v_cvt_f32_i32_e32 v113, v113
	v_rndne_f32_e32 v109, v109
	v_fma_f32 v89, v89, v117, -v109
	v_mul_f32_e32 v110, 0xbed49a78, v110
	v_exp_f32_e32 v111, v110
	v_sin_f32_e32 v109, v89
	v_cos_f32_e32 v89, v89
	v_mul_f32_e32 v113, 0xbed49a78, v113
	v_mul_f32_e32 v111, 0.15915494, v111
	v_mul_f32_e32 v112, v111, v117
	v_rndne_f32_e32 v112, v112
	v_fma_f32 v111, v111, v117, -v112
	v_cos_f32_e32 v112, v111
	v_sin_f32_e32 v111, v111
	v_exp_f32_e32 v114, v113
	v_mul_f32_e32 v110, v84, v109
	v_mul_f32_e32 v109, v95, v109
	v_fma_f32 v110, v95, v89, -v110
	v_fmac_f32_e32 v109, v84, v89
	v_mul_f32_e32 v89, v81, v111
	v_fma_f32 v113, v90, v112, -v89
	v_mul_f32_e32 v89, 0.15915494, v114
	v_mul_f32_e32 v114, v89, v117
	v_rndne_f32_e32 v114, v114
	v_fma_f32 v89, v89, v117, -v114
	v_sin_f32_e32 v115, v89
	v_cos_f32_e32 v89, v89
	v_mul_f32_e32 v111, v90, v111
	v_fmac_f32_e32 v111, v81, v112
	v_mul_f32_e32 v112, v99, v115
	v_fma_f32 v114, v93, v89, -v112
	v_mul_f32_e32 v112, v93, v115
	v_fmac_f32_e32 v112, v99, v89
	s_cbranch_vccnz .LBB0_258
;     __device__ __forceinline__ void operator()(const f32x4 (&acc)[2][2][4][2], const pg8::Unit& u, int wr, int wc, int fr, int fq) const {
;     ...
;                     } else {
;                         bf16_t* p = (cs < 14 ? ksl : kwn) + ((size_t)(b * 2 + (cs & 1)) * 2048 + s) * 64 + d0; store8(p, r1); store8(p + 32, r2);
	s_and_b64 s[54:55], s[10:11], exec
	s_cselect_b32 s53, s77, s76
	s_cselect_b32 s56, s74, s75
	s_lshl_b32 s54, s52, 1
	s_or_b32 s54, s54, s97
	s_ashr_i32 s55, s54, 31
	s_lshl_b64 s[54:55], s[54:55], 18
	s_add_u32 s54, s56, s54
	s_addc_u32 s55, s53, s55
	v_lshlrev_b32_e32 v136, 7, v108
	v_lshl_add_u64 v[116:117], s[54:55], 0, v[136:137]
	v_lshlrev_b32_e32 v136, 1, v140
	v_lshl_add_u64 v[122:123], v[116:117], 0, v[136:137]
	v_cvt_pk_bf16_f32 v116, v91, v101
	v_cvt_pk_bf16_f32 v117, v103, v105
	v_cvt_pk_bf16_f32 v118, v107, v110
	v_cvt_pk_bf16_f32 v119, v113, v114
	s_mov_b64 s[54:55], 0
	global_store_dwordx4 v[122:123], v[116:119], off
	s_nop 1
	v_cvt_pk_bf16_f32 v116, v80, v100
	v_cvt_pk_bf16_f32 v117, v102, v104
	v_cvt_pk_bf16_f32 v118, v106, v109
	v_cvt_pk_bf16_f32 v119, v111, v112
	global_store_dwordx4 v[122:123], v[116:119], off offset:64

; __device__ __forceinline__ float gelu_tanh(float x) {
;     const float u = 0.7978845608028654f * (x + 0.044715f * x * x * x);
;     return x / (1.f + __expf(-2.f * u));
; }
; __device__ __forceinline__ float head_ssq(const float (&v)[16]) {
;     float s = 0.f;
; #pragma unroll
;     for (int i = 0; i < 16; ++i) s += v[i] * v[i];
;     s += __shfl_xor(s, 16); s += __shfl_xor(s, 32);
;     return s;
.LBB0_269:
	s_andn2_b64 vcc, exec, s[72:73]
	s_mov_b64 s[54:55], -1
	s_cbranch_vccnz .LBB0_285
	s_andn2_b64 vcc, exec, s[70:71]
	s_cbranch_vccnz .LBB0_282
	s_andn2_b64 vcc, exec, s[42:43]
	s_cbranch_vccnz .LBB0_279
	s_andn2_b64 vcc, exec, s[40:41]
	s_cbranch_vccnz .LBB0_274
	s_ashr_i32 s53, s52, 31
	s_lshl_b64 s[56:57], s[52:53], 21
	v_readlane_b32 s36, v254, 33
	s_mov_b64 s[58:59], s[42:43]
	v_mul_f32_e32 v64, v93, v93
	v_mul_f32_e32 v64, 0xbdd2d3e8, v64
	v_add_f32_e32 v64, 0xc0135761, v64
	v_mul_f32_e32 v64, v93, v64
	v_exp_f32_e32 v64, v64
	s_nop 0
	v_add_f32_e32 v64, 1.0, v64
	v_rcp_f32_e32 v65, v64
	s_nop 0
	v_mul_f32_e32 v64, v93, v65
	s_nop 0
	s_nop 0
	v_mul_f32_e32 v65, v94, v94
	v_mul_f32_e32 v65, 0xbdd2d3e8, v65
	v_add_f32_e32 v65, 0xc0135761, v65
	v_mul_f32_e32 v65, v94, v65
	v_exp_f32_e32 v65, v65
	s_nop 0
	v_add_f32_e32 v65, 1.0, v65
	v_rcp_f32_e32 v66, v65
	s_nop 0
	v_mul_f32_e32 v81, v94, v66
	s_nop 0
	s_nop 0
	v_mul_f32_e32 v65, v95, v95
	v_mul_f32_e32 v65, 0xbdd2d3e8, v65
	v_add_f32_e32 v65, 0xc0135761, v65
	v_mul_f32_e32 v65, v95, v65
	v_exp_f32_e32 v65, v65
	s_nop 0
	v_add_f32_e32 v65, 1.0, v65
	v_rcp_f32_e32 v66, v65
	s_nop 0
	v_mul_f32_e32 v101, v95, v66
	s_nop 0
	s_nop 0
	v_mul_f32_e32 v65, v96, v96
	v_mul_f32_e32 v65, 0xbdd2d3e8, v65
	v_add_f32_e32 v65, 0xc0135761, v65
	v_mul_f32_e32 v65, v96, v65
	v_exp_f32_e32 v65, v65
	s_nop 0
	v_add_f32_e32 v65, 1.0, v65
	v_rcp_f32_e32 v66, v65
	s_nop 0
	v_mul_f32_e32 v102, v96, v66
	s_nop 0
	s_nop 0
	v_mul_f32_e32 v65, v97, v97
	v_mul_f32_e32 v65, 0xbdd2d3e8, v65
	v_add_f32_e32 v65, 0xc0135761, v65
	v_mul_f32_e32 v65, v97, v65
	v_exp_f32_e32 v65, v65
	s_nop 0
	v_add_f32_e32 v65, 1.0, v65
	v_rcp_f32_e32 v66, v65
	s_nop 0
	v_mul_f32_e32 v103, v97, v66
	s_nop 0
	s_nop 0
	v_mul_f32_e32 v65, v98, v98
	v_mul_f32_e32 v65, 0xbdd2d3e8, v65
	v_add_f32_e32 v65, 0xc0135761, v65
	v_mul_f32_e32 v65, v98, v65
	v_exp_f32_e32 v65, v65
	s_nop 0
	v_add_f32_e32 v65, 1.0, v65
	v_rcp_f32_e32 v66, v65
	s_nop 0
	v_mul_f32_e32 v104, v98, v66
	s_nop 0
	s_nop 0
	v_mul_f32_e32 v65, v99, v99
	v_mul_f32_e32 v65, 0xbdd2d3e8, v65
	v_add_f32_e32 v65, 0xc0135761, v65
	v_mul_f32_e32 v65, v99, v65
	v_exp_f32_e32 v65, v65
	s_nop 0
	v_add_f32_e32 v65, 1.0, v65
	v_rcp_f32_e32 v66, v65
	s_nop 0
	v_mul_f32_e32 v105, v99, v66
	s_nop 0
	s_nop 0
	v_mul_f32_e32 v65, v100, v100
	v_mul_f32_e32 v65, 0xbdd2d3e8, v65
	v_add_f32_e32 v65, 0xc0135761, v65
	v_mul_f32_e32 v65, v100, v65
	v_exp_f32_e32 v65, v65
	s_nop 0
	v_add_f32_e32 v65, 1.0, v65
	v_rcp_f32_e32 v66, v65
	s_nop 0
	v_mul_f32_e32 v106, v100, v66
	v_mul_f32_e32 v67, v85, v85
	v_mul_f32_e32 v67, 0xbdd2d3e8, v67
	v_add_f32_e32 v67, 0xc0135761, v67
	v_mul_f32_e32 v67, v85, v67
	v_exp_f32_e32 v67, v67
	s_nop 0
	v_add_f32_e32 v67, 1.0, v67
	v_rcp_f32_e32 v72, v67
	s_nop 0
	v_mul_f32_e32 v73, v85, v72
	v_mul_f32_e32 v65, v81, v81
	v_fmac_f32_e32 v65, v64, v64
	v_fmac_f32_e32 v65, v101, v101
	v_fmac_f32_e32 v65, v102, v102
	v_fmac_f32_e32 v65, v103, v103
	v_fmac_f32_e32 v65, v104, v104
	v_fmac_f32_e32 v65, v105, v105
	v_mul_f32_e32 v66, v84, v84
	v_mul_f32_e32 v66, 0xbdd2d3e8, v66
	v_add_f32_e32 v66, 0xc0135761, v66
	v_mul_f32_e32 v66, v84, v66
	v_exp_f32_e32 v66, v66
	s_nop 0
	v_add_f32_e32 v66, 1.0, v66
	v_rcp_f32_e32 v67, v66
	s_nop 0
	v_mul_f32_e32 v72, v84, v67
	v_fmac_f32_e32 v65, v106, v106
	v_pk_mul_f32 v[66:67], v[72:73], v[72:73]
	s_nop 0
	v_add_f32_e32 v65, v66, v65
	v_add_f32_e32 v65, v67, v65
	s_nop 0
	s_nop 0
	v_mul_f32_e32 v67, v89, v89
	v_mul_f32_e32 v67, 0xbdd2d3e8, v67
	v_add_f32_e32 v67, 0xc0135761, v67
	v_mul_f32_e32 v67, v89, v67
	v_exp_f32_e32 v67, v67
	s_nop 0
	v_add_f32_e32 v67, 1.0, v67
	v_rcp_f32_e32 v68, v67
	s_nop 0
	v_mul_f32_e32 v75, v89, v68
	s_nop 0
	v_mul_f32_e32 v66, v88, v88
	v_mul_f32_e32 v66, 0xbdd2d3e8, v66
	v_add_f32_e32 v66, 0xc0135761, v66
	v_mul_f32_e32 v66, v88, v66
	v_exp_f32_e32 v66, v66
	s_nop 0
	v_add_f32_e32 v66, 1.0, v66
	v_rcp_f32_e32 v67, v66
	s_nop 0
	v_mul_f32_e32 v74, v88, v67
	v_pk_mul_f32 v[66:67], v[74:75], v[74:75]
	s_nop 0
	v_add_f32_e32 v65, v66, v65
	v_add_f32_e32 v65, v67, v65
	s_nop 0
	s_nop 0
	v_mul_f32_e32 v67, v87, v87
	v_mul_f32_e32 v67, 0xbdd2d3e8, v67
	v_add_f32_e32 v67, 0xc0135761, v67
	v_mul_f32_e32 v67, v87, v67
	v_exp_f32_e32 v67, v67
	s_nop 0
	v_add_f32_e32 v67, 1.0, v67
	v_rcp_f32_e32 v68, v67
	s_nop 0
	v_mul_f32_e32 v77, v87, v68
	s_nop 0
	v_mul_f32_e32 v66, v86, v86
	v_mul_f32_e32 v66, 0xbdd2d3e8, v66
	v_add_f32_e32 v66, 0xc0135761, v66
	v_mul_f32_e32 v66, v86, v66
	v_exp_f32_e32 v66, v66
	s_nop 0
	v_add_f32_e32 v66, 1.0, v66
	v_rcp_f32_e32 v67, v66
	s_nop 0
	v_mul_f32_e32 v76, v86, v67
	v_pk_mul_f32 v[66:67], v[76:77], v[76:77]
	s_nop 0
	v_add_f32_e32 v65, v66, v65
	v_add_f32_e32 v65, v67, v65
	s_nop 0
	s_nop 0
	v_mul_f32_e32 v67, v83, v83
	v_mul_f32_e32 v67, 0xbdd2d3e8, v67
	v_add_f32_e32 v67, 0xc0135761, v67
	v_mul_f32_e32 v67, v83, v67
	v_exp_f32_e32 v67, v67
	s_nop 0
	v_add_f32_e32 v67, 1.0, v67
	v_rcp_f32_e32 v68, v67
	s_nop 0
	v_mul_f32_e32 v79, v83, v68
	s_lshr_b32 s54, s89, 4
	s_and_b32 s54, s54, 0x78
	s_add_i32 s54, s54, s29
	v_mul_f32_e32 v66, v82, v82
	v_mul_f32_e32 v66, 0xbdd2d3e8, v66
	v_add_f32_e32 v66, 0xc0135761, v66
	v_mul_f32_e32 v66, v82, v66
	v_exp_f32_e32 v66, v66
	s_nop 0
	v_add_f32_e32 v66, 1.0, v66
	v_rcp_f32_e32 v67, v66
	s_nop 0
	v_mul_f32_e32 v78, v82, v67
	v_pk_mul_f32 v[66:67], v[78:79], v[78:79]
	s_mov_b32 s55, s9
	v_add_f32_e32 v65, v66, v65
	v_add_f32_e32 v65, v67, v65
	v_and_b32_e32 v67, 64, v165
	v_xor_b32_e32 v66, 16, v165
	v_add_u32_e32 v67, 64, v67
	v_cmp_lt_i32_e32 vcc, v66, v67
	s_lshl_b64 s[54:55], s[54:55], 14
	s_add_u32 s53, s36, s56
	v_cndmask_b32_e32 v66, v165, v66, vcc
	v_lshlrev_b32_e32 v66, 2, v66
	v_mov_b32_e32 v66, v65
	s_nop 1
	v_permlane16_swap_b32 v65, v66
	v_readlane_b32 s36, v254, 35
	s_addc_u32 s56, s36, s57
	s_add_u32 s54, s53, s54
	s_addc_u32 s55, s56, s55
	s_waitcnt lgkmcnt(0)
; __device__ __forceinline__ unsigned f2bf(float f) { unsigned u = __float_as_uint(f); return (u + 0x7fffu + ((u >> 16) & 1u)) >> 16; }
;     __device__ __forceinline__ void operator()(const f32x4 (&acc)[2][2][4][2], const pg8::Unit& u, int wr, int wc, int fr, int fq) const {
;     ...
;                     const float rn = rsqrtf(head_ssq(y) * (1.f / 64.f) + EPS);
;                     bf16_t* p = zvT + (((size_t)b * 16 + (s >> 7)) * 8 + g) * 8192 + (s & 127);
; #pragma unroll
;                     for (int i = 0; i < 16; ++i) { const int d = 32 * (i >> 3) + d0 + (i & 7); p[d * 128] = (bf16_t)f2bf(y[i] * rn * g_sgu[g * 64 + d]); }
	v_add_f32_e32 v65, v65, v66
	v_xor_b32_e32 v66, 32, v165
	v_cmp_lt_i32_e32 vcc, v66, v67
	s_mov_b64 s[56:57], s[40:41]
	s_nop 0
	v_cndmask_b32_e32 v66, v165, v66, vcc
	v_lshlrev_b32_e32 v66, 2, v66
	v_mov_b32_e32 v66, v65
	s_nop 1
	v_permlane32_swap_b32 v65, v66
	s_waitcnt lgkmcnt(0)
	v_add_f32_e32 v65, v65, v66
	v_fmamk_f32 v65, v65, 0x3c800000, v161
	v_cmp_gt_f32_e32 vcc, s61, v65
	v_mul_f32_e32 v66, 0x4b800000, v65
	s_nop 0
	v_cndmask_b32_e32 v65, v65, v66, vcc
	v_rsq_f32_e32 v65, v65
	s_nop 0
	v_mul_f32_e32 v66, 0x45800000, v65
	v_cndmask_b32_e32 v107, v65, v66, vcc
	v_and_b32_e32 v65, 0x7f, v80
	v_lshlrev_b32_e32 v136, 1, v65
	v_lshl_add_u64 v[90:91], s[54:55], 0, v[136:137]
	s_mov_b64 s[54:55], s[38:39]
	v_readlane_b32 s36, v254, 8
	v_or_b32_e32 v136, s27, v140
	v_readlane_b32 s37, v254, 9
	v_mul_f32_e32 v108, v64, v107
	v_mul_f32_e32 v72, v72, v107
	v_lshl_add_u64 v[68:69], v[136:137], 2, s[36:37]
	global_load_dwordx4 v[64:67], v[68:69], off offset:16
	s_nop 0
	global_load_dwordx4 v[68:71], v[68:69], off
	v_lshlrev_b32_e32 v136, 1, v142
	v_readlane_b32 s50, v254, 22
	v_readlane_b32 s51, v254, 23
	v_readlane_b32 s38, v254, 10
	v_readlane_b32 s39, v254, 11
	v_readlane_b32 s40, v254, 12
	v_readlane_b32 s41, v254, 13
	v_readlane_b32 s42, v254, 14
	v_readlane_b32 s43, v254, 15
	v_readlane_b32 s49, v254, 21
	v_readlane_b32 s50, v254, 39
	s_mov_b64 s[38:39], s[54:55]
	s_mov_b64 s[42:43], s[58:59]
	s_mov_b64 s[40:41], s[56:57]
	v_readlane_b32 s49, v254, 41
	v_readlane_b32 s51, v254, 40
	s_mov_b64 s[54:55], 0
	v_readlane_b32 s44, v254, 16
	v_readlane_b32 s45, v254, 17
	v_readlane_b32 s46, v254, 18
	v_readlane_b32 s47, v254, 19
	v_readlane_b32 s48, v254, 20
	s_waitcnt vmcnt(0)
	v_mul_f32_e32 v68, v68, v108
	v_bfe_u32 v108, v68, 16, 1
	v_add3_u32 v68, v68, v108, s20
	v_lshl_add_u64 v[108:109], v[90:91], 0, v[136:137]
	global_store_short_d16_hi v[108:109], v68, off
	v_mul_f32_e32 v68, v81, v107
	v_add_u32_e32 v136, s27, v140
	v_mul_f32_e32 v68, v69, v68
	v_lshl_add_u64 v[108:109], v[136:137], 2, s[36:37]
	v_bfe_u32 v69, v68, 16, 1
	v_lshlrev_b32_e32 v136, 1, v144
	v_add3_u32 v81, v68, v69, s20
	v_lshl_add_u64 v[68:69], v[90:91], 0, v[136:137]
	global_store_short_d16_hi v[68:69], v81, off
	v_mul_f32_e32 v68, v101, v107
	v_mul_f32_e32 v68, v70, v68
	v_bfe_u32 v69, v68, 16, 1
	v_lshlrev_b32_e32 v136, 1, v146
	v_add3_u32 v70, v68, v69, s20
	v_lshl_add_u64 v[68:69], v[90:91], 0, v[136:137]
	global_store_short_d16_hi v[68:69], v70, off
	v_mul_f32_e32 v68, v102, v107
	v_mul_f32_e32 v68, v71, v68
	v_bfe_u32 v69, v68, 16, 1
	v_lshlrev_b32_e32 v136, 1, v148
	v_add3_u32 v70, v68, v69, s20
	v_lshl_add_u64 v[68:69], v[90:91], 0, v[136:137]
	global_store_short_d16_hi v[68:69], v70, off
	v_mul_f32_e32 v68, v103, v107
	v_mul_f32_e32 v64, v64, v68
	v_bfe_u32 v68, v64, 16, 1
	v_lshlrev_b32_e32 v136, 1, v150
	v_add3_u32 v64, v64, v68, s20
	v_lshl_add_u64 v[68:69], v[90:91], 0, v[136:137]
	global_store_short_d16_hi v[68:69], v64, off
	v_mul_f32_e32 v64, v104, v107
	v_mul_f32_e32 v64, v64, v65
	v_bfe_u32 v65, v64, 16, 1
	v_lshlrev_b32_e32 v136, 1, v152
	v_add3_u32 v68, v64, v65, s20
	v_lshl_add_u64 v[64:65], v[90:91], 0, v[136:137]
	global_store_short_d16_hi v[64:65], v68, off
	v_mul_f32_e32 v64, v105, v107
	v_mul_f32_e32 v64, v64, v66
	v_bfe_u32 v65, v64, 16, 1
	v_lshlrev_b32_e32 v136, 1, v154
	v_add3_u32 v66, v64, v65, s20
	v_lshl_add_u64 v[64:65], v[90:91], 0, v[136:137]
	global_store_short_d16_hi v[64:65], v66, off
	v_mul_f32_e32 v64, v106, v107
	v_mul_f32_e32 v64, v64, v67
	v_bfe_u32 v65, v64, 16, 1
	v_lshlrev_b32_e32 v136, 1, v156
	v_add3_u32 v66, v64, v65, s20
	v_lshl_add_u64 v[64:65], v[90:91], 0, v[136:137]
	global_store_short_d16_hi v[64:65], v66, off
	global_load_dwordx4 v[64:67], v[108:109], off offset:144
	s_nop 0
	global_load_dwordx4 v[68:71], v[108:109], off offset:128
	v_lshlrev_b32_e32 v136, 1, v158
	v_lshl_add_u64 v[102:103], v[90:91], 0, v[136:137]
	v_lshlrev_b32_e32 v136, 1, v160
	s_waitcnt vmcnt(0)
	v_mul_f32_e32 v68, v72, v68
	v_bfe_u32 v72, v68, 16, 1
	v_add3_u32 v68, v68, v72, s20
	global_store_short_d16_hi v[102:103], v68, off
	v_mul_f32_e32 v68, v73, v107
	v_mul_f32_e32 v68, v68, v69
	v_bfe_u32 v69, v68, 16, 1
	v_add3_u32 v72, v68, v69, s20
	v_lshl_add_u64 v[68:69], v[90:91], 0, v[136:137]
	global_store_short_d16_hi v[68:69], v72, off
	v_mul_f32_e32 v68, v74, v107
	v_mul_f32_e32 v68, v68, v70
	v_bfe_u32 v69, v68, 16, 1
	v_lshlrev_b32_e32 v136, 1, v162
	v_add3_u32 v70, v68, v69, s20
	v_lshl_add_u64 v[68:69], v[90:91], 0, v[136:137]
	global_store_short_d16_hi v[68:69], v70, off
	v_mul_f32_e32 v68, v75, v107
	v_mul_f32_e32 v68, v68, v71
	v_bfe_u32 v69, v68, 16, 1
	v_lshlrev_b32_e32 v136, 1, v164
	v_add3_u32 v70, v68, v69, s20
	v_lshl_add_u64 v[68:69], v[90:91], 0, v[136:137]
	global_store_short_d16_hi v[68:69], v70, off
	v_mul_f32_e32 v68, v76, v107
	v_mul_f32_e32 v64, v68, v64
	v_bfe_u32 v68, v64, 16, 1
	v_add3_u32 v64, v64, v68, s20
	v_or_b32_e32 v68, 0x1200, v142
	v_lshlrev_b32_e32 v136, 1, v68
	v_lshl_add_u64 v[68:69], v[90:91], 0, v[136:137]
	global_store_short_d16_hi v[68:69], v64, off
	v_mul_f32_e32 v64, v77, v107
	v_mul_f32_e32 v64, v64, v65
	v_bfe_u32 v65, v64, 16, 1
	v_add3_u32 v68, v64, v65, s20
	v_or_b32_e32 v64, 0x1280, v142
	v_lshlrev_b32_e32 v136, 1, v64
	v_lshl_add_u64 v[64:65], v[90:91], 0, v[136:137]
	global_store_short_d16_hi v[64:65], v68, off
	v_mul_f32_e32 v64, v78, v107
	v_mul_f32_e32 v64, v64, v66
	v_bfe_u32 v65, v64, 16, 1
	v_add3_u32 v66, v64, v65, s20
	v_or_b32_e32 v64, 0x1300, v142
	v_lshlrev_b32_e32 v136, 1, v64
	v_lshl_add_u64 v[64:65], v[90:91], 0, v[136:137]
	global_store_short_d16_hi v[64:65], v66, off
	v_mul_f32_e32 v64, v79, v107
	v_mul_f32_e32 v64, v64, v67
	v_bfe_u32 v65, v64, 16, 1
	v_lshlrev_b32_e32 v136, 1, v172
	v_add3_u32 v66, v64, v65, s20
	v_lshl_add_u64 v[64:65], v[90:91], 0, v[136:137]
	global_store_short_d16_hi v[64:65], v66, off

;     __device__ __forceinline__ void operator()(const f32x4 (&acc)[2][2][4][2], const pg8::Unit& u, int wr, int wc, int fr, int fq) const {
;     ...
;                 if (cs < 8 || cs == 12 || cs == 13 || cs == 16 || cs == 17) {
;                     const float* gg = cs < 8 ? g_q : (cs < 14 ? g_k + 64 : g_k + 128);
;                     const float rn = rsqrtf(head_ssq(v) * (1.f / 64.f) + EPS) * (cs < 8 ? QSCALE : 1.f);
;                     float y[16];
; #pragma unroll
;                     for (int i = 0; i < 16; ++i) y[i] = v[i] * rn * gg[32 * (i >> 3) + d0 + (i & 7)];
;                     float r1[8], r2[8];
; #pragma unroll
;                     for (int i = 0; i < 8; ++i) { int di = d0 + i; asm volatile("" : "+v"(di));
;                         const float frev = __builtin_amdgcn_exp2f(-(float)di * (13.287712379549449f / 32.f)) * 0.15915494309189535f;
;                         float xr = (float)s * frev; xr -= __builtin_rintf(xr);
;                         const float c = __builtin_amdgcn_cosf(xr), sn = __builtin_amdgcn_sinf(xr); r1[i] = y[i] * c - y[8 + i] * sn; r2[i] = y[8 + i] * c + y[i] * sn; }
;                     if (cs < 8) {
;                         bf16_t* p = qn + (size_t)row * 512 + cs * 64 + d0; store8(p, y); store8(p + 32, y + 8);
;                         bf16_t* p2 = qr + (size_t)row * 512 + cs * 64 + d0; store8(p2, r1); store8(p2 + 32, r2);
;                     } else {
;                         bf16_t* p = (cs < 14 ? ksl : kwn) + ((size_t)(b * 2 + (cs & 1)) * 2048 + s) * 64 + d0; store8(p, r1); store8(p + 32, r2);
.LBB0_289:
	global_load_dwordx4 v[72:75], v167, s[54:55]
	global_load_dwordx4 v[68:71], v167, s[54:55] offset:16
	global_load_dwordx4 v[76:79], v167, s[54:55] offset:128
	global_load_dwordx4 v[64:67], v167, s[54:55] offset:144
	v_mul_f32_e32 v81, v94, v94
	v_fmac_f32_e32 v81, v93, v93
	v_fmac_f32_e32 v81, v95, v95
	v_fmac_f32_e32 v81, v96, v96
	v_fmac_f32_e32 v81, v97, v97
	v_fmac_f32_e32 v81, v98, v98
	v_fmac_f32_e32 v81, v99, v99
	v_pk_mul_f32 v[90:91], v[84:85], v[84:85]
	v_fmac_f32_e32 v81, v100, v100
	v_add_f32_e32 v81, v90, v81
	v_pk_mul_f32 v[102:103], v[88:89], v[88:89]
	v_add_f32_e32 v81, v91, v81
	v_add_f32_e32 v81, v102, v81
	v_pk_mul_f32 v[104:105], v[86:87], v[86:87]
	v_and_b32_e32 v108, 64, v165
	v_add_f32_e32 v81, v103, v81
	v_xor_b32_e32 v101, 16, v165
	v_add_u32_e32 v108, 64, v108
	v_add_f32_e32 v81, v104, v81
	v_pk_mul_f32 v[106:107], v[82:83], v[82:83]
	v_cmp_lt_i32_e32 vcc, v101, v108
	v_add_f32_e32 v81, v105, v81
	v_add_f32_e32 v81, v106, v81
	v_cndmask_b32_e32 v101, v165, v101, vcc
	v_lshlrev_b32_e32 v101, 2, v101
	v_add_f32_e32 v81, v107, v81
	v_mov_b32_e32 v90, v81
	s_nop 1
	v_permlane16_swap_b32 v81, v90
	v_xor_b32_e32 v91, 32, v165
	v_cmp_lt_i32_e32 vcc, v91, v108
	s_mov_b64 s[54:55], -1
	s_waitcnt lgkmcnt(0)
	v_add_f32_e32 v81, v81, v90
	v_cndmask_b32_e32 v91, v165, v91, vcc
	v_lshlrev_b32_e32 v91, 2, v91
	v_mov_b32_e32 v90, v81
	s_nop 1
	v_permlane32_swap_b32 v81, v90
	v_mov_b32_e32 v91, v140
	s_waitcnt lgkmcnt(0)
	v_add_f32_e32 v81, v81, v90
	v_fmamk_f32 v81, v81, 0x3c800000, v161
	v_mul_f32_e32 v90, 0x4b800000, v81
	v_cmp_gt_f32_e32 vcc, s61, v81
	v_cvt_f32_i32_e32 v91, v91
	v_mul_f32_e32 v91, 0xbed49a78, v91
	v_cndmask_b32_e32 v81, v81, v90, vcc
	v_rsq_f32_e32 v90, v81
	v_exp_f32_e32 v91, v91
	v_cvt_f32_u32_e32 v81, v92
	v_mul_f32_e32 v101, 0x45800000, v90
	v_cndmask_b32_e32 v90, v90, v101, vcc
	v_mul_f32_e32 v90, s53, v90
	v_mul_f32_e32 v94, v94, v90
	v_mul_f32_e32 v99, v99, v90
	v_mul_f32_e32 v101, v84, v90
	v_mul_f32_e32 v93, v93, v90
	v_mul_f32_e32 v98, v98, v90
	v_mul_f32_e32 v102, v85, v90
	v_mul_f32_e32 v88, v88, v90
	v_mul_f32_e32 v104, v87, v90
	v_mul_f32_e32 v96, v96, v90
	v_mul_f32_e32 v100, v100, v90
	v_mul_f32_e32 v89, v89, v90
	v_mul_f32_e32 v103, v86, v90
	v_mul_f32_e32 v95, v95, v90
	v_mul_f32_e32 v97, v97, v90
	v_mul_f32_e32 v105, v82, v90
	s_and_b64 vcc, exec, s[6:7]
	s_waitcnt vmcnt(3)
	v_mul_f32_e32 v87, v73, v94
	s_waitcnt vmcnt(2)
	v_mul_f32_e32 v73, v70, v99
	s_waitcnt vmcnt(1)
	v_mul_f32_e32 v70, v76, v101
	v_mul_f32_e32 v76, 0.15915494, v91
	v_mul_f32_e32 v85, v72, v93
	v_mul_f32_e32 v84, v69, v98
	v_mul_f32_e32 v72, v77, v102
	v_mul_f32_e32 v69, v88, v78
	v_mul_f32_e32 v77, v76, v81
	v_mov_b32_e32 v78, v141
	v_rndne_f32_e32 v77, v77
	v_fma_f32 v76, v76, v81, -v77
	v_cvt_f32_i32_e32 v78, v78
	v_sin_f32_e32 v77, v76
	v_mul_f32_e32 v86, v75, v96
	v_mul_f32_e32 v75, v71, v100
	v_mul_f32_e32 v71, v89, v79
	v_cos_f32_e32 v79, v76
	v_mul_f32_e32 v82, v74, v95
	v_mul_f32_e32 v74, v68, v97
	s_waitcnt vmcnt(0)
	v_mul_f32_e32 v68, v103, v64
	v_mul_f32_e32 v64, v105, v66
	v_mul_f32_e32 v66, v83, v90
	v_mul_f32_e32 v76, 0xbed49a78, v78
	v_mul_f32_e32 v67, v66, v67
	v_mul_f32_e32 v66, v70, v77
	v_exp_f32_e32 v78, v76
	v_fma_f32 v76, v85, v79, -v66
	v_mul_f32_e32 v66, v85, v77
	v_fmac_f32_e32 v66, v70, v79
	v_mov_b32_e32 v79, v143
	v_mul_f32_e32 v77, 0.15915494, v78
	v_cvt_f32_i32_e32 v79, v79
	v_mul_f32_e32 v78, v77, v81
	v_rndne_f32_e32 v78, v78
	v_fma_f32 v77, v77, v81, -v78
	v_sin_f32_e32 v83, v77
	v_cos_f32_e32 v88, v77
	v_mul_f32_e32 v77, 0xbed49a78, v79
	v_exp_f32_e32 v79, v77
	v_mul_f32_e32 v77, v72, v83
	v_fma_f32 v78, v87, v88, -v77
	v_mul_f32_e32 v77, v87, v83
	v_mul_f32_e32 v79, 0.15915494, v79
	v_mul_f32_e32 v83, v79, v81
	v_rndne_f32_e32 v83, v83
	v_fma_f32 v79, v79, v81, -v83
	v_mov_b32_e32 v83, v145
	v_sin_f32_e32 v89, v79
	v_cvt_f32_i32_e32 v83, v83
	v_fmac_f32_e32 v77, v72, v88
	v_cos_f32_e32 v88, v79
	v_mul_f32_e32 v79, v69, v89
	v_mul_f32_e32 v83, 0xbed49a78, v83
	v_exp_f32_e32 v90, v83
	v_fma_f32 v83, v82, v88, -v79
	v_mul_f32_e32 v79, v82, v89
	v_fmac_f32_e32 v79, v69, v88
	v_mul_f32_e32 v88, 0.15915494, v90
	v_mov_b32_e32 v90, v147
	v_mul_f32_e32 v89, v88, v81
	v_cvt_f32_i32_e32 v90, v90
	v_rndne_f32_e32 v89, v89
	v_fma_f32 v88, v88, v81, -v89
	v_sin_f32_e32 v91, v88
	v_cos_f32_e32 v93, v88
	v_mul_f32_e32 v88, 0xbed49a78, v90
	v_exp_f32_e32 v90, v88
	v_mul_f32_e32 v88, v71, v91
	v_fma_f32 v89, v86, v93, -v88
	v_mul_f32_e32 v88, v86, v91
	v_mul_f32_e32 v90, 0.15915494, v90
	v_mul_f32_e32 v91, v90, v81
	v_rndne_f32_e32 v91, v91
	v_fma_f32 v90, v90, v81, -v91
	v_mov_b32_e32 v91, v153
	v_sin_f32_e32 v94, v90
	v_cvt_f32_i32_e32 v91, v91
	v_fmac_f32_e32 v88, v71, v93
	v_cos_f32_e32 v93, v90
	v_mul_f32_e32 v90, v68, v94
	v_mul_f32_e32 v91, 0xbed49a78, v91
	v_exp_f32_e32 v95, v91
	v_fma_f32 v91, v74, v93, -v90
	v_mul_f32_e32 v90, v74, v94
	v_fmac_f32_e32 v90, v68, v93
	v_mul_f32_e32 v93, 0.15915494, v95
	v_mov_b32_e32 v95, v155
	v_mul_f32_e32 v94, v93, v81
	v_cvt_f32_i32_e32 v95, v95
	v_rndne_f32_e32 v94, v94
	v_fma_f32 v93, v93, v81, -v94
	v_sin_f32_e32 v96, v93
	v_cos_f32_e32 v97, v93
	v_mul_f32_e32 v93, 0xbed49a78, v95
	v_exp_f32_e32 v95, v93
	v_mov_b32_e32 v98, v157
	v_mul_f32_e32 v65, v104, v65
	v_mul_f32_e32 v93, v65, v96
	v_mul_f32_e32 v95, 0.15915494, v95
	v_cvt_f32_i32_e32 v98, v98
	v_fma_f32 v94, v84, v97, -v93
	v_mul_f32_e32 v93, v84, v96
	v_mul_f32_e32 v96, v95, v81
	v_rndne_f32_e32 v96, v96
	v_fma_f32 v95, v95, v81, -v96
	v_cos_f32_e32 v99, v95
	v_sin_f32_e32 v96, v95
	v_mul_f32_e32 v95, 0xbed49a78, v98
	v_exp_f32_e32 v98, v95
	v_fmac_f32_e32 v93, v65, v97
	v_mul_f32_e32 v95, v64, v96
	v_mul_f32_e32 v96, v73, v96
	v_mul_f32_e32 v97, 0.15915494, v98
	v_mul_f32_e32 v98, v97, v81
	v_rndne_f32_e32 v98, v98
	v_fma_f32 v81, v97, v81, -v98
	v_sin_f32_e32 v97, v81
	v_cos_f32_e32 v81, v81
	v_fma_f32 v95, v73, v99, -v95
	v_fmac_f32_e32 v96, v64, v99
	v_mul_f32_e32 v98, v67, v97
	v_mul_f32_e32 v97, v75, v97
	v_fma_f32 v98, v75, v81, -v98
	v_fmac_f32_e32 v97, v67, v81
	s_cbranch_vccnz .LBB0_291
	s_and_b64 s[54:55], s[10:11], exec
	s_cselect_b32 s54, s77, s76
	s_cselect_b32 s55, s74, s75
	s_lshl_b32 s52, s52, 1
	s_or_b32 s52, s52, s97
	s_ashr_i32 s53, s52, 31
	s_lshl_b64 s[52:53], s[52:53], 18
	s_add_u32 s52, s55, s52
	s_addc_u32 s53, s54, s53
	v_lshlrev_b32_e32 v136, 7, v92
	v_lshl_add_u64 v[100:101], s[52:53], 0, v[136:137]
	v_lshlrev_b32_e32 v136, 1, v140
	v_lshl_add_u64 v[104:105], v[100:101], 0, v[136:137]
	v_cvt_pk_bf16_f32 v100, v76, v78
	v_cvt_pk_bf16_f32 v101, v83, v89
	v_cvt_pk_bf16_f32 v102, v91, v94
	v_cvt_pk_bf16_f32 v103, v95, v98
	s_mov_b64 s[54:55], 0
	global_store_dwordx4 v[104:105], v[100:103], off
	s_nop 1
	v_cvt_pk_bf16_f32 v100, v66, v77
	v_cvt_pk_bf16_f32 v101, v79, v88
	v_cvt_pk_bf16_f32 v102, v90, v93
	v_cvt_pk_bf16_f32 v103, v96, v97
	global_store_dwordx4 v[104:105], v[100:103], off offset:64

; __device__ __forceinline__ float gelu_tanh(float x) {
;     const float u = 0.7978845608028654f * (x + 0.044715f * x * x * x);
;     return x / (1.f + __expf(-2.f * u));
; }
; __device__ __forceinline__ float head_ssq(const float (&v)[16]) {
;     float s = 0.f;
; #pragma unroll
;     for (int i = 0; i < 16; ++i) s += v[i] * v[i];
;     s += __shfl_xor(s, 16); s += __shfl_xor(s, 32);
;     return s;
.LBB0_302:
	s_andn2_b64 vcc, exec, s[72:73]
	s_mov_b64 s[54:55], -1
	s_cbranch_vccnz .LBB0_318
	s_andn2_b64 vcc, exec, s[70:71]
	s_cbranch_vccnz .LBB0_315
	s_andn2_b64 vcc, exec, s[42:43]
	s_cbranch_vccnz .LBB0_312
	s_andn2_b64 vcc, exec, s[40:41]
	s_cbranch_vccnz .LBB0_307
	s_ashr_i32 s53, s52, 31
	s_lshl_b64 s[56:57], s[52:53], 21
	v_readlane_b32 s36, v254, 33
	s_mov_b64 s[58:59], s[42:43]
	v_mul_f32_e32 v48, v77, v77
	v_mul_f32_e32 v48, 0xbdd2d3e8, v48
	v_add_f32_e32 v48, 0xc0135761, v48
	v_mul_f32_e32 v48, v77, v48
	v_exp_f32_e32 v48, v48
	s_nop 0
	v_add_f32_e32 v48, 1.0, v48
	v_rcp_f32_e32 v49, v48
	s_nop 0
	v_mul_f32_e32 v48, v77, v49
	s_nop 0
	s_nop 0
	v_mul_f32_e32 v49, v78, v78
	v_mul_f32_e32 v49, 0xbdd2d3e8, v49
	v_add_f32_e32 v49, 0xc0135761, v49
	v_mul_f32_e32 v49, v78, v49
	v_exp_f32_e32 v49, v49
	s_nop 0
	v_add_f32_e32 v49, 1.0, v49
	v_rcp_f32_e32 v50, v49
	s_nop 0
	v_mul_f32_e32 v57, v78, v50
	s_nop 0
	s_nop 0
	v_mul_f32_e32 v49, v79, v79
	v_mul_f32_e32 v49, 0xbdd2d3e8, v49
	v_add_f32_e32 v49, 0xc0135761, v49
	v_mul_f32_e32 v49, v79, v49
	v_exp_f32_e32 v49, v49
	s_nop 0
	v_add_f32_e32 v49, 1.0, v49
	v_rcp_f32_e32 v50, v49
	s_nop 0
	v_mul_f32_e32 v85, v79, v50
	s_nop 0
	s_nop 0
	v_mul_f32_e32 v49, v80, v80
	v_mul_f32_e32 v49, 0xbdd2d3e8, v49
	v_add_f32_e32 v49, 0xc0135761, v49
	v_mul_f32_e32 v49, v80, v49
	v_exp_f32_e32 v49, v49
	s_nop 0
	v_add_f32_e32 v49, 1.0, v49
	v_rcp_f32_e32 v50, v49
	s_nop 0
	v_mul_f32_e32 v86, v80, v50
	s_nop 0
	s_nop 0
	v_mul_f32_e32 v49, v81, v81
	v_mul_f32_e32 v49, 0xbdd2d3e8, v49
	v_add_f32_e32 v49, 0xc0135761, v49
	v_mul_f32_e32 v49, v81, v49
	v_exp_f32_e32 v49, v49
	s_nop 0
	v_add_f32_e32 v49, 1.0, v49
	v_rcp_f32_e32 v50, v49
	s_nop 0
	v_mul_f32_e32 v87, v81, v50
	s_nop 0
	s_nop 0
	v_mul_f32_e32 v49, v82, v82
	v_mul_f32_e32 v49, 0xbdd2d3e8, v49
	v_add_f32_e32 v49, 0xc0135761, v49
	v_mul_f32_e32 v49, v82, v49
	v_exp_f32_e32 v49, v49
	s_nop 0
	v_add_f32_e32 v49, 1.0, v49
	v_rcp_f32_e32 v50, v49
	s_nop 0
	v_mul_f32_e32 v88, v82, v50
	s_nop 0
	s_nop 0
	v_mul_f32_e32 v49, v83, v83
	v_mul_f32_e32 v49, 0xbdd2d3e8, v49
	v_add_f32_e32 v49, 0xc0135761, v49
	v_mul_f32_e32 v49, v83, v49
	v_exp_f32_e32 v49, v49
	s_nop 0
	v_add_f32_e32 v49, 1.0, v49
	v_rcp_f32_e32 v50, v49
	s_nop 0
	v_mul_f32_e32 v89, v83, v50
	s_nop 0
	s_nop 0
	v_mul_f32_e32 v49, v84, v84
	v_mul_f32_e32 v49, 0xbdd2d3e8, v49
	v_add_f32_e32 v49, 0xc0135761, v49
	v_mul_f32_e32 v49, v84, v49
	v_exp_f32_e32 v49, v49
	s_nop 0
	v_add_f32_e32 v49, 1.0, v49
	v_rcp_f32_e32 v50, v49
	s_nop 0
	v_mul_f32_e32 v90, v84, v50
	v_mul_f32_e32 v51, v61, v61
	v_mul_f32_e32 v51, 0xbdd2d3e8, v51
	v_add_f32_e32 v51, 0xc0135761, v51
	v_mul_f32_e32 v51, v61, v51
	v_exp_f32_e32 v51, v51
	s_nop 0
	v_add_f32_e32 v51, 1.0, v51
	v_rcp_f32_e32 v66, v51
	s_nop 0
	v_mul_f32_e32 v67, v61, v66
	v_mul_f32_e32 v49, v57, v57
	v_fmac_f32_e32 v49, v48, v48
	v_fmac_f32_e32 v49, v85, v85
	v_fmac_f32_e32 v49, v86, v86
	v_fmac_f32_e32 v49, v87, v87
	v_fmac_f32_e32 v49, v88, v88
	v_fmac_f32_e32 v49, v89, v89
	v_mul_f32_e32 v50, v60, v60
	v_mul_f32_e32 v50, 0xbdd2d3e8, v50
	v_add_f32_e32 v50, 0xc0135761, v50
	v_mul_f32_e32 v50, v60, v50
	v_exp_f32_e32 v50, v50
	s_nop 0
	v_add_f32_e32 v50, 1.0, v50
	v_rcp_f32_e32 v51, v50
	s_nop 0
	v_mul_f32_e32 v66, v60, v51
	v_fmac_f32_e32 v49, v90, v90
	v_pk_mul_f32 v[50:51], v[66:67], v[66:67]
	s_nop 0
	v_add_f32_e32 v49, v50, v49
	v_add_f32_e32 v49, v51, v49
	s_nop 0
	s_nop 0
	v_mul_f32_e32 v51, v65, v65
	v_mul_f32_e32 v51, 0xbdd2d3e8, v51
	v_add_f32_e32 v51, 0xc0135761, v51
	v_mul_f32_e32 v51, v65, v51
	v_exp_f32_e32 v51, v51
	s_nop 0
	v_add_f32_e32 v51, 1.0, v51
	v_rcp_f32_e32 v52, v51
	s_nop 0
	v_mul_f32_e32 v69, v65, v52
	s_nop 0
	v_mul_f32_e32 v50, v64, v64
	v_mul_f32_e32 v50, 0xbdd2d3e8, v50
	v_add_f32_e32 v50, 0xc0135761, v50
	v_mul_f32_e32 v50, v64, v50
	v_exp_f32_e32 v50, v50
	s_nop 0
	v_add_f32_e32 v50, 1.0, v50
	v_rcp_f32_e32 v51, v50
	s_nop 0
	v_mul_f32_e32 v68, v64, v51
	v_pk_mul_f32 v[50:51], v[68:69], v[68:69]
	s_nop 0
	v_add_f32_e32 v49, v50, v49
	v_add_f32_e32 v49, v51, v49
	s_nop 0
	s_nop 0
	v_mul_f32_e32 v51, v63, v63
	v_mul_f32_e32 v51, 0xbdd2d3e8, v51
	v_add_f32_e32 v51, 0xc0135761, v51
	v_mul_f32_e32 v51, v63, v51
	v_exp_f32_e32 v51, v51
	s_nop 0
	v_add_f32_e32 v51, 1.0, v51
	v_rcp_f32_e32 v52, v51
	s_nop 0
	v_mul_f32_e32 v71, v63, v52
	s_nop 0
	v_mul_f32_e32 v50, v62, v62
	v_mul_f32_e32 v50, 0xbdd2d3e8, v50
	v_add_f32_e32 v50, 0xc0135761, v50
	v_mul_f32_e32 v50, v62, v50
	v_exp_f32_e32 v50, v50
	s_nop 0
	v_add_f32_e32 v50, 1.0, v50
	v_rcp_f32_e32 v51, v50
	s_nop 0
	v_mul_f32_e32 v70, v62, v51
	v_pk_mul_f32 v[50:51], v[70:71], v[70:71]
	s_nop 0
	v_add_f32_e32 v49, v50, v49
	v_add_f32_e32 v49, v51, v49
	s_nop 0
	s_nop 0
	v_mul_f32_e32 v51, v59, v59
	v_mul_f32_e32 v51, 0xbdd2d3e8, v51
	v_add_f32_e32 v51, 0xc0135761, v51
	v_mul_f32_e32 v51, v59, v51
	v_exp_f32_e32 v51, v51
	s_nop 0
	v_add_f32_e32 v51, 1.0, v51
	v_rcp_f32_e32 v52, v51
	s_nop 0
	v_mul_f32_e32 v73, v59, v52
	s_lshr_b32 s54, s89, 4
	s_and_b32 s54, s54, 0x78
	s_add_i32 s54, s54, s29
	v_mul_f32_e32 v50, v58, v58
	v_mul_f32_e32 v50, 0xbdd2d3e8, v50
	v_add_f32_e32 v50, 0xc0135761, v50
	v_mul_f32_e32 v50, v58, v50
	v_exp_f32_e32 v50, v50
	s_nop 0
	v_add_f32_e32 v50, 1.0, v50
	v_rcp_f32_e32 v51, v50
	s_nop 0
	v_mul_f32_e32 v72, v58, v51
	v_pk_mul_f32 v[50:51], v[72:73], v[72:73]
	s_mov_b32 s55, s9
	v_add_f32_e32 v49, v50, v49
	v_add_f32_e32 v49, v51, v49
	v_and_b32_e32 v51, 64, v165
	v_xor_b32_e32 v50, 16, v165
	v_add_u32_e32 v51, 64, v51
	v_cmp_lt_i32_e32 vcc, v50, v51
	s_lshl_b64 s[54:55], s[54:55], 14
	s_add_u32 s53, s36, s56
	v_cndmask_b32_e32 v50, v165, v50, vcc
	v_lshlrev_b32_e32 v50, 2, v50
	v_mov_b32_e32 v50, v49
	s_nop 1
	v_permlane16_swap_b32 v49, v50
	v_readlane_b32 s36, v254, 35
	s_addc_u32 s56, s36, s57
	s_add_u32 s54, s53, s54
	s_addc_u32 s55, s56, s55
	s_waitcnt lgkmcnt(0)
; __device__ __forceinline__ unsigned f2bf(float f) { unsigned u = __float_as_uint(f); return (u + 0x7fffu + ((u >> 16) & 1u)) >> 16; }
;     __device__ __forceinline__ void operator()(const f32x4 (&acc)[2][2][4][2], const pg8::Unit& u, int wr, int wc, int fr, int fq) const {
;     ...
;                     const float rn = rsqrtf(head_ssq(y) * (1.f / 64.f) + EPS);
;                     bf16_t* p = zvT + (((size_t)b * 16 + (s >> 7)) * 8 + g) * 8192 + (s & 127);
; #pragma unroll
;                     for (int i = 0; i < 16; ++i) { const int d = 32 * (i >> 3) + d0 + (i & 7); p[d * 128] = (bf16_t)f2bf(y[i] * rn * g_sgu[g * 64 + d]); }
	v_add_f32_e32 v49, v49, v50
	v_xor_b32_e32 v50, 32, v165
	v_cmp_lt_i32_e32 vcc, v50, v51
	s_mov_b64 s[56:57], s[40:41]
	s_nop 0
	v_cndmask_b32_e32 v50, v165, v50, vcc
	v_lshlrev_b32_e32 v50, 2, v50
	v_mov_b32_e32 v50, v49
	s_nop 1
	v_permlane32_swap_b32 v49, v50
	s_waitcnt lgkmcnt(0)
	v_add_f32_e32 v49, v49, v50
	v_fmamk_f32 v49, v49, 0x3c800000, v161
	v_cmp_gt_f32_e32 vcc, s61, v49
	v_mul_f32_e32 v50, 0x4b800000, v49
	s_nop 0
	v_cndmask_b32_e32 v49, v49, v50, vcc
	v_rsq_f32_e32 v49, v49
	s_nop 0
	v_mul_f32_e32 v50, 0x45800000, v49
	v_cndmask_b32_e32 v91, v49, v50, vcc
	v_and_b32_e32 v49, 0x4f, v56
	v_lshlrev_b32_e32 v136, 1, v49
	v_lshl_add_u64 v[74:75], s[54:55], 0, v[136:137]
	s_mov_b64 s[54:55], s[38:39]
	v_readlane_b32 s36, v254, 8
	v_or_b32_e32 v136, s27, v140
	v_readlane_b32 s37, v254, 9
	v_mul_f32_e32 v92, v48, v91
	v_readlane_b32 s50, v254, 22
	v_lshl_add_u64 v[52:53], v[136:137], 2, s[36:37]
	global_load_dwordx4 v[48:51], v[52:53], off offset:16
	s_nop 0
	global_load_dwordx4 v[52:55], v[52:53], off
	v_lshlrev_b32_e32 v136, 1, v142
	v_readlane_b32 s51, v254, 23
	v_readlane_b32 s38, v254, 10
	v_readlane_b32 s39, v254, 11
	v_readlane_b32 s40, v254, 12
	v_readlane_b32 s41, v254, 13
	v_readlane_b32 s42, v254, 14
	v_readlane_b32 s43, v254, 15
	v_readlane_b32 s49, v254, 21
	v_readlane_b32 s50, v254, 39
	s_mov_b64 s[38:39], s[54:55]
	s_mov_b64 s[42:43], s[58:59]
	s_mov_b64 s[40:41], s[56:57]
	v_readlane_b32 s49, v254, 41
	v_readlane_b32 s51, v254, 40
	s_mov_b64 s[54:55], 0
	v_readlane_b32 s44, v254, 16
	v_readlane_b32 s45, v254, 17
	v_readlane_b32 s46, v254, 18
	v_readlane_b32 s47, v254, 19
	v_readlane_b32 s48, v254, 20
	s_waitcnt vmcnt(0)
	v_mul_f32_e32 v52, v52, v92
	v_bfe_u32 v92, v52, 16, 1
	v_add3_u32 v52, v52, v92, s20
	v_lshl_add_u64 v[92:93], v[74:75], 0, v[136:137]
	global_store_short_d16_hi v[92:93], v52, off
	v_mul_f32_e32 v52, v57, v91
	v_add_u32_e32 v136, s27, v140
	v_mul_f32_e32 v52, v53, v52
	v_lshl_add_u64 v[92:93], v[136:137], 2, s[36:37]
	v_bfe_u32 v53, v52, 16, 1
	v_lshlrev_b32_e32 v136, 1, v144
	v_add3_u32 v57, v52, v53, s20
	v_lshl_add_u64 v[52:53], v[74:75], 0, v[136:137]
	global_store_short_d16_hi v[52:53], v57, off
	v_mul_f32_e32 v52, v85, v91
	v_mul_f32_e32 v52, v54, v52
	v_bfe_u32 v53, v52, 16, 1
	v_lshlrev_b32_e32 v136, 1, v146
	v_add3_u32 v54, v52, v53, s20
	v_lshl_add_u64 v[52:53], v[74:75], 0, v[136:137]
	global_store_short_d16_hi v[52:53], v54, off
	v_mul_f32_e32 v52, v86, v91
	v_mul_f32_e32 v52, v55, v52
	v_bfe_u32 v53, v52, 16, 1
	v_lshlrev_b32_e32 v136, 1, v148
	v_add3_u32 v54, v52, v53, s20
	v_lshl_add_u64 v[52:53], v[74:75], 0, v[136:137]
	global_store_short_d16_hi v[52:53], v54, off
	v_mul_f32_e32 v52, v87, v91
	v_mul_f32_e32 v48, v48, v52
	v_bfe_u32 v52, v48, 16, 1
	v_lshlrev_b32_e32 v136, 1, v150
	v_add3_u32 v48, v48, v52, s20
	v_lshl_add_u64 v[52:53], v[74:75], 0, v[136:137]
	global_store_short_d16_hi v[52:53], v48, off
	v_mul_f32_e32 v48, v88, v91
	v_mul_f32_e32 v48, v48, v49
	v_bfe_u32 v49, v48, 16, 1
	v_lshlrev_b32_e32 v136, 1, v152
	v_add3_u32 v52, v48, v49, s20
	v_lshl_add_u64 v[48:49], v[74:75], 0, v[136:137]
	global_store_short_d16_hi v[48:49], v52, off
	v_mul_f32_e32 v48, v89, v91
	v_mul_f32_e32 v48, v48, v50
	v_bfe_u32 v49, v48, 16, 1
	v_lshlrev_b32_e32 v136, 1, v154
	v_add3_u32 v50, v48, v49, s20
	v_lshl_add_u64 v[48:49], v[74:75], 0, v[136:137]
	global_store_short_d16_hi v[48:49], v50, off
	v_mul_f32_e32 v48, v90, v91
	v_mul_f32_e32 v48, v48, v51
	v_bfe_u32 v49, v48, 16, 1
	v_lshlrev_b32_e32 v136, 1, v156
	v_add3_u32 v50, v48, v49, s20
	v_lshl_add_u64 v[48:49], v[74:75], 0, v[136:137]
	global_store_short_d16_hi v[48:49], v50, off
	global_load_dwordx4 v[48:51], v[92:93], off offset:144
	s_nop 0
	global_load_dwordx4 v[52:55], v[92:93], off offset:128
	v_mul_f32_e32 v57, v66, v91
	v_lshlrev_b32_e32 v136, 1, v158
	v_lshl_add_u64 v[86:87], v[74:75], 0, v[136:137]
	v_lshlrev_b32_e32 v136, 1, v160
	s_waitcnt vmcnt(0)
	v_mul_f32_e32 v52, v57, v52
	v_bfe_u32 v57, v52, 16, 1
	v_add3_u32 v52, v52, v57, s20
	global_store_short_d16_hi v[86:87], v52, off
	v_mul_f32_e32 v52, v67, v91
	v_mul_f32_e32 v52, v52, v53
	v_bfe_u32 v53, v52, 16, 1
	v_add3_u32 v57, v52, v53, s20
	v_lshl_add_u64 v[52:53], v[74:75], 0, v[136:137]
	global_store_short_d16_hi v[52:53], v57, off
	v_mul_f32_e32 v52, v68, v91
	v_mul_f32_e32 v52, v52, v54
	v_bfe_u32 v53, v52, 16, 1
	v_lshlrev_b32_e32 v136, 1, v162
	v_add3_u32 v54, v52, v53, s20
	v_lshl_add_u64 v[52:53], v[74:75], 0, v[136:137]
	global_store_short_d16_hi v[52:53], v54, off
	v_mul_f32_e32 v52, v69, v91
	v_mul_f32_e32 v52, v52, v55
	v_bfe_u32 v53, v52, 16, 1
	v_lshlrev_b32_e32 v136, 1, v164
	v_add3_u32 v54, v52, v53, s20
	v_lshl_add_u64 v[52:53], v[74:75], 0, v[136:137]
	global_store_short_d16_hi v[52:53], v54, off
	v_mul_f32_e32 v52, v70, v91
	v_mul_f32_e32 v48, v52, v48
	v_bfe_u32 v52, v48, 16, 1
	v_add3_u32 v48, v48, v52, s20
	v_or_b32_e32 v52, 0x1200, v142
	v_lshlrev_b32_e32 v136, 1, v52
	v_lshl_add_u64 v[52:53], v[74:75], 0, v[136:137]
	global_store_short_d16_hi v[52:53], v48, off
	v_mul_f32_e32 v48, v71, v91
	v_mul_f32_e32 v48, v48, v49
	v_bfe_u32 v49, v48, 16, 1
	v_add3_u32 v52, v48, v49, s20
	v_or_b32_e32 v48, 0x1280, v142
	v_lshlrev_b32_e32 v136, 1, v48
	v_lshl_add_u64 v[48:49], v[74:75], 0, v[136:137]
	global_store_short_d16_hi v[48:49], v52, off
	v_mul_f32_e32 v48, v72, v91
	v_mul_f32_e32 v48, v48, v50
	v_bfe_u32 v49, v48, 16, 1
	v_add3_u32 v50, v48, v49, s20
	v_or_b32_e32 v48, 0x1300, v142
	v_lshlrev_b32_e32 v136, 1, v48
	v_lshl_add_u64 v[48:49], v[74:75], 0, v[136:137]
	global_store_short_d16_hi v[48:49], v50, off
	v_mul_f32_e32 v48, v73, v91
	v_mul_f32_e32 v48, v48, v51
	v_bfe_u32 v49, v48, 16, 1
	v_lshlrev_b32_e32 v136, 1, v172
	v_add3_u32 v50, v48, v49, s20
	v_lshl_add_u64 v[48:49], v[74:75], 0, v[136:137]
	global_store_short_d16_hi v[48:49], v50, off

;     __device__ __forceinline__ void operator()(const f32x4 (&acc)[2][2][4][2], const pg8::Unit& u, int wr, int wc, int fr, int fq) const {
;     ...
;                 if (cs < 8 || cs == 12 || cs == 13 || cs == 16 || cs == 17) {
;                     const float* gg = cs < 8 ? g_q : (cs < 14 ? g_k + 64 : g_k + 128);
;                     const float rn = rsqrtf(head_ssq(v) * (1.f / 64.f) + EPS) * (cs < 8 ? QSCALE : 1.f);
;                     float y[16];
; #pragma unroll
;                     for (int i = 0; i < 16; ++i) y[i] = v[i] * rn * gg[32 * (i >> 3) + d0 + (i & 7)];
;                     float r1[8], r2[8];
; #pragma unroll
;                     for (int i = 0; i < 8; ++i) { int di = d0 + i; asm volatile("" : "+v"(di));
;                         const float frev = __builtin_amdgcn_exp2f(-(float)di * (13.287712379549449f / 32.f)) * 0.15915494309189535f;
;                         float xr = (float)s * frev; xr -= __builtin_rintf(xr);
;                         const float c = __builtin_amdgcn_cosf(xr), sn = __builtin_amdgcn_sinf(xr); r1[i] = y[i] * c - y[8 + i] * sn; r2[i] = y[8 + i] * c + y[i] * sn; }
;                     if (cs < 8) {
;                         bf16_t* p = qn + (size_t)row * 512 + cs * 64 + d0; store8(p, y); store8(p + 32, y + 8);
;                         bf16_t* p2 = qr + (size_t)row * 512 + cs * 64 + d0; store8(p2, r1); store8(p2 + 32, r2);
;                     } else {
;                         bf16_t* p = (cs < 14 ? ksl : kwn) + ((size_t)(b * 2 + (cs & 1)) * 2048 + s) * 64 + d0; store8(p, r1); store8(p + 32, r2);
.LBB0_322:
	global_load_dwordx4 v[48:51], v167, s[54:55]
	global_load_dwordx4 v[52:55], v167, s[54:55] offset:16
	global_load_dwordx4 v[68:71], v167, s[54:55] offset:128
	global_load_dwordx4 v[72:75], v167, s[54:55] offset:144
	v_mul_f32_e32 v57, v78, v78
	v_fmac_f32_e32 v57, v77, v77
	v_fmac_f32_e32 v57, v79, v79
	v_fmac_f32_e32 v57, v80, v80
	v_fmac_f32_e32 v57, v81, v81
	v_fmac_f32_e32 v57, v82, v82
	v_fmac_f32_e32 v57, v83, v83
	v_pk_mul_f32 v[66:67], v[60:61], v[60:61]
	v_fmac_f32_e32 v57, v84, v84
	v_add_f32_e32 v57, v66, v57
	v_pk_mul_f32 v[86:87], v[64:65], v[64:65]
	v_add_f32_e32 v57, v67, v57
	v_add_f32_e32 v57, v86, v57
	v_pk_mul_f32 v[88:89], v[62:63], v[62:63]
	v_and_b32_e32 v92, 64, v165
	v_add_f32_e32 v57, v87, v57
	v_xor_b32_e32 v85, 16, v165
	v_add_u32_e32 v92, 64, v92
	v_add_f32_e32 v57, v88, v57
	v_pk_mul_f32 v[90:91], v[58:59], v[58:59]
	v_cmp_lt_i32_e32 vcc, v85, v92
	v_add_f32_e32 v57, v89, v57
	v_add_f32_e32 v57, v90, v57
	v_cndmask_b32_e32 v85, v165, v85, vcc
	v_lshlrev_b32_e32 v85, 2, v85
	v_add_f32_e32 v57, v91, v57
	v_mov_b32_e32 v66, v57
	s_nop 1
	v_permlane16_swap_b32 v57, v66
	v_xor_b32_e32 v67, 32, v165
	v_cmp_lt_i32_e32 vcc, v67, v92
	v_cvt_f32_u32_e32 v85, v76
	s_mov_b64 s[54:55], -1
	v_cndmask_b32_e32 v67, v165, v67, vcc
	v_lshlrev_b32_e32 v67, 2, v67
	s_waitcnt lgkmcnt(0)
	v_add_f32_e32 v57, v57, v66
	v_mov_b32_e32 v66, v57
	s_nop 1
	v_permlane32_swap_b32 v57, v66
	v_mov_b32_e32 v67, v140
	s_waitcnt lgkmcnt(0)
	v_add_f32_e32 v57, v57, v66
	v_fmamk_f32 v57, v57, 0x3c800000, v161
	v_mul_f32_e32 v66, 0x4b800000, v57
	v_cmp_gt_f32_e32 vcc, s61, v57
	v_cvt_f32_i32_e32 v67, v67
	s_nop 0
	v_cndmask_b32_e32 v57, v57, v66, vcc
	v_rsq_f32_e32 v57, v57
	v_mul_f32_e32 v66, 0xbed49a78, v67
	v_exp_f32_e32 v67, v66
	v_mul_f32_e32 v66, 0x45800000, v57
	v_cndmask_b32_e32 v57, v57, v66, vcc
	v_mul_f32_e32 v57, s53, v57
	v_mul_f32_e32 v66, v77, v57
	v_mul_f32_e32 v77, v78, v57
	v_mul_f32_e32 v78, v79, v57
	v_mul_f32_e32 v79, v80, v57
	v_mul_f32_e32 v80, v81, v57
	v_mul_f32_e32 v81, v82, v57
	v_mul_f32_e32 v82, v83, v57
	v_mul_f32_e32 v83, v84, v57
	v_mul_f32_e32 v84, v60, v57
	v_mul_f32_e32 v86, v61, v57
	v_mul_f32_e32 v87, v64, v57
	v_mul_f32_e32 v88, v65, v57
	v_mul_f32_e32 v89, v62, v57
	v_mul_f32_e32 v90, v63, v57
	v_mul_f32_e32 v91, v58, v57
	s_and_b64 vcc, exec, s[6:7]
	s_waitcnt vmcnt(3)
	v_mul_f32_e32 v64, v48, v66
	v_mul_f32_e32 v48, v59, v57
	v_mul_f32_e32 v57, 0.15915494, v67
	v_mul_f32_e32 v59, v57, v85
	v_rndne_f32_e32 v59, v59
	v_fma_f32 v57, v57, v85, -v59
	v_mov_b32_e32 v59, v141
	s_waitcnt vmcnt(2)
	v_mul_f32_e32 v63, v53, v81
	v_cvt_f32_i32_e32 v59, v59
	s_waitcnt vmcnt(1)
	v_mul_f32_e32 v53, v68, v84
	v_sin_f32_e32 v68, v57
	v_cos_f32_e32 v57, v57
	v_mul_f32_e32 v59, 0xbed49a78, v59
	v_mul_f32_e32 v61, v55, v83
	v_mul_f32_e32 v55, v69, v86
	v_exp_f32_e32 v69, v59
	s_waitcnt vmcnt(0)
	v_mul_f32_e32 v67, v48, v75
	v_mul_f32_e32 v48, v53, v68
	v_fma_f32 v59, v64, v57, -v48
	v_mul_f32_e32 v48, v64, v68
	v_fmac_f32_e32 v48, v53, v57
	v_mul_f32_e32 v57, 0.15915494, v69
	v_mov_b32_e32 v69, v143
	v_mul_f32_e32 v65, v51, v79
	v_cvt_f32_i32_e32 v69, v69
	v_mul_f32_e32 v51, v87, v70
	v_mul_f32_e32 v58, v54, v82
	v_mul_f32_e32 v54, v88, v71
	v_mul_f32_e32 v69, 0xbed49a78, v69
	v_exp_f32_e32 v70, v69
	v_mul_f32_e32 v68, v57, v85
	v_rndne_f32_e32 v68, v68
	v_fma_f32 v57, v57, v85, -v68
	v_mul_f32_e32 v70, 0.15915494, v70
	v_mul_f32_e32 v71, v70, v85
	v_rndne_f32_e32 v71, v71
	v_fma_f32 v70, v70, v85, -v71
	v_mov_b32_e32 v71, v145
	v_sin_f32_e32 v68, v57
	v_cos_f32_e32 v57, v57
	v_cvt_f32_i32_e32 v71, v71
	v_mul_f32_e32 v66, v49, v77
	v_mul_f32_e32 v62, v50, v78
	v_mul_f32_e32 v50, v89, v72
	v_mul_f32_e32 v69, v55, v68
	v_mul_f32_e32 v68, v66, v68
	v_sin_f32_e32 v72, v70
	v_fma_f32 v69, v66, v57, -v69
	v_fmac_f32_e32 v68, v55, v57
	v_cos_f32_e32 v57, v70
	v_mul_f32_e32 v71, 0xbed49a78, v71
	v_mul_f32_e32 v60, v52, v80
	v_mul_f32_e32 v52, v90, v73
	v_exp_f32_e32 v73, v71
	v_mul_f32_e32 v70, v51, v72
	v_fma_f32 v71, v62, v57, -v70
	v_mul_f32_e32 v70, v62, v72
	v_fmac_f32_e32 v70, v51, v57
	v_mul_f32_e32 v57, 0.15915494, v73
	v_mov_b32_e32 v73, v147
	v_mul_f32_e32 v49, v91, v74
	v_cvt_f32_i32_e32 v73, v73
	v_mul_f32_e32 v72, v57, v85
	v_rndne_f32_e32 v72, v72
	v_fma_f32 v57, v57, v85, -v72
	v_mul_f32_e32 v73, 0xbed49a78, v73
	v_exp_f32_e32 v74, v73
	v_sin_f32_e32 v72, v57
	v_cos_f32_e32 v57, v57
	v_mov_b32_e32 v81, v157
	v_mul_f32_e32 v74, 0.15915494, v74
	v_mul_f32_e32 v75, v74, v85
	v_rndne_f32_e32 v75, v75
	v_fma_f32 v74, v74, v85, -v75
	v_mov_b32_e32 v75, v153
	v_mul_f32_e32 v73, v54, v72
	v_cvt_f32_i32_e32 v75, v75
	v_mul_f32_e32 v72, v65, v72
	v_sin_f32_e32 v77, v74
	v_fma_f32 v73, v65, v57, -v73
	v_fmac_f32_e32 v72, v54, v57
	v_cos_f32_e32 v57, v74
	v_mul_f32_e32 v75, 0xbed49a78, v75
	v_exp_f32_e32 v78, v75
	v_mul_f32_e32 v74, v50, v77
	v_fma_f32 v75, v60, v57, -v74
	v_mul_f32_e32 v74, v60, v77
	v_fmac_f32_e32 v74, v50, v57
	v_mul_f32_e32 v57, 0.15915494, v78
	v_mov_b32_e32 v78, v155
	v_mul_f32_e32 v77, v57, v85
	v_cvt_f32_i32_e32 v78, v78
	v_cvt_f32_i32_e32 v81, v81
	v_rndne_f32_e32 v77, v77
	v_fma_f32 v57, v57, v85, -v77
	v_mul_f32_e32 v78, 0xbed49a78, v78
	v_exp_f32_e32 v79, v78
	v_sin_f32_e32 v77, v57
	v_cos_f32_e32 v57, v57
	v_mul_f32_e32 v81, 0xbed49a78, v81
	v_mul_f32_e32 v79, 0.15915494, v79
	v_mul_f32_e32 v80, v79, v85
	v_rndne_f32_e32 v80, v80
	v_fma_f32 v79, v79, v85, -v80
	v_cos_f32_e32 v80, v79
	v_sin_f32_e32 v79, v79
	v_exp_f32_e32 v82, v81
	v_mul_f32_e32 v78, v52, v77
	v_mul_f32_e32 v77, v63, v77
	v_fma_f32 v78, v63, v57, -v78
	v_fmac_f32_e32 v77, v52, v57
	v_mul_f32_e32 v57, v49, v79
	v_fma_f32 v81, v58, v80, -v57
	v_mul_f32_e32 v57, 0.15915494, v82
	v_mul_f32_e32 v82, v57, v85
	v_rndne_f32_e32 v82, v82
	v_fma_f32 v57, v57, v85, -v82
	v_sin_f32_e32 v83, v57
	v_cos_f32_e32 v57, v57
	v_mul_f32_e32 v79, v58, v79
	v_fmac_f32_e32 v79, v49, v80
	v_mul_f32_e32 v80, v67, v83
	v_fma_f32 v82, v61, v57, -v80
	v_mul_f32_e32 v80, v61, v83
	v_fmac_f32_e32 v80, v67, v57
	s_cbranch_vccnz .LBB0_324
	s_and_b64 s[54:55], s[10:11], exec
	s_cselect_b32 s53, s77, s76
	s_cselect_b32 s56, s74, s75
	s_lshl_b32 s54, s52, 1
	s_or_b32 s54, s54, s97
	s_ashr_i32 s55, s54, 31
	s_lshl_b64 s[54:55], s[54:55], 18
	s_add_u32 s54, s56, s54
	s_addc_u32 s55, s53, s55
	v_lshlrev_b32_e32 v136, 7, v76
	v_lshl_add_u64 v[84:85], s[54:55], 0, v[136:137]
	v_lshlrev_b32_e32 v136, 1, v140
	v_lshl_add_u64 v[88:89], v[84:85], 0, v[136:137]
	v_cvt_pk_bf16_f32 v84, v59, v69
	v_cvt_pk_bf16_f32 v85, v71, v73
	v_cvt_pk_bf16_f32 v86, v75, v78
	v_cvt_pk_bf16_f32 v87, v81, v82
	s_mov_b64 s[54:55], 0
	global_store_dwordx4 v[88:89], v[84:87], off
	s_nop 1
	v_cvt_pk_bf16_f32 v84, v48, v68
	v_cvt_pk_bf16_f32 v85, v70, v72
	v_cvt_pk_bf16_f32 v86, v74, v77
	v_cvt_pk_bf16_f32 v87, v79, v80
	global_store_dwordx4 v[88:89], v[84:87], off offset:64

; __device__ __forceinline__ float gelu_tanh(float x) {
;     const float u = 0.7978845608028654f * (x + 0.044715f * x * x * x);
;     return x / (1.f + __expf(-2.f * u));
; }
; __device__ __forceinline__ float head_ssq(const float (&v)[16]) {
;     float s = 0.f;
; #pragma unroll
;     for (int i = 0; i < 16; ++i) s += v[i] * v[i];
;     s += __shfl_xor(s, 16); s += __shfl_xor(s, 32);
;     return s;
.LBB0_335:
	s_andn2_b64 vcc, exec, s[72:73]
	s_mov_b64 s[54:55], -1
	s_cbranch_vccnz .LBB0_351
	s_andn2_b64 vcc, exec, s[70:71]
	s_cbranch_vccnz .LBB0_348
	s_andn2_b64 vcc, exec, s[42:43]
	s_cbranch_vccnz .LBB0_345
	s_andn2_b64 vcc, exec, s[40:41]
	s_cbranch_vccnz .LBB0_340
	s_ashr_i32 s53, s52, 31
	s_lshl_b64 s[56:57], s[52:53], 21
	v_readlane_b32 s36, v254, 33
	s_mov_b64 s[58:59], s[42:43]
	v_mul_f32_e32 v32, v69, v69
	v_mul_f32_e32 v32, 0xbdd2d3e8, v32
	v_add_f32_e32 v32, 0xc0135761, v32
	v_mul_f32_e32 v32, v69, v32
	v_exp_f32_e32 v32, v32
	s_nop 0
	v_add_f32_e32 v32, 1.0, v32
	v_rcp_f32_e32 v33, v32
	s_nop 0
	v_mul_f32_e32 v32, v69, v33
	s_nop 0
	s_nop 0
	v_mul_f32_e32 v33, v68, v68
	v_mul_f32_e32 v33, 0xbdd2d3e8, v33
	v_add_f32_e32 v33, 0xc0135761, v33
	v_mul_f32_e32 v33, v68, v33
	v_exp_f32_e32 v33, v33
	s_nop 0
	v_add_f32_e32 v33, 1.0, v33
	v_rcp_f32_e32 v34, v33
	s_nop 0
	v_mul_f32_e32 v41, v68, v34
	s_nop 0
	s_nop 0
	v_mul_f32_e32 v33, v67, v67
	v_mul_f32_e32 v33, 0xbdd2d3e8, v33
	v_add_f32_e32 v33, 0xc0135761, v33
	v_mul_f32_e32 v33, v67, v33
	v_exp_f32_e32 v33, v33
	s_nop 0
	v_add_f32_e32 v33, 1.0, v33
	v_rcp_f32_e32 v34, v33
	s_nop 0
	v_mul_f32_e32 v70, v67, v34
	s_nop 0
	s_nop 0
	v_mul_f32_e32 v33, v66, v66
	v_mul_f32_e32 v33, 0xbdd2d3e8, v33
	v_add_f32_e32 v33, 0xc0135761, v33
	v_mul_f32_e32 v33, v66, v33
	v_exp_f32_e32 v33, v33
	s_nop 0
	v_add_f32_e32 v33, 1.0, v33
	v_rcp_f32_e32 v34, v33
	s_nop 0
	v_mul_f32_e32 v71, v66, v34
	s_nop 0
	s_nop 0
	v_mul_f32_e32 v33, v65, v65
	v_mul_f32_e32 v33, 0xbdd2d3e8, v33
	v_add_f32_e32 v33, 0xc0135761, v33
	v_mul_f32_e32 v33, v65, v33
	v_exp_f32_e32 v33, v33
	s_nop 0
	v_add_f32_e32 v33, 1.0, v33
	v_rcp_f32_e32 v34, v33
	s_nop 0
	v_mul_f32_e32 v72, v65, v34
	s_nop 0
	s_nop 0
	v_mul_f32_e32 v33, v64, v64
	v_mul_f32_e32 v33, 0xbdd2d3e8, v33
	v_add_f32_e32 v33, 0xc0135761, v33
	v_mul_f32_e32 v33, v64, v33
	v_exp_f32_e32 v33, v33
	s_nop 0
	v_add_f32_e32 v33, 1.0, v33
	v_rcp_f32_e32 v34, v33
	s_nop 0
	v_mul_f32_e32 v73, v64, v34
	s_nop 0
	s_nop 0
	v_mul_f32_e32 v33, v63, v63
	v_mul_f32_e32 v33, 0xbdd2d3e8, v33
	v_add_f32_e32 v33, 0xc0135761, v33
	v_mul_f32_e32 v33, v63, v33
	v_exp_f32_e32 v33, v33
	s_nop 0
	v_add_f32_e32 v33, 1.0, v33
	v_rcp_f32_e32 v34, v33
	s_nop 0
	v_mul_f32_e32 v74, v63, v34
	s_nop 0
	s_nop 0
	v_mul_f32_e32 v33, v62, v62
	v_mul_f32_e32 v33, 0xbdd2d3e8, v33
	v_add_f32_e32 v33, 0xc0135761, v33
	v_mul_f32_e32 v33, v62, v33
	v_exp_f32_e32 v33, v33
	s_nop 0
	v_add_f32_e32 v33, 1.0, v33
	v_rcp_f32_e32 v34, v33
	s_nop 0
	v_mul_f32_e32 v75, v62, v34
	v_mul_f32_e32 v35, v49, v49
	v_mul_f32_e32 v35, 0xbdd2d3e8, v35
	v_add_f32_e32 v35, 0xc0135761, v35
	v_mul_f32_e32 v35, v49, v35
	v_exp_f32_e32 v35, v35
	s_nop 0
	v_add_f32_e32 v35, 1.0, v35
	v_rcp_f32_e32 v50, v35
	s_nop 0
	v_mul_f32_e32 v51, v49, v50
	v_mul_f32_e32 v33, v41, v41
	v_fmac_f32_e32 v33, v32, v32
	v_fmac_f32_e32 v33, v70, v70
	v_fmac_f32_e32 v33, v71, v71
	v_fmac_f32_e32 v33, v72, v72
	v_fmac_f32_e32 v33, v73, v73
	v_fmac_f32_e32 v33, v74, v74
	v_mul_f32_e32 v34, v48, v48
	v_mul_f32_e32 v34, 0xbdd2d3e8, v34
	v_add_f32_e32 v34, 0xc0135761, v34
	v_mul_f32_e32 v34, v48, v34
	v_exp_f32_e32 v34, v34
	s_nop 0
	v_add_f32_e32 v34, 1.0, v34
	v_rcp_f32_e32 v35, v34
	s_nop 0
	v_mul_f32_e32 v50, v48, v35
	v_fmac_f32_e32 v33, v75, v75
	v_pk_mul_f32 v[34:35], v[50:51], v[50:51]
	s_nop 0
	v_add_f32_e32 v33, v34, v33
	v_add_f32_e32 v33, v35, v33
	s_nop 0
	s_nop 0
	v_mul_f32_e32 v35, v47, v47
	v_mul_f32_e32 v35, 0xbdd2d3e8, v35
	v_add_f32_e32 v35, 0xc0135761, v35
	v_mul_f32_e32 v35, v47, v35
	v_exp_f32_e32 v35, v35
	s_nop 0
	v_add_f32_e32 v35, 1.0, v35
	v_rcp_f32_e32 v36, v35
	s_nop 0
	v_mul_f32_e32 v53, v47, v36
	s_nop 0
	v_mul_f32_e32 v34, v46, v46
	v_mul_f32_e32 v34, 0xbdd2d3e8, v34
	v_add_f32_e32 v34, 0xc0135761, v34
	v_mul_f32_e32 v34, v46, v34
	v_exp_f32_e32 v34, v34
	s_nop 0
	v_add_f32_e32 v34, 1.0, v34
	v_rcp_f32_e32 v35, v34
	s_nop 0
	v_mul_f32_e32 v52, v46, v35
	v_pk_mul_f32 v[34:35], v[52:53], v[52:53]
	s_nop 0
	v_add_f32_e32 v33, v34, v33
	v_add_f32_e32 v33, v35, v33
	s_nop 0
	s_nop 0
	v_mul_f32_e32 v35, v45, v45
	v_mul_f32_e32 v35, 0xbdd2d3e8, v35
	v_add_f32_e32 v35, 0xc0135761, v35
	v_mul_f32_e32 v35, v45, v35
	v_exp_f32_e32 v35, v35
	s_nop 0
	v_add_f32_e32 v35, 1.0, v35
	v_rcp_f32_e32 v36, v35
	s_nop 0
	v_mul_f32_e32 v55, v45, v36
	s_nop 0
	v_mul_f32_e32 v34, v44, v44
	v_mul_f32_e32 v34, 0xbdd2d3e8, v34
	v_add_f32_e32 v34, 0xc0135761, v34
	v_mul_f32_e32 v34, v44, v34
	v_exp_f32_e32 v34, v34
	s_nop 0
	v_add_f32_e32 v34, 1.0, v34
	v_rcp_f32_e32 v35, v34
	s_nop 0
	v_mul_f32_e32 v54, v44, v35
	v_pk_mul_f32 v[34:35], v[54:55], v[54:55]
	s_nop 0
	v_add_f32_e32 v33, v34, v33
	v_add_f32_e32 v33, v35, v33
	s_nop 0
	s_nop 0
	v_mul_f32_e32 v35, v43, v43
	v_mul_f32_e32 v35, 0xbdd2d3e8, v35
	v_add_f32_e32 v35, 0xc0135761, v35
	v_mul_f32_e32 v35, v43, v35
	v_exp_f32_e32 v35, v35
	s_nop 0
	v_add_f32_e32 v35, 1.0, v35
	v_rcp_f32_e32 v36, v35
	s_nop 0
	v_mul_f32_e32 v59, v43, v36
	s_lshr_b32 s54, s89, 4
	s_and_b32 s54, s54, 0x78
	s_add_i32 s54, s54, s29
	v_mul_f32_e32 v34, v42, v42
	v_mul_f32_e32 v34, 0xbdd2d3e8, v34
	v_add_f32_e32 v34, 0xc0135761, v34
	v_mul_f32_e32 v34, v42, v34
	v_exp_f32_e32 v34, v34
	s_nop 0
	v_add_f32_e32 v34, 1.0, v34
	v_rcp_f32_e32 v35, v34
	s_nop 0
	v_mul_f32_e32 v58, v42, v35
	v_pk_mul_f32 v[34:35], v[58:59], v[58:59]
	s_mov_b32 s55, s9
	v_add_f32_e32 v33, v34, v33
	v_add_f32_e32 v33, v35, v33
	v_and_b32_e32 v35, 64, v165
	v_xor_b32_e32 v34, 16, v165
	v_add_u32_e32 v35, 64, v35
	v_cmp_lt_i32_e32 vcc, v34, v35
	s_lshl_b64 s[54:55], s[54:55], 14
	s_add_u32 s53, s36, s56
	v_cndmask_b32_e32 v34, v165, v34, vcc
	v_lshlrev_b32_e32 v34, 2, v34
	v_mov_b32_e32 v34, v33
	s_nop 1
	v_permlane16_swap_b32 v33, v34
	v_readlane_b32 s36, v254, 35
	s_addc_u32 s56, s36, s57
	s_add_u32 s54, s53, s54
	s_addc_u32 s55, s56, s55
	s_waitcnt lgkmcnt(0)
; __device__ __forceinline__ unsigned f2bf(float f) { unsigned u = __float_as_uint(f); return (u + 0x7fffu + ((u >> 16) & 1u)) >> 16; }
;     __device__ __forceinline__ void operator()(const f32x4 (&acc)[2][2][4][2], const pg8::Unit& u, int wr, int wc, int fr, int fq) const {
;     ...
;                     const float rn = rsqrtf(head_ssq(y) * (1.f / 64.f) + EPS);
;                     bf16_t* p = zvT + (((size_t)b * 16 + (s >> 7)) * 8 + g) * 8192 + (s & 127);
; #pragma unroll
;                     for (int i = 0; i < 16; ++i) { const int d = 32 * (i >> 3) + d0 + (i & 7); p[d * 128] = (bf16_t)f2bf(y[i] * rn * g_sgu[g * 64 + d]); }
	v_add_f32_e32 v33, v33, v34
	v_xor_b32_e32 v34, 32, v165
	v_cmp_lt_i32_e32 vcc, v34, v35
	s_mov_b64 s[56:57], s[40:41]
	s_nop 0
	v_cndmask_b32_e32 v34, v165, v34, vcc
	v_lshlrev_b32_e32 v34, 2, v34
	v_mov_b32_e32 v34, v33
	s_nop 1
	v_permlane32_swap_b32 v33, v34
	s_waitcnt lgkmcnt(0)
	v_add_f32_e32 v33, v33, v34
	v_fmamk_f32 v33, v33, 0x3c800000, v161
	v_cmp_gt_f32_e32 vcc, s61, v33
	v_mul_f32_e32 v34, 0x4b800000, v33
	s_nop 0
	v_cndmask_b32_e32 v33, v33, v34, vcc
	v_rsq_f32_e32 v33, v33
	s_nop 0
	v_mul_f32_e32 v34, 0x45800000, v33
	v_cndmask_b32_e32 v76, v33, v34, vcc
	v_and_b32_e32 v33, 0x5f, v40
	v_lshlrev_b32_e32 v136, 1, v33
	v_lshl_add_u64 v[60:61], s[54:55], 0, v[136:137]
	s_mov_b64 s[54:55], s[38:39]
	v_readlane_b32 s36, v254, 8
	v_or_b32_e32 v136, s27, v140
	v_readlane_b32 s37, v254, 9
	v_mul_f32_e32 v77, v32, v76
	v_readlane_b32 s50, v254, 22
	v_lshl_add_u64 v[36:37], v[136:137], 2, s[36:37]
	global_load_dwordx4 v[32:35], v[36:37], off offset:16
	s_nop 0
	global_load_dwordx4 v[36:39], v[36:37], off
	v_lshlrev_b32_e32 v136, 1, v142
	v_lshl_add_u64 v[78:79], v[60:61], 0, v[136:137]
	v_add_u32_e32 v136, s27, v140
	v_readlane_b32 s51, v254, 23
	v_readlane_b32 s38, v254, 10
	v_readlane_b32 s39, v254, 11
	v_readlane_b32 s40, v254, 12
	v_readlane_b32 s41, v254, 13
	v_readlane_b32 s42, v254, 14
	v_readlane_b32 s43, v254, 15
	v_readlane_b32 s49, v254, 21
	v_readlane_b32 s50, v254, 39
	s_mov_b64 s[38:39], s[54:55]
	s_mov_b64 s[42:43], s[58:59]
	s_mov_b64 s[40:41], s[56:57]
	v_readlane_b32 s49, v254, 41
	v_readlane_b32 s51, v254, 40
	s_mov_b64 s[54:55], 0
	v_readlane_b32 s44, v254, 16
	v_readlane_b32 s45, v254, 17
	v_readlane_b32 s46, v254, 18
	v_readlane_b32 s47, v254, 19
	v_readlane_b32 s48, v254, 20
	s_waitcnt vmcnt(0)
	v_mul_f32_e32 v36, v36, v77
	v_bfe_u32 v77, v36, 16, 1
	v_add3_u32 v36, v36, v77, s20
	global_store_short_d16_hi v[78:79], v36, off
	v_mul_f32_e32 v36, v41, v76
	v_mul_f32_e32 v36, v37, v36
	v_lshl_add_u64 v[78:79], v[136:137], 2, s[36:37]
	v_bfe_u32 v37, v36, 16, 1
	v_lshlrev_b32_e32 v136, 1, v144
	v_add3_u32 v41, v36, v37, s20
	v_lshl_add_u64 v[36:37], v[60:61], 0, v[136:137]
	global_store_short_d16_hi v[36:37], v41, off
	v_mul_f32_e32 v36, v70, v76
	v_mul_f32_e32 v36, v38, v36
	v_bfe_u32 v37, v36, 16, 1
	v_lshlrev_b32_e32 v136, 1, v146
	v_add3_u32 v38, v36, v37, s20
	v_lshl_add_u64 v[36:37], v[60:61], 0, v[136:137]
	global_store_short_d16_hi v[36:37], v38, off
	v_mul_f32_e32 v36, v71, v76
	v_mul_f32_e32 v36, v39, v36
	v_bfe_u32 v37, v36, 16, 1
	v_lshlrev_b32_e32 v136, 1, v148
	v_add3_u32 v38, v36, v37, s20
	v_lshl_add_u64 v[36:37], v[60:61], 0, v[136:137]
	global_store_short_d16_hi v[36:37], v38, off
	v_mul_f32_e32 v36, v72, v76
	v_mul_f32_e32 v32, v32, v36
	v_bfe_u32 v36, v32, 16, 1
	v_lshlrev_b32_e32 v136, 1, v150
	v_add3_u32 v32, v32, v36, s20
	v_lshl_add_u64 v[36:37], v[60:61], 0, v[136:137]
	global_store_short_d16_hi v[36:37], v32, off
	v_mul_f32_e32 v32, v73, v76
	v_mul_f32_e32 v32, v32, v33
	v_bfe_u32 v33, v32, 16, 1
	v_lshlrev_b32_e32 v136, 1, v152
	v_add3_u32 v36, v32, v33, s20
	v_lshl_add_u64 v[32:33], v[60:61], 0, v[136:137]
	global_store_short_d16_hi v[32:33], v36, off
	v_mul_f32_e32 v32, v74, v76
	v_mul_f32_e32 v32, v32, v34
	v_bfe_u32 v33, v32, 16, 1
	v_lshlrev_b32_e32 v136, 1, v154
	v_add3_u32 v34, v32, v33, s20
	v_lshl_add_u64 v[32:33], v[60:61], 0, v[136:137]
	global_store_short_d16_hi v[32:33], v34, off
	v_mul_f32_e32 v32, v75, v76
	v_mul_f32_e32 v32, v32, v35
	v_bfe_u32 v33, v32, 16, 1
	v_lshlrev_b32_e32 v136, 1, v156
	v_add3_u32 v34, v32, v33, s20
	v_lshl_add_u64 v[32:33], v[60:61], 0, v[136:137]
	global_store_short_d16_hi v[32:33], v34, off
	global_load_dwordx4 v[32:35], v[78:79], off offset:144
	s_nop 0
	global_load_dwordx4 v[36:39], v[78:79], off offset:128
	v_mul_f32_e32 v41, v50, v76
	v_lshlrev_b32_e32 v136, 1, v158
	v_lshl_add_u64 v[70:71], v[60:61], 0, v[136:137]
	v_lshlrev_b32_e32 v136, 1, v160
	s_waitcnt vmcnt(0)
	v_mul_f32_e32 v36, v41, v36
	v_bfe_u32 v41, v36, 16, 1
	v_add3_u32 v36, v36, v41, s20
	global_store_short_d16_hi v[70:71], v36, off
	v_mul_f32_e32 v36, v51, v76
	v_mul_f32_e32 v36, v36, v37
	v_bfe_u32 v37, v36, 16, 1
	v_add3_u32 v41, v36, v37, s20
	v_lshl_add_u64 v[36:37], v[60:61], 0, v[136:137]
	global_store_short_d16_hi v[36:37], v41, off
	v_mul_f32_e32 v36, v52, v76
	v_mul_f32_e32 v36, v36, v38
	v_bfe_u32 v37, v36, 16, 1
	v_lshlrev_b32_e32 v136, 1, v162
	v_add3_u32 v38, v36, v37, s20
	v_lshl_add_u64 v[36:37], v[60:61], 0, v[136:137]
	global_store_short_d16_hi v[36:37], v38, off
	v_mul_f32_e32 v36, v53, v76
	v_mul_f32_e32 v36, v36, v39
	v_bfe_u32 v37, v36, 16, 1
	v_lshlrev_b32_e32 v136, 1, v164
	v_add3_u32 v38, v36, v37, s20
	v_lshl_add_u64 v[36:37], v[60:61], 0, v[136:137]
	global_store_short_d16_hi v[36:37], v38, off
	v_mul_f32_e32 v36, v54, v76
	v_mul_f32_e32 v32, v36, v32
	v_bfe_u32 v36, v32, 16, 1
	v_add3_u32 v32, v32, v36, s20
	v_or_b32_e32 v36, 0x1200, v142
	v_lshlrev_b32_e32 v136, 1, v36
	v_lshl_add_u64 v[36:37], v[60:61], 0, v[136:137]
	global_store_short_d16_hi v[36:37], v32, off
	v_mul_f32_e32 v32, v55, v76
	v_mul_f32_e32 v32, v32, v33
	v_bfe_u32 v33, v32, 16, 1
	v_add3_u32 v36, v32, v33, s20
	v_or_b32_e32 v32, 0x1280, v142
	v_lshlrev_b32_e32 v136, 1, v32
	v_lshl_add_u64 v[32:33], v[60:61], 0, v[136:137]
	global_store_short_d16_hi v[32:33], v36, off
	v_mul_f32_e32 v32, v58, v76
	v_mul_f32_e32 v32, v32, v34
	v_bfe_u32 v33, v32, 16, 1
	v_add3_u32 v34, v32, v33, s20
	v_or_b32_e32 v32, 0x1300, v142
	v_lshlrev_b32_e32 v136, 1, v32
	v_lshl_add_u64 v[32:33], v[60:61], 0, v[136:137]
	global_store_short_d16_hi v[32:33], v34, off
	v_mul_f32_e32 v32, v59, v76
	v_mul_f32_e32 v32, v32, v35
	v_bfe_u32 v33, v32, 16, 1
	v_lshlrev_b32_e32 v136, 1, v172
	v_add3_u32 v34, v32, v33, s20
	v_lshl_add_u64 v[32:33], v[60:61], 0, v[136:137]
	global_store_short_d16_hi v[32:33], v34, off

;     __device__ __forceinline__ void operator()(const f32x4 (&acc)[2][2][4][2], const pg8::Unit& u, int wr, int wc, int fr, int fq) const {
;     ...
;                 if (cs < 8 || cs == 12 || cs == 13 || cs == 16 || cs == 17) {
;                     const float* gg = cs < 8 ? g_q : (cs < 14 ? g_k + 64 : g_k + 128);
;                     const float rn = rsqrtf(head_ssq(v) * (1.f / 64.f) + EPS) * (cs < 8 ? QSCALE : 1.f);
;                     float y[16];
; #pragma unroll
;                     for (int i = 0; i < 16; ++i) y[i] = v[i] * rn * gg[32 * (i >> 3) + d0 + (i & 7)];
;                     float r1[8], r2[8];
; #pragma unroll
;                     for (int i = 0; i < 8; ++i) { int di = d0 + i; asm volatile("" : "+v"(di));
;                         const float frev = __builtin_amdgcn_exp2f(-(float)di * (13.287712379549449f / 32.f)) * 0.15915494309189535f;
;                         float xr = (float)s * frev; xr -= __builtin_rintf(xr);
;                         const float c = __builtin_amdgcn_cosf(xr), sn = __builtin_amdgcn_sinf(xr); r1[i] = y[i] * c - y[8 + i] * sn; r2[i] = y[8 + i] * c + y[i] * sn; }
.LBB0_355:
	v_mul_f32_e32 v34, v68, v68
	v_fmac_f32_e32 v34, v69, v69
	v_fmac_f32_e32 v34, v67, v67
	v_fmac_f32_e32 v34, v66, v66
	v_fmac_f32_e32 v34, v65, v65
	v_fmac_f32_e32 v34, v64, v64
	v_fmac_f32_e32 v34, v63, v63
	v_fmac_f32_e32 v34, v62, v62
	v_pk_mul_f32 v[32:33], v[48:49], v[48:49]
	s_nop 0
	v_add_f32_e32 v32, v32, v34
	v_add_f32_e32 v34, v33, v32
	v_pk_mul_f32 v[32:33], v[46:47], v[46:47]
	s_nop 0
	v_add_f32_e32 v32, v32, v34
	v_add_f32_e32 v34, v33, v32
	v_pk_mul_f32 v[32:33], v[44:45], v[44:45]
	s_nop 0
	v_add_f32_e32 v32, v32, v34
	v_add_f32_e32 v34, v33, v32
	v_pk_mul_f32 v[32:33], v[42:43], v[42:43]
	s_nop 0
	v_add_f32_e32 v32, v32, v34
	v_and_b32_e32 v34, 64, v165
	v_add_f32_e32 v32, v33, v32
	v_xor_b32_e32 v33, 16, v165
	v_add_u32_e32 v34, 64, v34
	v_cmp_lt_i32_e32 vcc, v33, v34
	s_nop 1
	v_cndmask_b32_e32 v33, v165, v33, vcc
	v_lshlrev_b32_e32 v33, 2, v33
	v_mov_b32_e32 v33, v32
	s_nop 1
	v_permlane16_swap_b32 v32, v33
	s_waitcnt lgkmcnt(0)
	v_add_f32_e32 v32, v32, v33
	v_xor_b32_e32 v33, 32, v165
	v_cmp_lt_i32_e32 vcc, v33, v34
	global_load_dwordx4 v[50:53], v167, s[54:55] offset:16
	global_load_dwordx4 v[34:37], v167, s[54:55]
	v_cndmask_b32_e32 v33, v165, v33, vcc
	v_lshlrev_b32_e32 v33, 2, v33
	v_mov_b32_e32 v33, v32
	s_nop 1
	v_permlane32_swap_b32 v32, v33
	s_waitcnt lgkmcnt(0)
	v_add_f32_e32 v32, v32, v33
	v_fmamk_f32 v32, v32, 0x3c800000, v161
	v_cmp_gt_f32_e32 vcc, s61, v32
	v_mul_f32_e32 v33, 0x4b800000, v32
	s_nop 0
	v_cndmask_b32_e32 v32, v32, v33, vcc
	v_rsq_f32_e32 v32, v32
	s_nop 0
	v_mul_f32_e32 v33, 0x45800000, v32
	v_cndmask_b32_e32 v32, v32, v33, vcc
	v_mul_f32_e32 v41, s53, v32
	v_mul_f32_e32 v32, v69, v41
	v_mul_f32_e32 v33, v68, v41
	v_mul_f32_e32 v39, v62, v41
	v_mul_f32_e32 v44, v44, v41
	v_mul_f32_e32 v48, v48, v41
	v_mul_f32_e32 v49, v49, v41
	v_mul_f32_e32 v46, v46, v41
	v_mul_f32_e32 v47, v47, v41
	v_mul_f32_e32 v45, v45, v41
	v_mul_f32_e32 v42, v42, v41
	s_and_b64 vcc, exec, s[6:7]
	s_waitcnt vmcnt(1)
	v_mul_f32_e32 v39, v53, v39
	s_waitcnt vmcnt(0)
	v_mul_f32_e32 v32, v34, v32
	v_mul_f32_e32 v34, v35, v33
	v_mul_f32_e32 v33, v67, v41
	v_mul_f32_e32 v35, v66, v41
	v_mul_f32_e32 v33, v36, v33
	v_mul_f32_e32 v36, v37, v35
	v_mul_f32_e32 v37, v64, v41
	v_mul_f32_e32 v35, v65, v41
	v_mul_f32_e32 v38, v51, v37
	v_mul_f32_e32 v37, v63, v41
	v_mul_f32_e32 v35, v50, v35
	v_mul_f32_e32 v37, v52, v37
	global_load_dwordx4 v[50:53], v167, s[54:55] offset:144
	global_load_dwordx4 v[58:61], v167, s[54:55] offset:128
	v_mul_f32_e32 v41, v43, v41
	s_mov_b64 s[54:55], -1
	s_waitcnt vmcnt(1)
	v_mul_f32_e32 v44, v44, v50
	v_mov_b32_e32 v50, v140
	v_mul_f32_e32 v43, v41, v53
	v_cvt_f32_i32_e32 v50, v50
	v_cvt_f32_u32_e32 v41, v57
	v_mul_f32_e32 v45, v45, v51
	v_mul_f32_e32 v42, v42, v52
	v_mul_f32_e32 v50, 0xbed49a78, v50
	v_exp_f32_e32 v50, v50
	s_waitcnt vmcnt(0)
	v_mul_f32_e32 v48, v58, v48
	v_mul_f32_e32 v49, v59, v49
	v_mul_f32_e32 v46, v46, v60
	v_mul_f32_e32 v50, 0.15915494, v50
	v_mul_f32_e32 v51, v50, v41
	v_rndne_f32_e32 v51, v51
	v_fma_f32 v50, v50, v41, -v51
	v_cos_f32_e32 v52, v50
	v_sin_f32_e32 v50, v50
	v_mul_f32_e32 v47, v47, v61
	v_mul_f32_e32 v51, v48, v50
	v_mul_f32_e32 v50, v32, v50
	v_fma_f32 v51, v32, v52, -v51
	v_fmac_f32_e32 v50, v48, v52
	v_mov_b32_e32 v52, v141
	s_nop 0
	v_cvt_f32_i32_e32 v52, v52
	v_mul_f32_e32 v52, 0xbed49a78, v52
	v_exp_f32_e32 v52, v52
	s_nop 0
	v_mul_f32_e32 v52, 0.15915494, v52
	v_mul_f32_e32 v53, v52, v41
	v_rndne_f32_e32 v53, v53
	v_fma_f32 v52, v52, v41, -v53
	v_cos_f32_e32 v54, v52
	v_sin_f32_e32 v52, v52
	s_nop 0
	v_mul_f32_e32 v53, v49, v52
	v_mul_f32_e32 v52, v34, v52
	v_fma_f32 v53, v34, v54, -v53
	v_fmac_f32_e32 v52, v49, v54
	v_mov_b32_e32 v54, v143
	s_nop 0
	v_cvt_f32_i32_e32 v54, v54
	v_mul_f32_e32 v54, 0xbed49a78, v54
	v_exp_f32_e32 v54, v54
	s_nop 0
	v_mul_f32_e32 v54, 0.15915494, v54
	v_mul_f32_e32 v55, v54, v41
	v_rndne_f32_e32 v55, v55
	v_fma_f32 v54, v54, v41, -v55
	v_cos_f32_e32 v58, v54
	v_sin_f32_e32 v54, v54
	s_nop 0
	v_mul_f32_e32 v55, v46, v54
	v_mul_f32_e32 v54, v33, v54
	v_fma_f32 v55, v33, v58, -v55
	v_fmac_f32_e32 v54, v46, v58
	v_mov_b32_e32 v58, v145
	s_nop 0
	v_cvt_f32_i32_e32 v58, v58
	v_mul_f32_e32 v58, 0xbed49a78, v58
	v_exp_f32_e32 v58, v58
	s_nop 0
	v_mul_f32_e32 v58, 0.15915494, v58
	v_mul_f32_e32 v59, v58, v41
	v_rndne_f32_e32 v59, v59
	v_fma_f32 v58, v58, v41, -v59
	v_cos_f32_e32 v60, v58
	v_sin_f32_e32 v58, v58
	s_nop 0
	v_mul_f32_e32 v59, v47, v58
	v_mul_f32_e32 v58, v36, v58
	v_fma_f32 v59, v36, v60, -v59
	v_fmac_f32_e32 v58, v47, v60
	v_mov_b32_e32 v60, v147
	s_nop 0
	v_cvt_f32_i32_e32 v60, v60
	v_mul_f32_e32 v60, 0xbed49a78, v60
	v_exp_f32_e32 v60, v60
	s_nop 0
	v_mul_f32_e32 v60, 0.15915494, v60
	v_mul_f32_e32 v61, v60, v41
	v_rndne_f32_e32 v61, v61
	v_fma_f32 v60, v60, v41, -v61
	v_cos_f32_e32 v62, v60
	v_sin_f32_e32 v60, v60
	s_nop 0
	v_mul_f32_e32 v61, v44, v60
	v_mul_f32_e32 v60, v35, v60
	v_fma_f32 v61, v35, v62, -v61
	v_fmac_f32_e32 v60, v44, v62
	v_mov_b32_e32 v62, v153
	s_nop 0
	v_cvt_f32_i32_e32 v62, v62
	v_mul_f32_e32 v62, 0xbed49a78, v62
	v_exp_f32_e32 v62, v62
	s_nop 0
	v_mul_f32_e32 v62, 0.15915494, v62
	v_mul_f32_e32 v63, v62, v41
	v_rndne_f32_e32 v63, v63
	v_fma_f32 v62, v62, v41, -v63
	v_cos_f32_e32 v64, v62
	v_sin_f32_e32 v62, v62
	s_nop 0
	v_mul_f32_e32 v63, v45, v62
	v_mul_f32_e32 v62, v38, v62
	v_fma_f32 v63, v38, v64, -v63
	v_fmac_f32_e32 v62, v45, v64
	v_mov_b32_e32 v64, v155
	s_nop 0
	v_cvt_f32_i32_e32 v64, v64
	v_mul_f32_e32 v64, 0xbed49a78, v64
	v_exp_f32_e32 v64, v64
	s_nop 0
	v_mul_f32_e32 v64, 0.15915494, v64
	v_mul_f32_e32 v65, v64, v41
	v_rndne_f32_e32 v65, v65
	v_fma_f32 v64, v64, v41, -v65
	v_cos_f32_e32 v66, v64
	v_sin_f32_e32 v64, v64
	s_nop 0
	v_mul_f32_e32 v65, v42, v64
	v_mul_f32_e32 v64, v37, v64
	v_fma_f32 v65, v37, v66, -v65
	v_fmac_f32_e32 v64, v42, v66
	v_mov_b32_e32 v66, v157
	s_nop 0
	v_cvt_f32_i32_e32 v66, v66
	v_mul_f32_e32 v66, 0xbed49a78, v66
	v_exp_f32_e32 v66, v66
	s_nop 0
	v_mul_f32_e32 v66, 0.15915494, v66
	v_mul_f32_e32 v67, v66, v41
	v_rndne_f32_e32 v67, v67
	v_fma_f32 v41, v66, v41, -v67
	v_cos_f32_e32 v68, v41
	v_sin_f32_e32 v41, v41
	s_nop 0
	v_mul_f32_e32 v66, v43, v41
	v_fma_f32 v67, v39, v68, -v66
	v_mul_f32_e32 v66, v39, v41
	v_fmac_f32_e32 v66, v43, v68
	s_cbranch_vccnz .LBB0_357
;     __device__ __forceinline__ void operator()(const f32x4 (&acc)[2][2][4][2], const pg8::Unit& u, int wr, int wc, int fr, int fq) const {
;     ...
;                     } else {
;                         bf16_t* p = (cs < 14 ? ksl : kwn) + ((size_t)(b * 2 + (cs & 1)) * 2048 + s) * 64 + d0; store8(p, r1); store8(p + 32, r2);
	s_and_b64 s[54:55], s[10:11], exec
	s_cselect_b32 s53, s77, s76
	s_cselect_b32 s56, s74, s75
	s_lshl_b32 s54, s52, 1
	s_or_b32 s54, s54, s97
	s_ashr_i32 s55, s54, 31
	s_lshl_b64 s[54:55], s[54:55], 18
	s_add_u32 s54, s56, s54
	s_addc_u32 s55, s53, s55
	v_lshlrev_b32_e32 v136, 7, v57
	v_lshl_add_u64 v[68:69], s[54:55], 0, v[136:137]
	v_lshlrev_b32_e32 v136, 1, v140
	v_lshl_add_u64 v[72:73], v[68:69], 0, v[136:137]
	v_cvt_pk_bf16_f32 v68, v51, v53
	v_cvt_pk_bf16_f32 v69, v55, v59
	v_cvt_pk_bf16_f32 v70, v61, v63
	v_cvt_pk_bf16_f32 v71, v65, v67
	s_mov_b64 s[54:55], 0
	global_store_dwordx4 v[72:73], v[68:71], off
	s_nop 1
	v_cvt_pk_bf16_f32 v68, v50, v52
	v_cvt_pk_bf16_f32 v69, v54, v58
	v_cvt_pk_bf16_f32 v70, v60, v62
	v_cvt_pk_bf16_f32 v71, v64, v66
	global_store_dwordx4 v[72:73], v[68:71], off offset:64

; __device__ __forceinline__ float gelu_tanh(float x) {
;     const float u = 0.7978845608028654f * (x + 0.044715f * x * x * x);
;     return x / (1.f + __expf(-2.f * u));
; }
; __device__ __forceinline__ float head_ssq(const float (&v)[16]) {
;     float s = 0.f;
; #pragma unroll
;     for (int i = 0; i < 16; ++i) s += v[i] * v[i];
;     s += __shfl_xor(s, 16); s += __shfl_xor(s, 32);
;     return s;
.LBB0_368:
	s_andn2_b64 vcc, exec, s[72:73]
	s_mov_b64 s[54:55], -1
	s_cbranch_vccnz .LBB0_384
	s_andn2_b64 vcc, exec, s[70:71]
	s_cbranch_vccnz .LBB0_381
	s_andn2_b64 vcc, exec, s[42:43]
	s_cbranch_vccnz .LBB0_378
	s_andn2_b64 vcc, exec, s[40:41]
	s_cbranch_vccnz .LBB0_373
	s_ashr_i32 s53, s52, 31
	s_lshl_b64 s[56:57], s[52:53], 21
	v_readlane_b32 s36, v254, 33
	s_mov_b64 s[58:59], s[42:43]
	v_mul_f32_e32 v16, v45, v45
	v_mul_f32_e32 v16, 0xbdd2d3e8, v16
	v_add_f32_e32 v16, 0xc0135761, v16
	v_mul_f32_e32 v16, v45, v16
	v_exp_f32_e32 v16, v16
	s_nop 0
	v_add_f32_e32 v16, 1.0, v16
	v_rcp_f32_e32 v17, v16
	s_nop 0
	v_mul_f32_e32 v16, v45, v17
	s_nop 0
	s_nop 0
	v_mul_f32_e32 v17, v46, v46
	v_mul_f32_e32 v17, 0xbdd2d3e8, v17
	v_add_f32_e32 v17, 0xc0135761, v17
	v_mul_f32_e32 v17, v46, v17
	v_exp_f32_e32 v17, v17
	s_nop 0
	v_add_f32_e32 v17, 1.0, v17
	v_rcp_f32_e32 v18, v17
	s_nop 0
	v_mul_f32_e32 v25, v46, v18
	s_nop 0
	s_nop 0
	v_mul_f32_e32 v17, v47, v47
	v_mul_f32_e32 v17, 0xbdd2d3e8, v17
	v_add_f32_e32 v17, 0xc0135761, v17
	v_mul_f32_e32 v17, v47, v17
	v_exp_f32_e32 v17, v17
	s_nop 0
	v_add_f32_e32 v17, 1.0, v17
	v_rcp_f32_e32 v18, v17
	s_nop 0
	v_mul_f32_e32 v53, v47, v18
	s_nop 0
	s_nop 0
	v_mul_f32_e32 v17, v48, v48
	v_mul_f32_e32 v17, 0xbdd2d3e8, v17
	v_add_f32_e32 v17, 0xc0135761, v17
	v_mul_f32_e32 v17, v48, v17
	v_exp_f32_e32 v17, v17
	s_nop 0
	v_add_f32_e32 v17, 1.0, v17
	v_rcp_f32_e32 v18, v17
	s_nop 0
	v_mul_f32_e32 v54, v48, v18
	s_nop 0
	s_nop 0
	v_mul_f32_e32 v17, v49, v49
	v_mul_f32_e32 v17, 0xbdd2d3e8, v17
	v_add_f32_e32 v17, 0xc0135761, v17
	v_mul_f32_e32 v17, v49, v17
	v_exp_f32_e32 v17, v17
	s_nop 0
	v_add_f32_e32 v17, 1.0, v17
	v_rcp_f32_e32 v18, v17
	s_nop 0
	v_mul_f32_e32 v55, v49, v18
	s_nop 0
	s_nop 0
	v_mul_f32_e32 v17, v50, v50
	v_mul_f32_e32 v17, 0xbdd2d3e8, v17
	v_add_f32_e32 v17, 0xc0135761, v17
	v_mul_f32_e32 v17, v50, v17
	v_exp_f32_e32 v17, v17
	s_nop 0
	v_add_f32_e32 v17, 1.0, v17
	v_rcp_f32_e32 v18, v17
	s_nop 0
	v_mul_f32_e32 v57, v50, v18
	s_nop 0
	s_nop 0
	v_mul_f32_e32 v17, v51, v51
	v_mul_f32_e32 v17, 0xbdd2d3e8, v17
	v_add_f32_e32 v17, 0xc0135761, v17
	v_mul_f32_e32 v17, v51, v17
	v_exp_f32_e32 v17, v17
	s_nop 0
	v_add_f32_e32 v17, 1.0, v17
	v_rcp_f32_e32 v18, v17
	s_nop 0
	v_mul_f32_e32 v58, v51, v18
	s_nop 0
	s_nop 0
	v_mul_f32_e32 v17, v52, v52
	v_mul_f32_e32 v17, 0xbdd2d3e8, v17
	v_add_f32_e32 v17, 0xc0135761, v17
	v_mul_f32_e32 v17, v52, v17
	v_exp_f32_e32 v17, v17
	s_nop 0
	v_add_f32_e32 v17, 1.0, v17
	v_rcp_f32_e32 v18, v17
	s_nop 0
	v_mul_f32_e32 v59, v52, v18
	v_mul_f32_e32 v19, v29, v29
	v_mul_f32_e32 v19, 0xbdd2d3e8, v19
	v_add_f32_e32 v19, 0xc0135761, v19
	v_mul_f32_e32 v19, v29, v19
	v_exp_f32_e32 v19, v19
	s_nop 0
	v_add_f32_e32 v19, 1.0, v19
	v_rcp_f32_e32 v34, v19
	s_nop 0
	v_mul_f32_e32 v35, v29, v34
	v_mul_f32_e32 v17, v25, v25
	v_fmac_f32_e32 v17, v16, v16
	v_fmac_f32_e32 v17, v53, v53
	v_fmac_f32_e32 v17, v54, v54
	v_fmac_f32_e32 v17, v55, v55
	v_fmac_f32_e32 v17, v57, v57
	v_fmac_f32_e32 v17, v58, v58
	v_mul_f32_e32 v18, v28, v28
	v_mul_f32_e32 v18, 0xbdd2d3e8, v18
	v_add_f32_e32 v18, 0xc0135761, v18
	v_mul_f32_e32 v18, v28, v18
	v_exp_f32_e32 v18, v18
	s_nop 0
	v_add_f32_e32 v18, 1.0, v18
	v_rcp_f32_e32 v19, v18
	s_nop 0
	v_mul_f32_e32 v34, v28, v19
	v_fmac_f32_e32 v17, v59, v59
	v_pk_mul_f32 v[18:19], v[34:35], v[34:35]
	s_nop 0
	v_add_f32_e32 v17, v18, v17
	v_add_f32_e32 v17, v19, v17
	s_nop 0
	s_nop 0
	v_mul_f32_e32 v19, v33, v33
	v_mul_f32_e32 v19, 0xbdd2d3e8, v19
	v_add_f32_e32 v19, 0xc0135761, v19
	v_mul_f32_e32 v19, v33, v19
	v_exp_f32_e32 v19, v19
	s_nop 0
	v_add_f32_e32 v19, 1.0, v19
	v_rcp_f32_e32 v20, v19
	s_nop 0
	v_mul_f32_e32 v37, v33, v20
	s_nop 0
	v_mul_f32_e32 v18, v32, v32
	v_mul_f32_e32 v18, 0xbdd2d3e8, v18
	v_add_f32_e32 v18, 0xc0135761, v18
	v_mul_f32_e32 v18, v32, v18
	v_exp_f32_e32 v18, v18
	s_nop 0
	v_add_f32_e32 v18, 1.0, v18
	v_rcp_f32_e32 v19, v18
	s_nop 0
	v_mul_f32_e32 v36, v32, v19
	v_pk_mul_f32 v[18:19], v[36:37], v[36:37]
	s_nop 0
	v_add_f32_e32 v17, v18, v17
	v_add_f32_e32 v17, v19, v17
	s_nop 0
	s_nop 0
	v_mul_f32_e32 v19, v31, v31
	v_mul_f32_e32 v19, 0xbdd2d3e8, v19
	v_add_f32_e32 v19, 0xc0135761, v19
	v_mul_f32_e32 v19, v31, v19
	v_exp_f32_e32 v19, v19
	s_nop 0
	v_add_f32_e32 v19, 1.0, v19
	v_rcp_f32_e32 v20, v19
	s_nop 0
	v_mul_f32_e32 v39, v31, v20
	s_nop 0
	v_mul_f32_e32 v18, v30, v30
	v_mul_f32_e32 v18, 0xbdd2d3e8, v18
	v_add_f32_e32 v18, 0xc0135761, v18
	v_mul_f32_e32 v18, v30, v18
	v_exp_f32_e32 v18, v18
	s_nop 0
	v_add_f32_e32 v18, 1.0, v18
	v_rcp_f32_e32 v19, v18
	s_nop 0
	v_mul_f32_e32 v38, v30, v19
	v_pk_mul_f32 v[18:19], v[38:39], v[38:39]
	s_nop 0
	v_add_f32_e32 v17, v18, v17
	v_add_f32_e32 v17, v19, v17
	s_nop 0
	s_nop 0
	v_mul_f32_e32 v19, v27, v27
	v_mul_f32_e32 v19, 0xbdd2d3e8, v19
	v_add_f32_e32 v19, 0xc0135761, v19
	v_mul_f32_e32 v19, v27, v19
	v_exp_f32_e32 v19, v19
	s_nop 0
	v_add_f32_e32 v19, 1.0, v19
	v_rcp_f32_e32 v20, v19
	s_nop 0
	v_mul_f32_e32 v41, v27, v20
	s_lshr_b32 s54, s89, 4
	s_and_b32 s54, s54, 0x78
	s_add_i32 s54, s54, s29
	v_mul_f32_e32 v18, v26, v26
	v_mul_f32_e32 v18, 0xbdd2d3e8, v18
	v_add_f32_e32 v18, 0xc0135761, v18
	v_mul_f32_e32 v18, v26, v18
	v_exp_f32_e32 v18, v18
	s_nop 0
	v_add_f32_e32 v18, 1.0, v18
	v_rcp_f32_e32 v19, v18
	s_nop 0
	v_mul_f32_e32 v40, v26, v19
	v_pk_mul_f32 v[18:19], v[40:41], v[40:41]
	s_mov_b32 s55, s9
	v_add_f32_e32 v17, v18, v17
	v_add_f32_e32 v17, v19, v17
	v_and_b32_e32 v19, 64, v165
	v_xor_b32_e32 v18, 16, v165
	v_add_u32_e32 v19, 64, v19
	v_cmp_lt_i32_e32 vcc, v18, v19
	s_lshl_b64 s[54:55], s[54:55], 14
	s_add_u32 s53, s36, s56
	v_cndmask_b32_e32 v18, v165, v18, vcc
	v_lshlrev_b32_e32 v18, 2, v18
	v_mov_b32_e32 v18, v17
	s_nop 1
	v_permlane16_swap_b32 v17, v18
	v_readlane_b32 s36, v254, 35
	s_addc_u32 s56, s36, s57
	s_add_u32 s54, s53, s54
	s_addc_u32 s55, s56, s55
	s_waitcnt lgkmcnt(0)
; __device__ __forceinline__ unsigned f2bf(float f) { unsigned u = __float_as_uint(f); return (u + 0x7fffu + ((u >> 16) & 1u)) >> 16; }
;     __device__ __forceinline__ void operator()(const f32x4 (&acc)[2][2][4][2], const pg8::Unit& u, int wr, int wc, int fr, int fq) const {
;     ...
;                     const float rn = rsqrtf(head_ssq(y) * (1.f / 64.f) + EPS);
;                     bf16_t* p = zvT + (((size_t)b * 16 + (s >> 7)) * 8 + g) * 8192 + (s & 127);
; #pragma unroll
;                     for (int i = 0; i < 16; ++i) { const int d = 32 * (i >> 3) + d0 + (i & 7); p[d * 128] = (bf16_t)f2bf(y[i] * rn * g_sgu[g * 64 + d]); }
	v_add_f32_e32 v17, v17, v18
	v_xor_b32_e32 v18, 32, v165
	v_cmp_lt_i32_e32 vcc, v18, v19
	s_mov_b64 s[56:57], s[40:41]
	s_nop 0
	v_cndmask_b32_e32 v18, v165, v18, vcc
	v_lshlrev_b32_e32 v18, 2, v18
	v_mov_b32_e32 v18, v17
	s_nop 1
	v_permlane32_swap_b32 v17, v18
	s_waitcnt lgkmcnt(0)
	v_add_f32_e32 v17, v17, v18
	v_fmamk_f32 v17, v17, 0x3c800000, v161
	v_cmp_gt_f32_e32 vcc, s61, v17
	v_mul_f32_e32 v18, 0x4b800000, v17
	s_nop 0
	v_cndmask_b32_e32 v17, v17, v18, vcc
	v_rsq_f32_e32 v17, v17
	s_nop 0
	v_mul_f32_e32 v18, 0x45800000, v17
	v_cndmask_b32_e32 v60, v17, v18, vcc
	v_and_b32_e32 v17, 0x6f, v24
	v_lshlrev_b32_e32 v136, 1, v17
	v_lshl_add_u64 v[42:43], s[54:55], 0, v[136:137]
	s_mov_b64 s[54:55], s[38:39]
	v_readlane_b32 s36, v254, 8
	v_or_b32_e32 v136, s27, v140
	v_readlane_b32 s37, v254, 9
	v_mul_f32_e32 v61, v16, v60
	v_readlane_b32 s50, v254, 22
	v_lshl_add_u64 v[20:21], v[136:137], 2, s[36:37]
	global_load_dwordx4 v[16:19], v[20:21], off offset:16
	s_nop 0
	global_load_dwordx4 v[20:23], v[20:21], off
	v_lshlrev_b32_e32 v136, 1, v142
	v_lshl_add_u64 v[62:63], v[42:43], 0, v[136:137]
	v_add_u32_e32 v136, s27, v140
	v_readlane_b32 s51, v254, 23
	v_readlane_b32 s38, v254, 10
	v_readlane_b32 s39, v254, 11
	v_readlane_b32 s40, v254, 12
	v_readlane_b32 s41, v254, 13
	v_readlane_b32 s42, v254, 14
	v_readlane_b32 s43, v254, 15
	v_readlane_b32 s49, v254, 21
	v_readlane_b32 s50, v254, 39
	s_mov_b64 s[38:39], s[54:55]
	s_mov_b64 s[42:43], s[58:59]
	s_mov_b64 s[40:41], s[56:57]
	v_readlane_b32 s49, v254, 41
	v_readlane_b32 s51, v254, 40
	s_mov_b64 s[54:55], 0
	v_readlane_b32 s44, v254, 16
	v_readlane_b32 s45, v254, 17
	v_readlane_b32 s46, v254, 18
	v_readlane_b32 s47, v254, 19
	v_readlane_b32 s48, v254, 20
	s_waitcnt vmcnt(0)
	v_mul_f32_e32 v20, v20, v61
	v_bfe_u32 v61, v20, 16, 1
	v_add3_u32 v20, v20, v61, s20
	global_store_short_d16_hi v[62:63], v20, off
	v_mul_f32_e32 v20, v25, v60
	v_mul_f32_e32 v20, v21, v20
	v_lshl_add_u64 v[62:63], v[136:137], 2, s[36:37]
	v_bfe_u32 v21, v20, 16, 1
	v_lshlrev_b32_e32 v136, 1, v144
	v_add3_u32 v25, v20, v21, s20
	v_lshl_add_u64 v[20:21], v[42:43], 0, v[136:137]
	global_store_short_d16_hi v[20:21], v25, off
	v_mul_f32_e32 v20, v53, v60
	v_mul_f32_e32 v20, v22, v20
	v_bfe_u32 v21, v20, 16, 1
	v_lshlrev_b32_e32 v136, 1, v146
	v_add3_u32 v22, v20, v21, s20
	v_lshl_add_u64 v[20:21], v[42:43], 0, v[136:137]
	global_store_short_d16_hi v[20:21], v22, off
	v_mul_f32_e32 v20, v54, v60
	v_mul_f32_e32 v20, v23, v20
	v_bfe_u32 v21, v20, 16, 1
	v_lshlrev_b32_e32 v136, 1, v148
	v_add3_u32 v22, v20, v21, s20
	v_lshl_add_u64 v[20:21], v[42:43], 0, v[136:137]
	global_store_short_d16_hi v[20:21], v22, off
	v_mul_f32_e32 v20, v55, v60
	v_mul_f32_e32 v16, v16, v20
	v_bfe_u32 v20, v16, 16, 1
	v_lshlrev_b32_e32 v136, 1, v150
	v_add3_u32 v16, v16, v20, s20
	v_lshl_add_u64 v[20:21], v[42:43], 0, v[136:137]
	global_store_short_d16_hi v[20:21], v16, off
	v_mul_f32_e32 v16, v57, v60
	v_mul_f32_e32 v16, v16, v17
	v_bfe_u32 v17, v16, 16, 1
	v_lshlrev_b32_e32 v136, 1, v152
	v_add3_u32 v20, v16, v17, s20
	v_lshl_add_u64 v[16:17], v[42:43], 0, v[136:137]
	global_store_short_d16_hi v[16:17], v20, off
	v_mul_f32_e32 v16, v58, v60
	v_mul_f32_e32 v16, v16, v18
	v_bfe_u32 v17, v16, 16, 1
	v_lshlrev_b32_e32 v136, 1, v154
	v_add3_u32 v18, v16, v17, s20
	v_lshl_add_u64 v[16:17], v[42:43], 0, v[136:137]
	global_store_short_d16_hi v[16:17], v18, off
	v_mul_f32_e32 v16, v59, v60
	v_mul_f32_e32 v16, v16, v19
	v_bfe_u32 v17, v16, 16, 1
	v_lshlrev_b32_e32 v136, 1, v156
	v_add3_u32 v18, v16, v17, s20
	v_lshl_add_u64 v[16:17], v[42:43], 0, v[136:137]
	global_store_short_d16_hi v[16:17], v18, off
	global_load_dwordx4 v[16:19], v[62:63], off offset:144
	s_nop 0
	global_load_dwordx4 v[20:23], v[62:63], off offset:128
	v_mul_f32_e32 v25, v34, v60
	v_lshlrev_b32_e32 v136, 1, v158
	v_lshl_add_u64 v[54:55], v[42:43], 0, v[136:137]
	v_lshlrev_b32_e32 v136, 1, v160
	s_waitcnt vmcnt(0)
	v_mul_f32_e32 v20, v25, v20
	v_bfe_u32 v25, v20, 16, 1
	v_add3_u32 v20, v20, v25, s20
	global_store_short_d16_hi v[54:55], v20, off
	v_mul_f32_e32 v20, v35, v60
	v_mul_f32_e32 v20, v20, v21
	v_bfe_u32 v21, v20, 16, 1
	v_add3_u32 v25, v20, v21, s20
	v_lshl_add_u64 v[20:21], v[42:43], 0, v[136:137]
	global_store_short_d16_hi v[20:21], v25, off
	v_mul_f32_e32 v20, v36, v60
	v_mul_f32_e32 v20, v20, v22
	v_bfe_u32 v21, v20, 16, 1
	v_lshlrev_b32_e32 v136, 1, v162
	v_add3_u32 v22, v20, v21, s20
	v_lshl_add_u64 v[20:21], v[42:43], 0, v[136:137]
	global_store_short_d16_hi v[20:21], v22, off
	v_mul_f32_e32 v20, v37, v60
	v_mul_f32_e32 v20, v20, v23
	v_bfe_u32 v21, v20, 16, 1
	v_lshlrev_b32_e32 v136, 1, v164
	v_add3_u32 v22, v20, v21, s20
	v_lshl_add_u64 v[20:21], v[42:43], 0, v[136:137]
	global_store_short_d16_hi v[20:21], v22, off
	v_mul_f32_e32 v20, v38, v60
	v_mul_f32_e32 v16, v20, v16
	v_bfe_u32 v20, v16, 16, 1
	v_add3_u32 v16, v16, v20, s20
	v_or_b32_e32 v20, 0x1200, v142
	v_lshlrev_b32_e32 v136, 1, v20
	v_lshl_add_u64 v[20:21], v[42:43], 0, v[136:137]
	global_store_short_d16_hi v[20:21], v16, off
	v_mul_f32_e32 v16, v39, v60
	v_mul_f32_e32 v16, v16, v17
	v_bfe_u32 v17, v16, 16, 1
	v_add3_u32 v20, v16, v17, s20
	v_or_b32_e32 v16, 0x1280, v142
	v_lshlrev_b32_e32 v136, 1, v16
	v_lshl_add_u64 v[16:17], v[42:43], 0, v[136:137]
	global_store_short_d16_hi v[16:17], v20, off
	v_mul_f32_e32 v16, v40, v60
	v_mul_f32_e32 v16, v16, v18
	v_bfe_u32 v17, v16, 16, 1
	v_add3_u32 v18, v16, v17, s20
	v_or_b32_e32 v16, 0x1300, v142
	v_lshlrev_b32_e32 v136, 1, v16
	v_lshl_add_u64 v[16:17], v[42:43], 0, v[136:137]
	global_store_short_d16_hi v[16:17], v18, off
	v_mul_f32_e32 v16, v41, v60
	v_mul_f32_e32 v16, v16, v19
	v_bfe_u32 v17, v16, 16, 1
	v_lshlrev_b32_e32 v136, 1, v172
	v_add3_u32 v18, v16, v17, s20
	v_lshl_add_u64 v[16:17], v[42:43], 0, v[136:137]
	global_store_short_d16_hi v[16:17], v18, off

;     __device__ __forceinline__ void operator()(const f32x4 (&acc)[2][2][4][2], const pg8::Unit& u, int wr, int wc, int fr, int fq) const {
;     ...
;                 if (cs < 8 || cs == 12 || cs == 13 || cs == 16 || cs == 17) {
;                     const float* gg = cs < 8 ? g_q : (cs < 14 ? g_k + 64 : g_k + 128);
;                     const float rn = rsqrtf(head_ssq(v) * (1.f / 64.f) + EPS) * (cs < 8 ? QSCALE : 1.f);
;                     float y[16];
; #pragma unroll
;                     for (int i = 0; i < 16; ++i) y[i] = v[i] * rn * gg[32 * (i >> 3) + d0 + (i & 7)];
;                     float r1[8], r2[8];
; #pragma unroll
;                     for (int i = 0; i < 8; ++i) { int di = d0 + i; asm volatile("" : "+v"(di));
;                         const float frev = __builtin_amdgcn_exp2f(-(float)di * (13.287712379549449f / 32.f)) * 0.15915494309189535f;
;                         float xr = (float)s * frev; xr -= __builtin_rintf(xr);
;                         const float c = __builtin_amdgcn_cosf(xr), sn = __builtin_amdgcn_sinf(xr); r1[i] = y[i] * c - y[8 + i] * sn; r2[i] = y[8 + i] * c + y[i] * sn; }
;                     if (cs < 8) {
;                         bf16_t* p = qn + (size_t)row * 512 + cs * 64 + d0; store8(p, y); store8(p + 32, y + 8);
;                         bf16_t* p2 = qr + (size_t)row * 512 + cs * 64 + d0; store8(p2, r1); store8(p2 + 32, r2);
;                     } else {
;                         bf16_t* p = (cs < 14 ? ksl : kwn) + ((size_t)(b * 2 + (cs & 1)) * 2048 + s) * 64 + d0; store8(p, r1); store8(p + 32, r2);
.LBB0_388:
	global_load_dwordx4 v[16:19], v167, s[54:55]
	global_load_dwordx4 v[20:23], v167, s[54:55] offset:16
	global_load_dwordx4 v[36:39], v167, s[54:55] offset:128
	global_load_dwordx4 v[40:43], v167, s[54:55] offset:144
	v_mul_f32_e32 v25, v46, v46
	v_fmac_f32_e32 v25, v45, v45
	v_fmac_f32_e32 v25, v47, v47
	v_fmac_f32_e32 v25, v48, v48
	v_fmac_f32_e32 v25, v49, v49
	v_fmac_f32_e32 v25, v50, v50
	v_fmac_f32_e32 v25, v51, v51
	v_pk_mul_f32 v[34:35], v[28:29], v[28:29]
	v_fmac_f32_e32 v25, v52, v52
	v_add_f32_e32 v25, v34, v25
	v_pk_mul_f32 v[54:55], v[32:33], v[32:33]
	v_add_f32_e32 v25, v35, v25
	v_add_f32_e32 v25, v54, v25
	v_pk_mul_f32 v[58:59], v[30:31], v[30:31]
	v_and_b32_e32 v57, 64, v165
	v_add_f32_e32 v25, v55, v25
	v_xor_b32_e32 v53, 16, v165
	v_add_u32_e32 v57, 64, v57
	v_add_f32_e32 v25, v58, v25
	v_pk_mul_f32 v[60:61], v[26:27], v[26:27]
	v_cmp_lt_i32_e32 vcc, v53, v57
	v_add_f32_e32 v25, v59, v25
	v_add_f32_e32 v25, v60, v25
	v_cndmask_b32_e32 v53, v165, v53, vcc
	v_lshlrev_b32_e32 v53, 2, v53
	v_add_f32_e32 v25, v61, v25
	v_mov_b32_e32 v34, v25
	s_nop 1
	v_permlane16_swap_b32 v25, v34
	v_xor_b32_e32 v35, 32, v165
	v_cmp_lt_i32_e32 vcc, v35, v57
	v_cvt_f32_u32_e32 v53, v44
	s_mov_b64 s[54:55], -1
	v_cndmask_b32_e32 v35, v165, v35, vcc
	v_lshlrev_b32_e32 v35, 2, v35
	s_waitcnt lgkmcnt(0)
	v_add_f32_e32 v25, v25, v34
	v_mov_b32_e32 v34, v25
	s_nop 1
	v_permlane32_swap_b32 v25, v34
	v_mov_b32_e32 v35, v140
	s_waitcnt lgkmcnt(0)
	v_add_f32_e32 v25, v25, v34
	v_fmamk_f32 v25, v25, 0x3c800000, v161
	v_mul_f32_e32 v34, 0x4b800000, v25
	v_cmp_gt_f32_e32 vcc, s61, v25
	v_cvt_f32_i32_e32 v35, v35
	s_nop 0
	v_cndmask_b32_e32 v25, v25, v34, vcc
	v_rsq_f32_e32 v25, v25
	v_mul_f32_e32 v34, 0xbed49a78, v35
	v_exp_f32_e32 v35, v34
	v_mul_f32_e32 v34, 0x45800000, v25
	v_cndmask_b32_e32 v25, v25, v34, vcc
	v_mul_f32_e32 v25, s53, v25
	v_mul_f32_e32 v34, v45, v25
	v_mul_f32_e32 v45, v46, v25
	v_mul_f32_e32 v46, v47, v25
	v_mul_f32_e32 v47, v48, v25
	v_mul_f32_e32 v48, v49, v25
	v_mul_f32_e32 v49, v50, v25
	v_mul_f32_e32 v50, v51, v25
	v_mul_f32_e32 v51, v52, v25
	v_mul_f32_e32 v52, v28, v25
	v_mul_f32_e32 v54, v29, v25
	v_mul_f32_e32 v55, v32, v25
	v_mul_f32_e32 v57, v33, v25
	v_mul_f32_e32 v58, v30, v25
	v_mul_f32_e32 v59, v31, v25
	v_mul_f32_e32 v60, v26, v25
	s_and_b64 vcc, exec, s[6:7]
	s_waitcnt vmcnt(3)
	v_mul_f32_e32 v32, v16, v34
	v_mul_f32_e32 v16, v27, v25
	v_mul_f32_e32 v25, 0.15915494, v35
	v_mul_f32_e32 v27, v25, v53
	v_rndne_f32_e32 v27, v27
	v_fma_f32 v25, v25, v53, -v27
	v_mov_b32_e32 v27, v141
	s_waitcnt vmcnt(2)
	v_mul_f32_e32 v31, v21, v49
	v_cvt_f32_i32_e32 v27, v27
	s_waitcnt vmcnt(1)
	v_mul_f32_e32 v21, v36, v52
	v_sin_f32_e32 v36, v25
	v_cos_f32_e32 v25, v25
	v_mul_f32_e32 v27, 0xbed49a78, v27
	v_mul_f32_e32 v29, v23, v51
	v_mul_f32_e32 v23, v37, v54
	v_exp_f32_e32 v37, v27
	s_waitcnt vmcnt(0)
	v_mul_f32_e32 v35, v16, v43
	v_mul_f32_e32 v16, v21, v36
	v_fma_f32 v27, v32, v25, -v16
	v_mul_f32_e32 v16, v32, v36
	v_fmac_f32_e32 v16, v21, v25
	v_mul_f32_e32 v25, 0.15915494, v37
	v_mov_b32_e32 v37, v143
	v_mul_f32_e32 v33, v19, v47
	v_cvt_f32_i32_e32 v37, v37
	v_mul_f32_e32 v19, v55, v38
	v_mul_f32_e32 v26, v22, v50
	v_mul_f32_e32 v22, v57, v39
	v_mul_f32_e32 v37, 0xbed49a78, v37
	v_exp_f32_e32 v38, v37
	v_mul_f32_e32 v36, v25, v53
	v_rndne_f32_e32 v36, v36
	v_fma_f32 v25, v25, v53, -v36
	v_mul_f32_e32 v38, 0.15915494, v38
	v_mul_f32_e32 v39, v38, v53
	v_rndne_f32_e32 v39, v39
	v_fma_f32 v38, v38, v53, -v39
	v_mov_b32_e32 v39, v145
	v_sin_f32_e32 v36, v25
	v_cos_f32_e32 v25, v25
	v_cvt_f32_i32_e32 v39, v39
	v_mul_f32_e32 v34, v17, v45
	v_mul_f32_e32 v30, v18, v46
	v_mul_f32_e32 v18, v58, v40
	v_mul_f32_e32 v37, v23, v36
	v_mul_f32_e32 v36, v34, v36
	v_sin_f32_e32 v40, v38
	v_fma_f32 v37, v34, v25, -v37
	v_fmac_f32_e32 v36, v23, v25
	v_cos_f32_e32 v25, v38
	v_mul_f32_e32 v39, 0xbed49a78, v39
	v_mul_f32_e32 v28, v20, v48
	v_mul_f32_e32 v20, v59, v41
	v_exp_f32_e32 v41, v39
	v_mul_f32_e32 v38, v19, v40
	v_fma_f32 v39, v30, v25, -v38
	v_mul_f32_e32 v38, v30, v40
	v_fmac_f32_e32 v38, v19, v25
	v_mul_f32_e32 v25, 0.15915494, v41
	v_mov_b32_e32 v41, v147
	v_mul_f32_e32 v17, v60, v42
	v_cvt_f32_i32_e32 v41, v41
	v_mul_f32_e32 v40, v25, v53
	v_rndne_f32_e32 v40, v40
	v_fma_f32 v25, v25, v53, -v40
	v_mul_f32_e32 v41, 0xbed49a78, v41
	v_exp_f32_e32 v42, v41
	v_sin_f32_e32 v40, v25
	v_cos_f32_e32 v25, v25
	v_mov_b32_e32 v49, v157
	v_mul_f32_e32 v42, 0.15915494, v42
	v_mul_f32_e32 v43, v42, v53
	v_rndne_f32_e32 v43, v43
	v_fma_f32 v42, v42, v53, -v43
	v_mov_b32_e32 v43, v153
	v_mul_f32_e32 v41, v22, v40
	v_cvt_f32_i32_e32 v43, v43
	v_mul_f32_e32 v40, v33, v40
	v_sin_f32_e32 v45, v42
	v_fma_f32 v41, v33, v25, -v41
	v_fmac_f32_e32 v40, v22, v25
	v_cos_f32_e32 v25, v42
	v_mul_f32_e32 v43, 0xbed49a78, v43
	v_exp_f32_e32 v46, v43
	v_mul_f32_e32 v42, v18, v45
	v_fma_f32 v43, v28, v25, -v42
	v_mul_f32_e32 v42, v28, v45
	v_fmac_f32_e32 v42, v18, v25
	v_mul_f32_e32 v25, 0.15915494, v46
	v_mov_b32_e32 v46, v155
	v_mul_f32_e32 v45, v25, v53
	v_cvt_f32_i32_e32 v46, v46
	v_cvt_f32_i32_e32 v49, v49
	v_rndne_f32_e32 v45, v45
	v_fma_f32 v25, v25, v53, -v45
	v_mul_f32_e32 v46, 0xbed49a78, v46
	v_exp_f32_e32 v47, v46
	v_sin_f32_e32 v45, v25
	v_cos_f32_e32 v25, v25
	v_mul_f32_e32 v49, 0xbed49a78, v49
	v_mul_f32_e32 v47, 0.15915494, v47
	v_mul_f32_e32 v48, v47, v53
	v_rndne_f32_e32 v48, v48
	v_fma_f32 v47, v47, v53, -v48
	v_cos_f32_e32 v48, v47
	v_sin_f32_e32 v47, v47
	v_exp_f32_e32 v50, v49
	v_mul_f32_e32 v46, v20, v45
	v_mul_f32_e32 v45, v31, v45
	v_fma_f32 v46, v31, v25, -v46
	v_fmac_f32_e32 v45, v20, v25
	v_mul_f32_e32 v25, v17, v47
	v_fma_f32 v49, v26, v48, -v25
	v_mul_f32_e32 v25, 0.15915494, v50
	v_mul_f32_e32 v50, v25, v53
	v_rndne_f32_e32 v50, v50
	v_fma_f32 v25, v25, v53, -v50
	v_sin_f32_e32 v51, v25
	v_cos_f32_e32 v25, v25
	v_mul_f32_e32 v47, v26, v47
	v_fmac_f32_e32 v47, v17, v48
	v_mul_f32_e32 v48, v35, v51
	v_fma_f32 v50, v29, v25, -v48
	v_mul_f32_e32 v48, v29, v51
	v_fmac_f32_e32 v48, v35, v25
	s_cbranch_vccnz .LBB0_390
	s_and_b64 s[54:55], s[10:11], exec
	s_cselect_b32 s53, s77, s76
	s_cselect_b32 s56, s74, s75
	s_lshl_b32 s54, s52, 1
	s_or_b32 s54, s54, s97
	s_ashr_i32 s55, s54, 31
	s_lshl_b64 s[54:55], s[54:55], 18
	s_add_u32 s54, s56, s54
	s_addc_u32 s55, s53, s55
	v_lshlrev_b32_e32 v136, 7, v44
	v_lshl_add_u64 v[52:53], s[54:55], 0, v[136:137]
	v_lshlrev_b32_e32 v136, 1, v140
	v_lshl_add_u64 v[58:59], v[52:53], 0, v[136:137]
	v_cvt_pk_bf16_f32 v52, v27, v37
	v_cvt_pk_bf16_f32 v53, v39, v41
	v_cvt_pk_bf16_f32 v54, v43, v46
	v_cvt_pk_bf16_f32 v55, v49, v50
	s_mov_b64 s[54:55], 0
	global_store_dwordx4 v[58:59], v[52:55], off
	s_nop 1
	v_cvt_pk_bf16_f32 v52, v16, v36
	v_cvt_pk_bf16_f32 v53, v38, v40
	v_cvt_pk_bf16_f32 v54, v42, v45
	v_cvt_pk_bf16_f32 v55, v47, v48
	global_store_dwordx4 v[58:59], v[52:55], off offset:64

; __device__ __forceinline__ float gelu_tanh(float x) {
;     const float u = 0.7978845608028654f * (x + 0.044715f * x * x * x);
;     return x / (1.f + __expf(-2.f * u));
; }
; __device__ __forceinline__ float head_ssq(const float (&v)[16]) {
;     float s = 0.f;
; #pragma unroll
;     for (int i = 0; i < 16; ++i) s += v[i] * v[i];
;     s += __shfl_xor(s, 16); s += __shfl_xor(s, 32);
;     return s;
.LBB0_401:
	s_andn2_b64 vcc, exec, s[72:73]
	s_mov_b64 s[50:51], -1
	s_cbranch_vccnz .LBB0_417
	s_andn2_b64 vcc, exec, s[70:71]
	s_mov_b64 s[48:49], -1
	s_cbranch_vccnz .LBB0_414
	s_andn2_b64 vcc, exec, s[42:43]
	s_mov_b64 s[46:47], -1
	s_cbranch_vccnz .LBB0_411
	s_andn2_b64 vcc, exec, s[40:41]
	s_mov_b64 s[44:45], -1
	s_cbranch_vccnz .LBB0_406
	s_ashr_i32 s53, s52, 31
	s_lshl_b64 s[46:47], s[52:53], 21
	v_readlane_b32 s36, v254, 35
	s_mov_b64 s[54:55], s[38:39]
	v_mul_f32_e32 v0, v36, v36
	v_mul_f32_e32 v0, 0xbdd2d3e8, v0
	v_add_f32_e32 v0, 0xc0135761, v0
	v_mul_f32_e32 v0, v36, v0
	v_exp_f32_e32 v0, v0
	s_nop 0
	v_add_f32_e32 v0, 1.0, v0
	v_rcp_f32_e32 v1, v0
	s_nop 0
	v_mul_f32_e32 v0, v36, v1
	s_nop 0
	s_nop 0
	v_mul_f32_e32 v1, v35, v35
	v_mul_f32_e32 v1, 0xbdd2d3e8, v1
	v_add_f32_e32 v1, 0xc0135761, v1
	v_mul_f32_e32 v1, v35, v1
	v_exp_f32_e32 v1, v1
	s_nop 0
	v_add_f32_e32 v1, 1.0, v1
	v_rcp_f32_e32 v2, v1
	s_nop 0
	v_mul_f32_e32 v9, v35, v2
	s_nop 0
	s_nop 0
	v_mul_f32_e32 v1, v34, v34
	v_mul_f32_e32 v1, 0xbdd2d3e8, v1
	v_add_f32_e32 v1, 0xc0135761, v1
	v_mul_f32_e32 v1, v34, v1
	v_exp_f32_e32 v1, v1
	s_nop 0
	v_add_f32_e32 v1, 1.0, v1
	v_rcp_f32_e32 v2, v1
	s_nop 0
	v_mul_f32_e32 v37, v34, v2
	s_nop 0
	s_nop 0
	v_mul_f32_e32 v1, v33, v33
	v_mul_f32_e32 v1, 0xbdd2d3e8, v1
	v_add_f32_e32 v1, 0xc0135761, v1
	v_mul_f32_e32 v1, v33, v1
	v_exp_f32_e32 v1, v1
	s_nop 0
	v_add_f32_e32 v1, 1.0, v1
	v_rcp_f32_e32 v2, v1
	s_nop 0
	v_mul_f32_e32 v38, v33, v2
	s_nop 0
	s_nop 0
	v_mul_f32_e32 v1, v32, v32
	v_mul_f32_e32 v1, 0xbdd2d3e8, v1
	v_add_f32_e32 v1, 0xc0135761, v1
	v_mul_f32_e32 v1, v32, v1
	v_exp_f32_e32 v1, v1
	s_nop 0
	v_add_f32_e32 v1, 1.0, v1
	v_rcp_f32_e32 v2, v1
	s_nop 0
	v_mul_f32_e32 v39, v32, v2
	s_nop 0
	s_nop 0
	v_mul_f32_e32 v1, v31, v31
	v_mul_f32_e32 v1, 0xbdd2d3e8, v1
	v_add_f32_e32 v1, 0xc0135761, v1
	v_mul_f32_e32 v1, v31, v1
	v_exp_f32_e32 v1, v1
	s_nop 0
	v_add_f32_e32 v1, 1.0, v1
	v_rcp_f32_e32 v2, v1
	s_nop 0
	v_mul_f32_e32 v40, v31, v2
	s_nop 0
	s_nop 0
	v_mul_f32_e32 v1, v30, v30
	v_mul_f32_e32 v1, 0xbdd2d3e8, v1
	v_add_f32_e32 v1, 0xc0135761, v1
	v_mul_f32_e32 v1, v30, v1
	v_exp_f32_e32 v1, v1
	s_nop 0
	v_add_f32_e32 v1, 1.0, v1
	v_rcp_f32_e32 v2, v1
	s_nop 0
	v_mul_f32_e32 v41, v30, v2
	s_nop 0
	s_nop 0
	v_mul_f32_e32 v1, v29, v29
	v_mul_f32_e32 v1, 0xbdd2d3e8, v1
	v_add_f32_e32 v1, 0xc0135761, v1
	v_mul_f32_e32 v1, v29, v1
	v_exp_f32_e32 v1, v1
	s_nop 0
	v_add_f32_e32 v1, 1.0, v1
	v_rcp_f32_e32 v2, v1
	s_nop 0
	v_mul_f32_e32 v42, v29, v2
	v_mul_f32_e32 v3, v17, v17
	v_mul_f32_e32 v3, 0xbdd2d3e8, v3
	v_add_f32_e32 v3, 0xc0135761, v3
	v_mul_f32_e32 v3, v17, v3
	v_exp_f32_e32 v3, v3
	s_nop 0
	v_add_f32_e32 v3, 1.0, v3
	v_rcp_f32_e32 v18, v3
	s_nop 0
	v_mul_f32_e32 v19, v17, v18
	v_mul_f32_e32 v1, v9, v9
	v_fmac_f32_e32 v1, v0, v0
	v_fmac_f32_e32 v1, v37, v37
	v_fmac_f32_e32 v1, v38, v38
	v_fmac_f32_e32 v1, v39, v39
	v_fmac_f32_e32 v1, v40, v40
	v_fmac_f32_e32 v1, v41, v41
	v_mul_f32_e32 v2, v16, v16
	v_mul_f32_e32 v2, 0xbdd2d3e8, v2
	v_add_f32_e32 v2, 0xc0135761, v2
	v_mul_f32_e32 v2, v16, v2
	v_exp_f32_e32 v2, v2
	s_nop 0
	v_add_f32_e32 v2, 1.0, v2
	v_rcp_f32_e32 v3, v2
	s_nop 0
	v_mul_f32_e32 v18, v16, v3
	v_fmac_f32_e32 v1, v42, v42
	v_pk_mul_f32 v[2:3], v[18:19], v[18:19]
	s_nop 0
	v_add_f32_e32 v1, v2, v1
	v_add_f32_e32 v1, v3, v1
	s_nop 0
	s_nop 0
	v_mul_f32_e32 v3, v15, v15
	v_mul_f32_e32 v3, 0xbdd2d3e8, v3
	v_add_f32_e32 v3, 0xc0135761, v3
	v_mul_f32_e32 v3, v15, v3
	v_exp_f32_e32 v3, v3
	s_nop 0
	v_add_f32_e32 v3, 1.0, v3
	v_rcp_f32_e32 v4, v3
	s_nop 0
	v_mul_f32_e32 v21, v15, v4
	s_nop 0
	v_mul_f32_e32 v2, v14, v14
	v_mul_f32_e32 v2, 0xbdd2d3e8, v2
	v_add_f32_e32 v2, 0xc0135761, v2
	v_mul_f32_e32 v2, v14, v2
	v_exp_f32_e32 v2, v2
	s_nop 0
	v_add_f32_e32 v2, 1.0, v2
	v_rcp_f32_e32 v3, v2
	s_nop 0
	v_mul_f32_e32 v20, v14, v3
	v_pk_mul_f32 v[2:3], v[20:21], v[20:21]
	s_nop 0
	v_add_f32_e32 v1, v2, v1
	v_add_f32_e32 v1, v3, v1
	s_nop 0
	s_nop 0
	v_mul_f32_e32 v3, v13, v13
	v_mul_f32_e32 v3, 0xbdd2d3e8, v3
	v_add_f32_e32 v3, 0xc0135761, v3
	v_mul_f32_e32 v3, v13, v3
	v_exp_f32_e32 v3, v3
	s_nop 0
	v_add_f32_e32 v3, 1.0, v3
	v_rcp_f32_e32 v4, v3
	s_nop 0
	v_mul_f32_e32 v23, v13, v4
	s_nop 0
	v_mul_f32_e32 v2, v12, v12
	v_mul_f32_e32 v2, 0xbdd2d3e8, v2
	v_add_f32_e32 v2, 0xc0135761, v2
	v_mul_f32_e32 v2, v12, v2
	v_exp_f32_e32 v2, v2
	s_nop 0
	v_add_f32_e32 v2, 1.0, v2
	v_rcp_f32_e32 v3, v2
	s_nop 0
	v_mul_f32_e32 v22, v12, v3
	v_pk_mul_f32 v[2:3], v[22:23], v[22:23]
	s_nop 0
	v_add_f32_e32 v1, v2, v1
	v_add_f32_e32 v1, v3, v1
	s_nop 0
	s_nop 0
	v_mul_f32_e32 v3, v11, v11
	v_mul_f32_e32 v3, 0xbdd2d3e8, v3
	v_add_f32_e32 v3, 0xc0135761, v3
	v_mul_f32_e32 v3, v11, v3
	v_exp_f32_e32 v3, v3
	s_nop 0
	v_add_f32_e32 v3, 1.0, v3
	v_rcp_f32_e32 v4, v3
	s_nop 0
	v_mul_f32_e32 v25, v11, v4
	s_lshr_b32 s44, s89, 4
	s_and_b32 s44, s44, 0x78
	s_add_i32 s44, s44, s29
	v_mul_f32_e32 v2, v10, v10
	v_mul_f32_e32 v2, 0xbdd2d3e8, v2
	v_add_f32_e32 v2, 0xc0135761, v2
	v_mul_f32_e32 v2, v10, v2
	v_exp_f32_e32 v2, v2
	s_nop 0
	v_add_f32_e32 v2, 1.0, v2
	v_rcp_f32_e32 v3, v2
	s_nop 0
	v_mul_f32_e32 v24, v10, v3
	v_pk_mul_f32 v[2:3], v[24:25], v[24:25]
	s_mov_b32 s45, s9
	v_add_f32_e32 v1, v2, v1
	v_add_f32_e32 v1, v3, v1
	v_and_b32_e32 v3, 64, v165
	v_xor_b32_e32 v2, 16, v165
	v_add_u32_e32 v3, 64, v3
	v_cmp_lt_i32_e32 vcc, v2, v3
	s_lshl_b64 s[44:45], s[44:45], 14
	v_readlane_b32 s29, v254, 33
	v_cndmask_b32_e32 v2, v165, v2, vcc
	v_lshlrev_b32_e32 v2, 2, v2
	v_mov_b32_e32 v2, v1
	s_nop 1
	v_permlane16_swap_b32 v1, v2
	s_add_u32 s29, s29, s46
	s_addc_u32 s46, s36, s47
	s_add_u32 s44, s29, s44
	s_addc_u32 s45, s46, s45
	s_waitcnt lgkmcnt(0)
; __device__ __forceinline__ unsigned f2bf(float f) { unsigned u = __float_as_uint(f); return (u + 0x7fffu + ((u >> 16) & 1u)) >> 16; }
;     __device__ __forceinline__ void operator()(const f32x4 (&acc)[2][2][4][2], const pg8::Unit& u, int wr, int wc, int fr, int fq) const {
;     ...
;                     const float rn = rsqrtf(head_ssq(y) * (1.f / 64.f) + EPS);
;                     bf16_t* p = zvT + (((size_t)b * 16 + (s >> 7)) * 8 + g) * 8192 + (s & 127);
; #pragma unroll
;                     for (int i = 0; i < 16; ++i) { const int d = 32 * (i >> 3) + d0 + (i & 7); p[d * 128] = (bf16_t)f2bf(y[i] * rn * g_sgu[g * 64 + d]); }
	v_add_f32_e32 v1, v1, v2
	v_xor_b32_e32 v2, 32, v165
	v_cmp_lt_i32_e32 vcc, v2, v3
	s_nop 1
	v_cndmask_b32_e32 v2, v165, v2, vcc
	v_lshlrev_b32_e32 v2, 2, v2
	v_mov_b32_e32 v2, v1
	s_nop 1
	v_permlane32_swap_b32 v1, v2
	s_waitcnt lgkmcnt(0)
	v_add_f32_e32 v1, v1, v2
	v_fmamk_f32 v1, v1, 0x3c800000, v161
	v_cmp_gt_f32_e32 vcc, s61, v1
	v_mul_f32_e32 v2, 0x4b800000, v1
	s_nop 0
	v_cndmask_b32_e32 v1, v1, v2, vcc
	v_rsq_f32_e32 v1, v1
	s_nop 0
	v_mul_f32_e32 v2, 0x45800000, v1
	v_cndmask_b32_e32 v43, v1, v2, vcc
	v_and_b32_e32 v1, 0x7f, v8
	v_lshlrev_b32_e32 v136, 1, v1
	v_lshl_add_u64 v[26:27], s[44:45], 0, v[136:137]
	v_readlane_b32 s36, v254, 8
	v_or_b32_e32 v136, s27, v140
	v_readlane_b32 s37, v254, 9
	v_mul_f32_e32 v44, v0, v43
	v_readlane_b32 s38, v254, 10
	v_lshl_add_u64 v[4:5], v[136:137], 2, s[36:37]
	global_load_dwordx4 v[0:3], v[4:5], off offset:16
	s_nop 0
	global_load_dwordx4 v[4:7], v[4:5], off
	v_lshlrev_b32_e32 v136, 1, v142
	v_readlane_b32 s39, v254, 11
	v_readlane_b32 s44, v254, 16
	v_readlane_b32 s45, v254, 17
	s_mov_b64 s[38:39], s[54:55]
	s_mov_b64 s[44:45], 0
	v_readlane_b32 s40, v254, 12
	v_readlane_b32 s41, v254, 13
	v_readlane_b32 s42, v254, 14
	v_readlane_b32 s43, v254, 15
	v_readlane_b32 s46, v254, 18
	v_readlane_b32 s47, v254, 19
	v_readlane_b32 s48, v254, 20
	v_readlane_b32 s49, v254, 21
	v_readlane_b32 s50, v254, 22
	v_readlane_b32 s51, v254, 23
	s_waitcnt vmcnt(0)
	v_mul_f32_e32 v4, v4, v44
	v_bfe_u32 v44, v4, 16, 1
	v_add3_u32 v4, v4, v44, s20
	v_lshl_add_u64 v[44:45], v[26:27], 0, v[136:137]
	global_store_short_d16_hi v[44:45], v4, off
	v_mul_f32_e32 v4, v9, v43
	v_add_u32_e32 v136, s27, v140
	v_mul_f32_e32 v4, v5, v4
	v_lshl_add_u64 v[44:45], v[136:137], 2, s[36:37]
	v_bfe_u32 v5, v4, 16, 1
	v_lshlrev_b32_e32 v136, 1, v144
	v_add3_u32 v9, v4, v5, s20
	v_lshl_add_u64 v[4:5], v[26:27], 0, v[136:137]
	global_store_short_d16_hi v[4:5], v9, off
	v_mul_f32_e32 v4, v37, v43
	v_mul_f32_e32 v4, v6, v4
	v_bfe_u32 v5, v4, 16, 1
	v_lshlrev_b32_e32 v136, 1, v146
	v_add3_u32 v6, v4, v5, s20
	v_lshl_add_u64 v[4:5], v[26:27], 0, v[136:137]
	global_store_short_d16_hi v[4:5], v6, off
	v_mul_f32_e32 v4, v38, v43
	v_mul_f32_e32 v4, v7, v4
	v_bfe_u32 v5, v4, 16, 1
	v_lshlrev_b32_e32 v136, 1, v148
	v_add3_u32 v6, v4, v5, s20
	v_lshl_add_u64 v[4:5], v[26:27], 0, v[136:137]
	global_store_short_d16_hi v[4:5], v6, off
	v_mul_f32_e32 v4, v39, v43
	v_mul_f32_e32 v0, v0, v4
	v_bfe_u32 v4, v0, 16, 1
	v_lshlrev_b32_e32 v136, 1, v150
	v_add3_u32 v0, v0, v4, s20
	v_lshl_add_u64 v[4:5], v[26:27], 0, v[136:137]
	global_store_short_d16_hi v[4:5], v0, off
	v_mul_f32_e32 v0, v40, v43
	v_mul_f32_e32 v0, v0, v1
	v_bfe_u32 v1, v0, 16, 1
	v_lshlrev_b32_e32 v136, 1, v152
	v_add3_u32 v4, v0, v1, s20
	v_lshl_add_u64 v[0:1], v[26:27], 0, v[136:137]
	global_store_short_d16_hi v[0:1], v4, off
	v_mul_f32_e32 v0, v41, v43
	v_mul_f32_e32 v0, v0, v2
	v_bfe_u32 v1, v0, 16, 1
	v_lshlrev_b32_e32 v136, 1, v154
	v_add3_u32 v2, v0, v1, s20
	v_lshl_add_u64 v[0:1], v[26:27], 0, v[136:137]
	global_store_short_d16_hi v[0:1], v2, off
	v_mul_f32_e32 v0, v42, v43
	v_mul_f32_e32 v0, v0, v3
	v_bfe_u32 v1, v0, 16, 1
	v_lshlrev_b32_e32 v136, 1, v156
	v_add3_u32 v2, v0, v1, s20
	v_lshl_add_u64 v[0:1], v[26:27], 0, v[136:137]
	global_store_short_d16_hi v[0:1], v2, off
	global_load_dwordx4 v[0:3], v[44:45], off offset:144
	s_nop 0
	global_load_dwordx4 v[4:7], v[44:45], off offset:128
	v_mul_f32_e32 v9, v18, v43
	v_lshlrev_b32_e32 v136, 1, v158
	v_lshl_add_u64 v[38:39], v[26:27], 0, v[136:137]
	v_lshlrev_b32_e32 v136, 1, v160
	s_waitcnt vmcnt(0)
	v_mul_f32_e32 v4, v9, v4
	v_bfe_u32 v9, v4, 16, 1
	v_add3_u32 v4, v4, v9, s20
	global_store_short_d16_hi v[38:39], v4, off
	v_mul_f32_e32 v4, v19, v43
	v_mul_f32_e32 v4, v4, v5
	v_bfe_u32 v5, v4, 16, 1
	v_add3_u32 v9, v4, v5, s20
	v_lshl_add_u64 v[4:5], v[26:27], 0, v[136:137]
	global_store_short_d16_hi v[4:5], v9, off
	v_mul_f32_e32 v4, v20, v43
	v_mul_f32_e32 v4, v4, v6
	v_bfe_u32 v5, v4, 16, 1
	v_lshlrev_b32_e32 v136, 1, v162
	v_add3_u32 v6, v4, v5, s20
	v_lshl_add_u64 v[4:5], v[26:27], 0, v[136:137]
	global_store_short_d16_hi v[4:5], v6, off
	v_mul_f32_e32 v4, v21, v43
	v_mul_f32_e32 v4, v4, v7
	v_bfe_u32 v5, v4, 16, 1
	v_lshlrev_b32_e32 v136, 1, v164
	v_add3_u32 v6, v4, v5, s20
	v_lshl_add_u64 v[4:5], v[26:27], 0, v[136:137]
	global_store_short_d16_hi v[4:5], v6, off
	v_mul_f32_e32 v4, v22, v43
	v_mul_f32_e32 v0, v4, v0
	v_bfe_u32 v4, v0, 16, 1
	v_add3_u32 v0, v0, v4, s20
	v_or_b32_e32 v4, 0x1200, v142
	v_lshlrev_b32_e32 v136, 1, v4
	v_lshl_add_u64 v[4:5], v[26:27], 0, v[136:137]
	global_store_short_d16_hi v[4:5], v0, off
	v_mul_f32_e32 v0, v23, v43
	v_mul_f32_e32 v0, v0, v1
	v_bfe_u32 v1, v0, 16, 1
	v_add3_u32 v4, v0, v1, s20
	v_or_b32_e32 v0, 0x1280, v142
	v_lshlrev_b32_e32 v136, 1, v0
	v_lshl_add_u64 v[0:1], v[26:27], 0, v[136:137]
	global_store_short_d16_hi v[0:1], v4, off
	v_mul_f32_e32 v0, v24, v43
	v_mul_f32_e32 v0, v0, v2
	v_bfe_u32 v1, v0, 16, 1
	v_add3_u32 v2, v0, v1, s20
	v_or_b32_e32 v0, 0x1300, v142
	v_lshlrev_b32_e32 v136, 1, v0
	v_lshl_add_u64 v[0:1], v[26:27], 0, v[136:137]
	global_store_short_d16_hi v[0:1], v2, off
	v_mul_f32_e32 v0, v25, v43
	v_mul_f32_e32 v0, v0, v3
	v_bfe_u32 v1, v0, 16, 1
	v_lshlrev_b32_e32 v136, 1, v172
	v_add3_u32 v2, v0, v1, s20
	v_lshl_add_u64 v[0:1], v[26:27], 0, v[136:137]
	global_store_short_d16_hi v[0:1], v2, off

;     __device__ __forceinline__ void operator()(const f32x4 (&acc)[2][2][4][2], const pg8::Unit& u, int wr, int wc, int fr, int fq) const {
;     ...
;                 if (cs < 8 || cs == 12 || cs == 13 || cs == 16 || cs == 17) {
;                     const float* gg = cs < 8 ? g_q : (cs < 14 ? g_k + 64 : g_k + 128);
;                     const float rn = rsqrtf(head_ssq(v) * (1.f / 64.f) + EPS) * (cs < 8 ? QSCALE : 1.f);
;                     float y[16];
; #pragma unroll
;                     for (int i = 0; i < 16; ++i) y[i] = v[i] * rn * gg[32 * (i >> 3) + d0 + (i & 7)];
;                     float r1[8], r2[8];
; #pragma unroll
;                     for (int i = 0; i < 8; ++i) { int di = d0 + i; asm volatile("" : "+v"(di));
;                         const float frev = __builtin_amdgcn_exp2f(-(float)di * (13.287712379549449f / 32.f)) * 0.15915494309189535f;
;                         float xr = (float)s * frev; xr -= __builtin_rintf(xr);
;                         const float c = __builtin_amdgcn_cosf(xr), sn = __builtin_amdgcn_sinf(xr); r1[i] = y[i] * c - y[8 + i] * sn; r2[i] = y[8 + i] * c + y[i] * sn; }
;                     if (cs < 8) {
;                         bf16_t* p = qn + (size_t)row * 512 + cs * 64 + d0; store8(p, y); store8(p + 32, y + 8);
;                         bf16_t* p2 = qr + (size_t)row * 512 + cs * 64 + d0; store8(p2, r1); store8(p2 + 32, r2);
;                     } else {
;                         bf16_t* p = (cs < 14 ? ksl : kwn) + ((size_t)(b * 2 + (cs & 1)) * 2048 + s) * 64 + d0; store8(p, r1); store8(p + 32, r2);
.LBB0_421:
	global_load_dwordx4 v[18:21], v167, s[40:41] offset:16
	global_load_dwordx4 v[4:7], v167, s[40:41]
	v_mul_f32_e32 v2, v35, v35
	v_fmac_f32_e32 v2, v36, v36
	v_fmac_f32_e32 v2, v34, v34
	v_fmac_f32_e32 v2, v33, v33
	v_fmac_f32_e32 v2, v32, v32
	v_fmac_f32_e32 v2, v31, v31
	v_fmac_f32_e32 v2, v30, v30
	v_fmac_f32_e32 v2, v29, v29
	v_pk_mul_f32 v[0:1], v[16:17], v[16:17]
	s_nop 0
	v_add_f32_e32 v0, v0, v2
	v_add_f32_e32 v2, v1, v0
	v_pk_mul_f32 v[0:1], v[14:15], v[14:15]
	s_nop 0
	v_add_f32_e32 v0, v0, v2
	v_add_f32_e32 v2, v1, v0
	v_pk_mul_f32 v[0:1], v[12:13], v[12:13]
	s_nop 0
	v_add_f32_e32 v0, v0, v2
	v_add_f32_e32 v2, v1, v0
	v_pk_mul_f32 v[0:1], v[10:11], v[10:11]
	s_nop 0
	v_add_f32_e32 v0, v0, v2
	v_and_b32_e32 v2, 64, v165
	v_add_f32_e32 v0, v1, v0
	v_xor_b32_e32 v1, 16, v165
	v_add_u32_e32 v2, 64, v2
	v_cmp_lt_i32_e32 vcc, v1, v2
	s_nop 1
	v_cndmask_b32_e32 v1, v165, v1, vcc
	v_lshlrev_b32_e32 v1, 2, v1
	v_mov_b32_e32 v1, v0
	s_nop 1
	v_permlane16_swap_b32 v0, v1
	s_waitcnt lgkmcnt(0)
	v_add_f32_e32 v0, v0, v1
	v_xor_b32_e32 v1, 32, v165
	v_cmp_lt_i32_e32 vcc, v1, v2
	s_nop 1
	v_cndmask_b32_e32 v1, v165, v1, vcc
	v_lshlrev_b32_e32 v1, 2, v1
	v_mov_b32_e32 v1, v0
	s_nop 1
	v_permlane32_swap_b32 v0, v1
	s_waitcnt lgkmcnt(0)
	v_add_f32_e32 v0, v0, v1
	v_fmamk_f32 v0, v0, 0x3c800000, v161
	v_cmp_gt_f32_e32 vcc, s61, v0
	v_mul_f32_e32 v1, 0x4b800000, v0
	s_nop 0
	v_cndmask_b32_e32 v0, v0, v1, vcc
	v_rsq_f32_e32 v0, v0
	s_nop 0
	v_mul_f32_e32 v1, 0x45800000, v0
	v_cndmask_b32_e32 v0, v0, v1, vcc
	v_mul_f32_e32 v0, s8, v0
	v_mul_f32_e32 v1, v36, v0
	s_and_b64 vcc, exec, s[6:7]
	s_waitcnt vmcnt(0)
	v_mul_f32_e32 v2, v4, v1
	v_mul_f32_e32 v1, v35, v0
	v_mul_f32_e32 v4, v5, v1
	v_mul_f32_e32 v1, v34, v0
	v_mul_f32_e32 v3, v6, v1
	v_mul_f32_e32 v1, v33, v0
	v_mul_f32_e32 v6, v7, v1
	v_mul_f32_e32 v1, v32, v0
	v_mul_f32_e32 v5, v18, v1
	v_mul_f32_e32 v1, v31, v0
	v_mul_f32_e32 v18, v19, v1
	v_mul_f32_e32 v1, v30, v0
	v_mul_f32_e32 v7, v20, v1
	v_mul_f32_e32 v1, v29, v0
	v_mul_f32_e32 v19, v21, v1
	global_load_dwordx4 v[20:23], v167, s[40:41] offset:144
	global_load_dwordx4 v[24:27], v167, s[40:41] offset:128
	v_mul_f32_e32 v1, v16, v0
	s_mov_b64 s[40:41], -1
	s_waitcnt vmcnt(0)
	v_mul_f32_e32 v16, v24, v1
	v_mul_f32_e32 v1, v17, v0
	v_mul_f32_e32 v17, v25, v1
	v_mul_f32_e32 v1, v14, v0
	v_mul_f32_e32 v14, v1, v26
	v_mul_f32_e32 v1, v15, v0
	v_mul_f32_e32 v15, v1, v27
	v_mul_f32_e32 v1, v12, v0
	v_mul_f32_e32 v12, v1, v20
	v_mul_f32_e32 v1, v13, v0
	v_mul_f32_e32 v13, v1, v21
	v_mul_f32_e32 v1, v10, v0
	v_mul_f32_e32 v10, v1, v22
	v_mov_b32_e32 v1, v140
	v_mul_f32_e32 v0, v11, v0
	v_cvt_f32_i32_e32 v1, v1
	v_mul_f32_e32 v11, v0, v23
	v_cvt_f32_u32_e32 v0, v28
	v_mul_f32_e32 v1, 0xbed49a78, v1
	v_exp_f32_e32 v1, v1
	s_nop 0
	v_mul_f32_e32 v1, 0.15915494, v1
	v_mul_f32_e32 v9, v1, v0
	v_rndne_f32_e32 v9, v9
	v_fma_f32 v1, v1, v0, -v9
	v_cos_f32_e32 v9, v1
	v_sin_f32_e32 v1, v1
	s_nop 0
	v_mul_f32_e32 v20, v16, v1
	v_fma_f32 v21, v2, v9, -v20
	v_mul_f32_e32 v20, v2, v1
	v_mov_b32_e32 v1, v141
	v_fmac_f32_e32 v20, v16, v9
	v_cvt_f32_i32_e32 v1, v1
	v_mul_f32_e32 v1, 0xbed49a78, v1
	v_exp_f32_e32 v1, v1
	s_nop 0
	v_mul_f32_e32 v1, 0.15915494, v1
	v_mul_f32_e32 v9, v1, v0
	v_rndne_f32_e32 v9, v9
	v_fma_f32 v1, v1, v0, -v9
	v_cos_f32_e32 v9, v1
	v_sin_f32_e32 v1, v1
	s_nop 0
	v_mul_f32_e32 v22, v17, v1
	v_fma_f32 v23, v4, v9, -v22
	v_mul_f32_e32 v22, v4, v1
	v_mov_b32_e32 v1, v143
	v_fmac_f32_e32 v22, v17, v9
	v_cvt_f32_i32_e32 v1, v1
	v_mul_f32_e32 v1, 0xbed49a78, v1
	v_exp_f32_e32 v1, v1
	s_nop 0
	v_mul_f32_e32 v1, 0.15915494, v1
	v_mul_f32_e32 v9, v1, v0
	v_rndne_f32_e32 v9, v9
	v_fma_f32 v1, v1, v0, -v9
	v_cos_f32_e32 v9, v1
	v_sin_f32_e32 v1, v1
	s_nop 0
	v_mul_f32_e32 v24, v14, v1
	v_fma_f32 v25, v3, v9, -v24
	v_mul_f32_e32 v24, v3, v1
	v_mov_b32_e32 v1, v145
	v_fmac_f32_e32 v24, v14, v9
	v_cvt_f32_i32_e32 v1, v1
	v_mul_f32_e32 v1, 0xbed49a78, v1
	v_exp_f32_e32 v1, v1
	s_nop 0
	v_mul_f32_e32 v1, 0.15915494, v1
	v_mul_f32_e32 v9, v1, v0
	v_rndne_f32_e32 v9, v9
	v_fma_f32 v1, v1, v0, -v9
	v_cos_f32_e32 v9, v1
	v_sin_f32_e32 v1, v1
	s_nop 0
	v_mul_f32_e32 v26, v15, v1
	v_fma_f32 v27, v6, v9, -v26
	v_mul_f32_e32 v26, v6, v1
	v_mov_b32_e32 v1, v147
	v_fmac_f32_e32 v26, v15, v9
	v_cvt_f32_i32_e32 v1, v1
	v_mul_f32_e32 v1, 0xbed49a78, v1
	v_exp_f32_e32 v1, v1
	s_nop 0
	v_mul_f32_e32 v1, 0.15915494, v1
	v_mul_f32_e32 v9, v1, v0
	v_rndne_f32_e32 v9, v9
	v_fma_f32 v1, v1, v0, -v9
	v_cos_f32_e32 v9, v1
	v_sin_f32_e32 v1, v1
	s_nop 0
	v_mul_f32_e32 v29, v12, v1
	v_fma_f32 v30, v5, v9, -v29
	v_mul_f32_e32 v29, v5, v1
	v_mov_b32_e32 v1, v153
	v_fmac_f32_e32 v29, v12, v9
	v_cvt_f32_i32_e32 v1, v1
	v_mul_f32_e32 v1, 0xbed49a78, v1
	v_exp_f32_e32 v1, v1
	s_nop 0
	v_mul_f32_e32 v1, 0.15915494, v1
	v_mul_f32_e32 v9, v1, v0
	v_rndne_f32_e32 v9, v9
	v_fma_f32 v1, v1, v0, -v9
	v_cos_f32_e32 v9, v1
	v_sin_f32_e32 v1, v1
	s_nop 0
	v_mul_f32_e32 v31, v13, v1
	v_fma_f32 v32, v18, v9, -v31
	v_mul_f32_e32 v31, v18, v1
	v_mov_b32_e32 v1, v155
	v_fmac_f32_e32 v31, v13, v9
	v_cvt_f32_i32_e32 v1, v1
	v_mul_f32_e32 v1, 0xbed49a78, v1
	v_exp_f32_e32 v1, v1
	s_nop 0
	v_mul_f32_e32 v1, 0.15915494, v1
	v_mul_f32_e32 v9, v1, v0
	v_rndne_f32_e32 v9, v9
	v_fma_f32 v1, v1, v0, -v9
	v_cos_f32_e32 v9, v1
	v_sin_f32_e32 v1, v1
	s_nop 0
	v_mul_f32_e32 v33, v10, v1
	v_fma_f32 v34, v7, v9, -v33
	v_mul_f32_e32 v33, v7, v1
	v_mov_b32_e32 v1, v157
	v_fmac_f32_e32 v33, v10, v9
	v_cvt_f32_i32_e32 v1, v1
	v_mul_f32_e32 v1, 0xbed49a78, v1
	v_exp_f32_e32 v1, v1
	s_nop 0
	v_mul_f32_e32 v1, 0.15915494, v1
	v_mul_f32_e32 v9, v1, v0
	v_rndne_f32_e32 v9, v9
	v_fma_f32 v0, v1, v0, -v9
	v_cos_f32_e32 v1, v0
	v_sin_f32_e32 v0, v0
	s_nop 0
	v_mul_f32_e32 v9, v11, v0
	v_mul_f32_e32 v35, v19, v0
	v_fma_f32 v36, v19, v1, -v9
	v_fmac_f32_e32 v35, v11, v1
	v_lshlrev_b32_e32 v0, 1, v140
	s_cbranch_vccnz .LBB0_423
	s_and_b64 s[6:7], s[10:11], exec
	s_cselect_b32 s8, s77, s76
	s_cselect_b32 s27, s74, s75
	s_lshl_b32 s6, s52, 1
	s_or_b32 s6, s6, s97
	s_ashr_i32 s7, s6, 31
	s_lshl_b64 s[6:7], s[6:7], 18
	s_add_u32 s6, s27, s6
	s_addc_u32 s7, s8, s7
	v_lshlrev_b32_e32 v136, 7, v28
	v_lshl_add_u64 v[38:39], s[6:7], 0, v[136:137]
	v_mov_b32_e32 v1, v137
	v_lshl_add_u64 v[42:43], v[38:39], 0, v[0:1]
	v_cvt_pk_bf16_f32 v38, v21, v23
	v_cvt_pk_bf16_f32 v39, v25, v27
	v_cvt_pk_bf16_f32 v40, v30, v32
	v_cvt_pk_bf16_f32 v41, v34, v36
	s_mov_b64 s[40:41], 0
	global_store_dwordx4 v[42:43], v[38:41], off
	s_nop 1
	v_cvt_pk_bf16_f32 v38, v20, v22
	v_cvt_pk_bf16_f32 v39, v24, v26
	v_cvt_pk_bf16_f32 v40, v29, v31
	v_cvt_pk_bf16_f32 v41, v33, v35
	global_store_dwordx4 v[42:43], v[38:41], off offset:64
